# early2 + tail priority 2 + faster wake + folded m0 s_nops in load segments
# speedup vs baseline: 1.0122x; 1.0041x over previous
; #define PG8_STAGE(bufoff, gbase, voff) do { _Pragma("unroll") for (int _i = 0; _i < 2; ++_i) \
;         __builtin_amdgcn_global_load_lds((const unsigned*)((const char*)(gbase) + (voff)[_i]), (PG8_LAS unsigned*)(lds + (bufoff) + ldsw + _i * 8192), 16, 0, 0); } while (0)
; #define PG8_LDA(dst, b, h) do { _Pragma("unroll") for (int m = 0; m < 4; ++m) _Pragma("unroll") for (int k = 0; k < 2; ++k) dst[m][k] = *(const PG8_LAS bf16x8*)(lds + PG8_SA(b, h) + aoff + m * 2048 + k * 1024); } while (0)
; #define PG8_LDB(dst, b, h) do { _Pragma("unroll") for (int n = 0; n < 2; ++n) _Pragma("unroll") for (int k = 0; k < 2; ++k) dst[n][k] = *(const PG8_LAS bf16x8*)(lds + PG8_SB(b, h) + boff + n * 2048 + k * 1024); } while (0)
; #define PG8_MMA(ai, bj, At, Bt) do { __builtin_amdgcn_s_setprio(1); _Pragma("unroll") for (int m = 0; m < 4; ++m) _Pragma("unroll") for (int n = 0; n < 2; ++n) _Pragma("unroll") for (int k = 0; k < 2; ++k) \
;         acc[ai][bj][m][n] = __builtin_amdgcn_mfma_f32_16x16x32_bf16(Bt[n][k], At[m][k], acc[ai][bj][m][n], 0, 0, 0); __builtin_amdgcn_s_setprio(0); } while (0)
; #define PG8_WAIT_V(n) asm volatile("s_waitcnt vmcnt(" #n ")" ::: "memory")
; #define PG8_WAIT_L(n) asm volatile("s_waitcnt lgkmcnt(" #n ")" ::: "memory")
; #define PG8_BAR __builtin_amdgcn_s_barrier()
; #define PG8_SCHED __builtin_amdgcn_sched_barrier(0)
; template <class Epi, class Sched, bool ALIGN_EPI = false, bool SP2 = false>
; __device__ __forceinline__ void gemm_phase(PG8_LAS unsigned char* lds, const Gemm g, const Sched& S, const Epi& E) {
;     ...
;         for (int t = 0; t < nt; t += 2) {
;             const bool last = (t == nt - 2);
;             const char* a1 = cA + (size_t)(t + 1) * kstep;
;             const char* a2 = last ? nA : cA + (size_t)(t + 2) * kstep; const char* b2 = last ? nB : cB + (size_t)(t + 2) * kstep;
;             const char* a3 = a2 + kstep; const char* b3 = b2 + kstep;
;             if constexpr (SP2) {
;             PG8_LDB(B0, 0, 0); PG8_LDB(B1, 0, 1); PG8_SCHED; PG8_LDA(At, 0, 0); PG8_STAGE(PG8_SA(1, 1), a1 + hstep, voffA);
;             PG8_WAIT_V(8); PG8_WAIT_L(0); PG8_BAR; PG8_MMA(0, 0, At, B0); PG8_MMA(0, 1, At, B1); PG8_BAR; PG8_SCHED;
;             PG8_LDA(At, 0, 1); PG8_STAGE(PG8_SB(0, 0), b2, voffB); PG8_STAGE(PG8_SB(0, 1), b2 + hstep, voffB); PG8_STAGE(PG8_SA(0, 0), a2, voffA);
.LBB0_200:
	ds_read_b128 v[148:151], v164
	ds_read_b128 v[152:155], v164 offset:1024
	ds_read_b128 v[156:159], v164 offset:2048
	ds_read_b128 v[168:171], v164 offset:3072
	ds_read_b128 v[172:175], v165
	ds_read_b128 v[176:179], v165 offset:1024
	ds_read_b128 v[180:183], v165 offset:2048
	ds_read_b128 v[184:187], v165 offset:3072
	s_add_u32 s52, s70, 0xfff80080
	s_addc_u32 s53, s71, -1
	s_cmp_eq_u32 s93, 28
	s_cselect_b32 s75, s39, s53
	s_cselect_b32 s74, s69, s52
	s_cselect_b32 s73, s35, s92
	s_cselect_b32 s72, s90, s91
	v_lshl_add_u64 v[220:221], s[70:71], 0, v[138:139]
	s_add_i32 m0, s33, 0xc000
	ds_read_b128 v[188:191], v166
	ds_read_b128 v[192:195], v166 offset:1024
	ds_read_b128 v[196:199], v166 offset:2048
	ds_read_b128 v[200:203], v166 offset:3072
	ds_read_b128 v[204:207], v166 offset:4096
	ds_read_b128 v[208:211], v166 offset:5120
	ds_read_b128 v[212:215], v166 offset:6144
	ds_read_b128 v[216:219], v166 offset:7168
	global_load_lds_dwordx4 v[220:221], off
	s_add_i32 m0, s33, 0xe000
	v_lshl_add_u64 v[220:221], s[70:71], 0, v[140:141]
	global_load_lds_dwordx4 v[220:221], off
	s_waitcnt vmcnt(8)
	s_waitcnt lgkmcnt(0)
	s_setprio 1
	s_barrier
	v_mfma_f32_16x16x32_bf16 v[124:127], v[148:151], v[188:191], v[124:127]
	v_mfma_f32_16x16x32_bf16 v[120:123], v[156:159], v[188:191], v[120:123]
	v_mfma_f32_16x16x32_bf16 v[116:119], v[148:151], v[196:199], v[116:119]
	v_mfma_f32_16x16x32_bf16 v[108:111], v[156:159], v[196:199], v[108:111]
	v_mfma_f32_16x16x32_bf16 v[100:103], v[148:151], v[204:207], v[100:103]
	v_mfma_f32_16x16x32_bf16 v[92:95], v[156:159], v[204:207], v[92:95]
	v_mfma_f32_16x16x32_bf16 v[84:87], v[148:151], v[212:215], v[84:87]
	v_mfma_f32_16x16x32_bf16 v[76:79], v[156:159], v[212:215], v[76:79]
	v_mfma_f32_16x16x32_bf16 v[124:127], v[152:155], v[192:195], v[124:127]
	v_mfma_f32_16x16x32_bf16 v[120:123], v[168:171], v[192:195], v[120:123]
	v_mfma_f32_16x16x32_bf16 v[116:119], v[152:155], v[200:203], v[116:119]
	v_mfma_f32_16x16x32_bf16 v[108:111], v[168:171], v[200:203], v[108:111]
	v_mfma_f32_16x16x32_bf16 v[100:103], v[152:155], v[208:211], v[100:103]
	v_mfma_f32_16x16x32_bf16 v[92:95], v[168:171], v[208:211], v[92:95]
	v_mfma_f32_16x16x32_bf16 v[84:87], v[152:155], v[216:219], v[84:87]
	v_mfma_f32_16x16x32_bf16 v[76:79], v[168:171], v[216:219], v[76:79]
	s_setprio 0
	s_setprio 1
	v_mfma_f32_16x16x32_bf16 v[112:115], v[172:175], v[188:191], v[112:115]
	v_mfma_f32_16x16x32_bf16 v[104:107], v[180:183], v[188:191], v[104:107]
	v_mfma_f32_16x16x32_bf16 v[96:99], v[172:175], v[196:199], v[96:99]
	v_mfma_f32_16x16x32_bf16 v[88:91], v[180:183], v[196:199], v[88:91]
	v_mfma_f32_16x16x32_bf16 v[80:83], v[172:175], v[204:207], v[80:83]
	v_mfma_f32_16x16x32_bf16 v[72:75], v[180:183], v[204:207], v[72:75]
	v_mfma_f32_16x16x32_bf16 v[68:71], v[172:175], v[212:215], v[68:71]
	v_mfma_f32_16x16x32_bf16 v[64:67], v[180:183], v[212:215], v[64:67]
	v_mfma_f32_16x16x32_bf16 v[112:115], v[176:179], v[192:195], v[112:115]
	v_mfma_f32_16x16x32_bf16 v[104:107], v[184:187], v[192:195], v[104:107]
	v_mfma_f32_16x16x32_bf16 v[96:99], v[176:179], v[200:203], v[96:99]
	v_mfma_f32_16x16x32_bf16 v[88:91], v[184:187], v[200:203], v[88:91]
	v_mfma_f32_16x16x32_bf16 v[80:83], v[176:179], v[208:211], v[80:83]
	v_mfma_f32_16x16x32_bf16 v[72:75], v[184:187], v[208:211], v[72:75]
	s_setprio 2
	s_barrier
	v_mfma_f32_16x16x32_bf16 v[68:71], v[176:179], v[216:219], v[68:71]
	v_mfma_f32_16x16x32_bf16 v[64:67], v[184:187], v[216:219], v[64:67]
	s_setprio 0
	s_add_i32 s52, s84, s3
	v_lshl_add_u64 v[220:221], s[72:73], 0, v[132:133]
	s_mov_b32 m0, s52
	ds_read_b128 v[188:191], v166 offset:16384
	ds_read_b128 v[192:195], v166 offset:17408
	ds_read_b128 v[196:199], v166 offset:18432
	ds_read_b128 v[200:203], v166 offset:19456
	ds_read_b128 v[204:207], v166 offset:20480
	ds_read_b128 v[208:211], v166 offset:21504
	ds_read_b128 v[212:215], v166 offset:22528
	ds_read_b128 v[216:219], v166 offset:23552
	global_load_lds_dwordx4 v[220:221], off
	s_add_i32 m0, s52, 0x2000
	s_add_u32 s96, s72, 0x80000
	v_lshl_add_u64 v[222:223], s[72:73], 0, v[128:129]
	s_addc_u32 s97, s73, 0
	s_add_i32 s52, s85, s3
	global_load_lds_dwordx4 v[222:223], off
	v_lshl_add_u64 v[224:225], s[96:97], 0, v[132:133]
	s_mov_b32 m0, s52
	v_lshl_add_u64 v[226:227], s[74:75], 0, v[130:131]
	global_load_lds_dwordx4 v[224:225], off
	s_add_i32 m0, s52, 0x2000
	v_lshl_add_u64 v[224:225], s[96:97], 0, v[128:129]
	global_load_lds_dwordx4 v[224:225], off
	s_mov_b32 m0, s33
	v_lshl_add_u64 v[224:225], s[74:75], 0, v[134:135]
	global_load_lds_dwordx4 v[224:225], off
	s_mov_b32 m0, s76
	s_nop 0
	global_load_lds_dwordx4 v[226:227], off
	s_waitcnt vmcnt(8)
	s_waitcnt lgkmcnt(0)
	s_setprio 1
	s_barrier
; #define PG8_STAGE(bufoff, gbase, voff) do { _Pragma("unroll") for (int _i = 0; _i < 2; ++_i) \
;         __builtin_amdgcn_global_load_lds((const unsigned*)((const char*)(gbase) + (voff)[_i]), (PG8_LAS unsigned*)(lds + (bufoff) + ldsw + _i * 8192), 16, 0, 0); } while (0)
; #define PG8_LDA(dst, b, h) do { _Pragma("unroll") for (int m = 0; m < 4; ++m) _Pragma("unroll") for (int k = 0; k < 2; ++k) dst[m][k] = *(const PG8_LAS bf16x8*)(lds + PG8_SA(b, h) + aoff + m * 2048 + k * 1024); } while (0)
; #define PG8_LDB(dst, b, h) do { _Pragma("unroll") for (int n = 0; n < 2; ++n) _Pragma("unroll") for (int k = 0; k < 2; ++k) dst[n][k] = *(const PG8_LAS bf16x8*)(lds + PG8_SB(b, h) + boff + n * 2048 + k * 1024); } while (0)
; #define PG8_MMA(ai, bj, At, Bt) do { __builtin_amdgcn_s_setprio(1); _Pragma("unroll") for (int m = 0; m < 4; ++m) _Pragma("unroll") for (int n = 0; n < 2; ++n) _Pragma("unroll") for (int k = 0; k < 2; ++k) \
;         acc[ai][bj][m][n] = __builtin_amdgcn_mfma_f32_16x16x32_bf16(Bt[n][k], At[m][k], acc[ai][bj][m][n], 0, 0, 0); __builtin_amdgcn_s_setprio(0); } while (0)
; #define PG8_WAIT_V(n) asm volatile("s_waitcnt vmcnt(" #n ")" ::: "memory")
; #define PG8_WAIT_L(n) asm volatile("s_waitcnt lgkmcnt(" #n ")" ::: "memory")
; #define PG8_BAR __builtin_amdgcn_s_barrier()
; #define PG8_SCHED __builtin_amdgcn_sched_barrier(0)
; template <class Epi, class Sched, bool ALIGN_EPI = false, bool SP2 = false>
; __device__ __forceinline__ void gemm_phase(PG8_LAS unsigned char* lds, const Gemm g, const Sched& S, const Epi& E) {
;     ...
;             PG8_WAIT_V(8); PG8_WAIT_L(0); PG8_BAR; PG8_MMA(1, 0, At, B0); PG8_MMA(1, 1, At, B1); PG8_BAR; PG8_SCHED;
;             PG8_LDB(B0, 1, 0); PG8_LDB(B1, 1, 1); PG8_SCHED; PG8_LDA(At, 1, 0); PG8_STAGE(PG8_SA(0, 1), a2 + hstep, voffA);
;             PG8_WAIT_V(8); PG8_WAIT_L(0); PG8_BAR; PG8_MMA(0, 0, At, B0); PG8_MMA(0, 1, At, B1); PG8_BAR; PG8_SCHED;
	v_mfma_f32_16x16x32_bf16 v[60:63], v[148:151], v[188:191], v[60:63]
	v_mfma_f32_16x16x32_bf16 v[56:59], v[156:159], v[188:191], v[56:59]
	v_mfma_f32_16x16x32_bf16 v[52:55], v[148:151], v[196:199], v[52:55]
	v_mfma_f32_16x16x32_bf16 v[44:47], v[156:159], v[196:199], v[44:47]
	v_mfma_f32_16x16x32_bf16 v[36:39], v[148:151], v[204:207], v[36:39]
	v_mfma_f32_16x16x32_bf16 v[28:31], v[156:159], v[204:207], v[28:31]
	v_mfma_f32_16x16x32_bf16 v[20:23], v[148:151], v[212:215], v[20:23]
	v_mfma_f32_16x16x32_bf16 v[12:15], v[156:159], v[212:215], v[12:15]
	v_mfma_f32_16x16x32_bf16 v[60:63], v[152:155], v[192:195], v[60:63]
	v_mfma_f32_16x16x32_bf16 v[56:59], v[168:171], v[192:195], v[56:59]
	v_mfma_f32_16x16x32_bf16 v[52:55], v[152:155], v[200:203], v[52:55]
	v_mfma_f32_16x16x32_bf16 v[44:47], v[168:171], v[200:203], v[44:47]
	v_mfma_f32_16x16x32_bf16 v[36:39], v[152:155], v[208:211], v[36:39]
	v_mfma_f32_16x16x32_bf16 v[28:31], v[168:171], v[208:211], v[28:31]
	v_mfma_f32_16x16x32_bf16 v[20:23], v[152:155], v[216:219], v[20:23]
	v_mfma_f32_16x16x32_bf16 v[12:15], v[168:171], v[216:219], v[12:15]
	s_setprio 0
	s_setprio 1
	v_mfma_f32_16x16x32_bf16 v[48:51], v[172:175], v[188:191], v[48:51]
	v_mfma_f32_16x16x32_bf16 v[40:43], v[180:183], v[188:191], v[40:43]
	v_mfma_f32_16x16x32_bf16 v[32:35], v[172:175], v[196:199], v[32:35]
	v_mfma_f32_16x16x32_bf16 v[24:27], v[180:183], v[196:199], v[24:27]
	v_mfma_f32_16x16x32_bf16 v[16:19], v[172:175], v[204:207], v[16:19]
	v_mfma_f32_16x16x32_bf16 v[8:11], v[180:183], v[204:207], v[8:11]
	v_mfma_f32_16x16x32_bf16 v[4:7], v[172:175], v[212:215], v[4:7]
	v_mfma_f32_16x16x32_bf16 v[0:3], v[180:183], v[212:215], v[0:3]
	v_mfma_f32_16x16x32_bf16 v[48:51], v[176:179], v[192:195], v[48:51]
	v_mfma_f32_16x16x32_bf16 v[40:43], v[184:187], v[192:195], v[40:43]
	v_mfma_f32_16x16x32_bf16 v[32:35], v[176:179], v[200:203], v[32:35]
	v_mfma_f32_16x16x32_bf16 v[24:27], v[184:187], v[200:203], v[24:27]
	v_mfma_f32_16x16x32_bf16 v[16:19], v[176:179], v[208:211], v[16:19]
	v_mfma_f32_16x16x32_bf16 v[8:11], v[184:187], v[208:211], v[8:11]
	s_setprio 2
	s_barrier
	v_mfma_f32_16x16x32_bf16 v[4:7], v[176:179], v[216:219], v[4:7]
	v_mfma_f32_16x16x32_bf16 v[0:3], v[184:187], v[216:219], v[0:3]
	s_setprio 0
	s_add_i32 s52, 0, 0x18000
	v_add_u32_e32 v136, s52, v161
	s_add_i32 s53, 0, 0x1c000
	ds_read_b128 v[148:151], v136
	ds_read_b128 v[152:155], v136 offset:1024
	ds_read_b128 v[156:159], v136 offset:2048
	ds_read_b128 v[168:171], v136 offset:3072
	v_add_u32_e32 v136, s53, v161
	ds_read_b128 v[172:175], v136
	ds_read_b128 v[176:179], v136 offset:1024
	ds_read_b128 v[180:183], v136 offset:2048
	ds_read_b128 v[184:187], v136 offset:3072
	s_add_u32 s74, s74, 0x80000
	s_addc_u32 s75, s75, 0
	s_mov_b32 m0, s77
	v_lshl_add_u64 v[228:229], s[74:75], 0, v[134:135]
	ds_read_b128 v[188:191], v166 offset:32768
	ds_read_b128 v[192:195], v166 offset:33792
	ds_read_b128 v[196:199], v166 offset:34816
	ds_read_b128 v[200:203], v166 offset:35840
	ds_read_b128 v[204:207], v166 offset:36864
	ds_read_b128 v[208:211], v166 offset:37888
	ds_read_b128 v[212:215], v166 offset:38912
	ds_read_b128 v[216:219], v166 offset:39936
	global_load_lds_dwordx4 v[228:229], off
	s_mov_b32 m0, s78
	v_lshl_add_u64 v[228:229], s[74:75], 0, v[130:131]
	global_load_lds_dwordx4 v[228:229], off
	s_waitcnt vmcnt(8)
	s_waitcnt lgkmcnt(0)
	s_setprio 1
	s_barrier
	v_mfma_f32_16x16x32_bf16 v[124:127], v[148:151], v[188:191], v[124:127]
	v_mfma_f32_16x16x32_bf16 v[120:123], v[156:159], v[188:191], v[120:123]
	v_mfma_f32_16x16x32_bf16 v[116:119], v[148:151], v[196:199], v[116:119]
	v_mfma_f32_16x16x32_bf16 v[108:111], v[156:159], v[196:199], v[108:111]
	v_mfma_f32_16x16x32_bf16 v[100:103], v[148:151], v[204:207], v[100:103]
	v_mfma_f32_16x16x32_bf16 v[92:95], v[156:159], v[204:207], v[92:95]
	v_mfma_f32_16x16x32_bf16 v[84:87], v[148:151], v[212:215], v[84:87]
	v_mfma_f32_16x16x32_bf16 v[76:79], v[156:159], v[212:215], v[76:79]
	v_mfma_f32_16x16x32_bf16 v[124:127], v[152:155], v[192:195], v[124:127]
	v_mfma_f32_16x16x32_bf16 v[120:123], v[168:171], v[192:195], v[120:123]
	v_mfma_f32_16x16x32_bf16 v[116:119], v[152:155], v[200:203], v[116:119]
	v_mfma_f32_16x16x32_bf16 v[108:111], v[168:171], v[200:203], v[108:111]
	v_mfma_f32_16x16x32_bf16 v[100:103], v[152:155], v[208:211], v[100:103]
	v_mfma_f32_16x16x32_bf16 v[92:95], v[168:171], v[208:211], v[92:95]
	v_mfma_f32_16x16x32_bf16 v[84:87], v[152:155], v[216:219], v[84:87]
	v_mfma_f32_16x16x32_bf16 v[76:79], v[168:171], v[216:219], v[76:79]
	s_setprio 0
	s_setprio 1
	v_mfma_f32_16x16x32_bf16 v[112:115], v[172:175], v[188:191], v[112:115]
	v_mfma_f32_16x16x32_bf16 v[104:107], v[180:183], v[188:191], v[104:107]
	v_mfma_f32_16x16x32_bf16 v[96:99], v[172:175], v[196:199], v[96:99]
	v_mfma_f32_16x16x32_bf16 v[88:91], v[180:183], v[196:199], v[88:91]
	v_mfma_f32_16x16x32_bf16 v[80:83], v[172:175], v[204:207], v[80:83]
	v_mfma_f32_16x16x32_bf16 v[72:75], v[180:183], v[204:207], v[72:75]
	v_mfma_f32_16x16x32_bf16 v[68:71], v[172:175], v[212:215], v[68:71]
	v_mfma_f32_16x16x32_bf16 v[64:67], v[180:183], v[212:215], v[64:67]
	v_mfma_f32_16x16x32_bf16 v[112:115], v[176:179], v[192:195], v[112:115]
	v_mfma_f32_16x16x32_bf16 v[104:107], v[184:187], v[192:195], v[104:107]
	v_mfma_f32_16x16x32_bf16 v[96:99], v[176:179], v[200:203], v[96:99]
	v_mfma_f32_16x16x32_bf16 v[88:91], v[184:187], v[200:203], v[88:91]
	v_mfma_f32_16x16x32_bf16 v[80:83], v[176:179], v[208:211], v[80:83]
	v_mfma_f32_16x16x32_bf16 v[72:75], v[184:187], v[208:211], v[72:75]
	s_setprio 2
	s_barrier
; #define PG8_STAGE(bufoff, gbase, voff) do { _Pragma("unroll") for (int _i = 0; _i < 2; ++_i) \
;         __builtin_amdgcn_global_load_lds((const unsigned*)((const char*)(gbase) + (voff)[_i]), (PG8_LAS unsigned*)(lds + (bufoff) + ldsw + _i * 8192), 16, 0, 0); } while (0)
; #define PG8_LDA(dst, b, h) do { _Pragma("unroll") for (int m = 0; m < 4; ++m) _Pragma("unroll") for (int k = 0; k < 2; ++k) dst[m][k] = *(const PG8_LAS bf16x8*)(lds + PG8_SA(b, h) + aoff + m * 2048 + k * 1024); } while (0)
; #define PG8_MMA(ai, bj, At, Bt) do { __builtin_amdgcn_s_setprio(1); _Pragma("unroll") for (int m = 0; m < 4; ++m) _Pragma("unroll") for (int n = 0; n < 2; ++n) _Pragma("unroll") for (int k = 0; k < 2; ++k) \
;         acc[ai][bj][m][n] = __builtin_amdgcn_mfma_f32_16x16x32_bf16(Bt[n][k], At[m][k], acc[ai][bj][m][n], 0, 0, 0); __builtin_amdgcn_s_setprio(0); } while (0)
; #define PG8_WAIT_V(n) asm volatile("s_waitcnt vmcnt(" #n ")" ::: "memory")
; #define PG8_WAIT_L(n) asm volatile("s_waitcnt lgkmcnt(" #n ")" ::: "memory")
; #define PG8_BAR __builtin_amdgcn_s_barrier()
; #define PG8_SCHED __builtin_amdgcn_sched_barrier(0)
; template <class Epi, class Sched, bool ALIGN_EPI = false, bool SP2 = false>
; __device__ __forceinline__ void gemm_phase(PG8_LAS unsigned char* lds, const Gemm g, const Sched& S, const Epi& E) {
;     ...
;         for (int t = 0; t < nt; t += 2) {
;             const bool last = (t == nt - 2);
;     ...
;             PG8_WAIT_V(8); PG8_WAIT_L(0); PG8_BAR; PG8_MMA(0, 0, At, B0); PG8_MMA(0, 1, At, B1); PG8_BAR; PG8_SCHED;
;             PG8_LDA(At, 1, 1); PG8_STAGE(PG8_SB(1, 0), b3, voffB); PG8_STAGE(PG8_SB(1, 1), b3 + hstep, voffB); PG8_STAGE(PG8_SA(1, 0), a3, voffA);
;             PG8_WAIT_V(8); PG8_WAIT_L(0); PG8_BAR; PG8_MMA(1, 0, At, B0); PG8_MMA(1, 1, At, B1); PG8_BAR; PG8_SCHED;
	v_mfma_f32_16x16x32_bf16 v[68:71], v[176:179], v[216:219], v[68:71]
	v_mfma_f32_16x16x32_bf16 v[64:67], v[184:187], v[216:219], v[64:67]
	s_setprio 0
	s_add_i32 s52, s52, s3
	v_lshl_add_u64 v[220:221], v[220:221], 0, s[12:13]
	s_mov_b32 m0, s52
	ds_read_b128 v[188:191], v166 offset:49152
	ds_read_b128 v[192:195], v166 offset:50176
	ds_read_b128 v[196:199], v166 offset:51200
	ds_read_b128 v[200:203], v166 offset:52224
	ds_read_b128 v[204:207], v166 offset:53248
	ds_read_b128 v[208:211], v166 offset:54272
	ds_read_b128 v[212:215], v166 offset:55296
	ds_read_b128 v[216:219], v166 offset:56320
	global_load_lds_dwordx4 v[220:221], off
	s_add_i32 m0, s52, 0x2000
	s_add_u32 s72, s72, 0x80080
	v_lshl_add_u64 v[220:221], v[222:223], 0, s[12:13]
	s_addc_u32 s73, s73, 0
	s_add_i32 s52, s53, s3
	global_load_lds_dwordx4 v[220:221], off
	s_mov_b32 m0, s52
	v_lshl_add_u64 v[220:221], s[72:73], 0, v[132:133]
	global_load_lds_dwordx4 v[220:221], off
	s_add_i32 m0, s52, 0x2000
	v_lshl_add_u64 v[220:221], s[72:73], 0, v[128:129]
	global_load_lds_dwordx4 v[220:221], off
	s_mov_b32 m0, s80
	v_lshl_add_u64 v[220:221], v[224:225], 0, s[12:13]
	global_load_lds_dwordx4 v[220:221], off
	s_mov_b32 m0, s81
	v_lshl_add_u64 v[220:221], v[226:227], 0, s[12:13]
	global_load_lds_dwordx4 v[220:221], off
	s_waitcnt vmcnt(8)
	s_waitcnt lgkmcnt(0)
	s_setprio 1
	s_barrier
	v_mfma_f32_16x16x32_bf16 v[60:63], v[148:151], v[188:191], v[60:63]
	v_mfma_f32_16x16x32_bf16 v[56:59], v[156:159], v[188:191], v[56:59]
	v_mfma_f32_16x16x32_bf16 v[52:55], v[148:151], v[196:199], v[52:55]
	v_mfma_f32_16x16x32_bf16 v[44:47], v[156:159], v[196:199], v[44:47]
	v_mfma_f32_16x16x32_bf16 v[36:39], v[148:151], v[204:207], v[36:39]
	v_mfma_f32_16x16x32_bf16 v[28:31], v[156:159], v[204:207], v[28:31]
	v_mfma_f32_16x16x32_bf16 v[20:23], v[148:151], v[212:215], v[20:23]
	v_mfma_f32_16x16x32_bf16 v[12:15], v[156:159], v[212:215], v[12:15]
	v_mfma_f32_16x16x32_bf16 v[60:63], v[152:155], v[192:195], v[60:63]
	v_mfma_f32_16x16x32_bf16 v[56:59], v[168:171], v[192:195], v[56:59]
	v_mfma_f32_16x16x32_bf16 v[52:55], v[152:155], v[200:203], v[52:55]
	v_mfma_f32_16x16x32_bf16 v[44:47], v[168:171], v[200:203], v[44:47]
	v_mfma_f32_16x16x32_bf16 v[36:39], v[152:155], v[208:211], v[36:39]
	v_mfma_f32_16x16x32_bf16 v[28:31], v[168:171], v[208:211], v[28:31]
	v_mfma_f32_16x16x32_bf16 v[20:23], v[152:155], v[216:219], v[20:23]
	v_mfma_f32_16x16x32_bf16 v[12:15], v[168:171], v[216:219], v[12:15]
	s_setprio 0
	s_setprio 1
	v_mfma_f32_16x16x32_bf16 v[48:51], v[172:175], v[188:191], v[48:51]
	v_mfma_f32_16x16x32_bf16 v[40:43], v[180:183], v[188:191], v[40:43]
	v_mfma_f32_16x16x32_bf16 v[32:35], v[172:175], v[196:199], v[32:35]
	v_mfma_f32_16x16x32_bf16 v[24:27], v[180:183], v[196:199], v[24:27]
	v_mfma_f32_16x16x32_bf16 v[16:19], v[172:175], v[204:207], v[16:19]
	v_mfma_f32_16x16x32_bf16 v[8:11], v[180:183], v[204:207], v[8:11]
	v_mfma_f32_16x16x32_bf16 v[4:7], v[172:175], v[212:215], v[4:7]
	v_mfma_f32_16x16x32_bf16 v[0:3], v[180:183], v[212:215], v[0:3]
	v_mfma_f32_16x16x32_bf16 v[48:51], v[176:179], v[192:195], v[48:51]
	v_mfma_f32_16x16x32_bf16 v[40:43], v[184:187], v[192:195], v[40:43]
	v_mfma_f32_16x16x32_bf16 v[32:35], v[176:179], v[200:203], v[32:35]
	v_mfma_f32_16x16x32_bf16 v[24:27], v[184:187], v[200:203], v[24:27]
	v_mfma_f32_16x16x32_bf16 v[16:19], v[176:179], v[208:211], v[16:19]
	v_mfma_f32_16x16x32_bf16 v[8:11], v[184:187], v[208:211], v[8:11]
	s_setprio 2
	s_barrier
	v_mfma_f32_16x16x32_bf16 v[4:7], v[176:179], v[216:219], v[4:7]
	v_mfma_f32_16x16x32_bf16 v[0:3], v[184:187], v[216:219], v[0:3]
	s_setprio 0
	s_add_i32 s93, s93, 2
	s_add_u32 s70, s70, 0x100
	s_addc_u32 s71, s71, 0
	s_add_u32 s91, s91, 0x100
	s_addc_u32 s92, s92, 0
	s_cmp_gt_u32 s93, 29
	s_cbranch_scc0 .LBB0_200
	s_and_b64 vcc, exec, s[14:15]
	s_cbranch_vccz .LBB0_203
	s_barrier

; #define PG8_STAGE(bufoff, gbase, voff) do { _Pragma("unroll") for (int _i = 0; _i < 2; ++_i) \
;         __builtin_amdgcn_global_load_lds((const unsigned*)((const char*)(gbase) + (voff)[_i]), (PG8_LAS unsigned*)(lds + (bufoff) + ldsw + _i * 8192), 16, 0, 0); } while (0)
; #define PG8_LDA(dst, b, h) do { _Pragma("unroll") for (int m = 0; m < 4; ++m) _Pragma("unroll") for (int k = 0; k < 2; ++k) dst[m][k] = *(const PG8_LAS bf16x8*)(lds + PG8_SA(b, h) + aoff + m * 2048 + k * 1024); } while (0)
; #define PG8_LDB(dst, b, h) do { _Pragma("unroll") for (int n = 0; n < 2; ++n) _Pragma("unroll") for (int k = 0; k < 2; ++k) dst[n][k] = *(const PG8_LAS bf16x8*)(lds + PG8_SB(b, h) + boff + n * 2048 + k * 1024); } while (0)
; #define PG8_MMA(ai, bj, At, Bt) do { __builtin_amdgcn_s_setprio(1); _Pragma("unroll") for (int m = 0; m < 4; ++m) _Pragma("unroll") for (int n = 0; n < 2; ++n) _Pragma("unroll") for (int k = 0; k < 2; ++k) \
;         acc[ai][bj][m][n] = __builtin_amdgcn_mfma_f32_16x16x32_bf16(Bt[n][k], At[m][k], acc[ai][bj][m][n], 0, 0, 0); __builtin_amdgcn_s_setprio(0); } while (0)
; #define PG8_WAIT_V(n) asm volatile("s_waitcnt vmcnt(" #n ")" ::: "memory")
; #define PG8_WAIT_L(n) asm volatile("s_waitcnt lgkmcnt(" #n ")" ::: "memory")
; #define PG8_BAR __builtin_amdgcn_s_barrier()
; #define PG8_SCHED __builtin_amdgcn_sched_barrier(0)
; template <class Epi, class Sched, bool ALIGN_EPI = false, bool SP2 = false>
; __device__ __forceinline__ void gemm_phase(PG8_LAS unsigned char* lds, const Gemm g, const Sched& S, const Epi& E) {
;     ...
;         for (int t = 0; t < nt; t += 2) {
;             const bool last = (t == nt - 2);
;             const char* a1 = cA + (size_t)(t + 1) * kstep;
;             const char* a2 = last ? nA : cA + (size_t)(t + 2) * kstep; const char* b2 = last ? nB : cB + (size_t)(t + 2) * kstep;
;             const char* a3 = a2 + kstep; const char* b3 = b2 + kstep;
;             if constexpr (SP2) {
;             PG8_LDB(B0, 0, 0); PG8_LDB(B1, 0, 1); PG8_SCHED; PG8_LDA(At, 0, 0); PG8_STAGE(PG8_SA(1, 1), a1 + hstep, voffA);
;             PG8_WAIT_V(8); PG8_WAIT_L(0); PG8_BAR; PG8_MMA(0, 0, At, B0); PG8_MMA(0, 1, At, B1); PG8_BAR; PG8_SCHED;
;             PG8_LDA(At, 0, 1); PG8_STAGE(PG8_SB(0, 0), b2, voffB); PG8_STAGE(PG8_SB(0, 1), b2 + hstep, voffB); PG8_STAGE(PG8_SA(0, 0), a2, voffA);
.LBB0_374:
	ds_read_b128 v[128:131], v230
	ds_read_b128 v[132:135], v230 offset:1024
	ds_read_b128 v[158:161], v230 offset:2048
	ds_read_b128 v[162:165], v230 offset:3072
	ds_read_b128 v[166:169], v231
	ds_read_b128 v[170:173], v231 offset:1024
	ds_read_b128 v[174:177], v231 offset:2048
	ds_read_b128 v[178:181], v231 offset:3072
	s_add_u32 s52, s76, 0xfff80080
	s_addc_u32 s53, s77, -1
	s_cmp_eq_u32 vcc_hi, 28
	s_cselect_b32 s81, s11, s53
	s_cselect_b32 s80, s55, s52
	s_cselect_b32 s79, s51, vcc_lo
	s_cselect_b32 s78, s73, s75
	v_lshl_add_u64 v[214:215], s[76:77], 0, v[150:151]
	s_add_i32 m0, s28, 0xc000
	ds_read_b128 v[182:185], v232
	ds_read_b128 v[186:189], v232 offset:1024
	ds_read_b128 v[190:193], v232 offset:2048
	ds_read_b128 v[194:197], v232 offset:3072
	ds_read_b128 v[198:201], v232 offset:4096
	ds_read_b128 v[202:205], v232 offset:5120
	ds_read_b128 v[206:209], v232 offset:6144
	ds_read_b128 v[210:213], v232 offset:7168
	global_load_lds_dwordx4 v[214:215], off
	s_add_i32 m0, s28, 0xe000
	v_lshl_add_u64 v[214:215], s[76:77], 0, v[152:153]
	global_load_lds_dwordx4 v[214:215], off
	s_waitcnt vmcnt(8)
	s_waitcnt lgkmcnt(0)
	s_setprio 1
	s_barrier
	v_mfma_f32_16x16x32_bf16 v[124:127], v[128:131], v[182:185], v[124:127]
	v_mfma_f32_16x16x32_bf16 v[120:123], v[158:161], v[182:185], v[120:123]
	v_mfma_f32_16x16x32_bf16 v[116:119], v[128:131], v[190:193], v[116:119]
	v_mfma_f32_16x16x32_bf16 v[112:115], v[158:161], v[190:193], v[112:115]
	v_mfma_f32_16x16x32_bf16 v[108:111], v[128:131], v[198:201], v[108:111]
	v_mfma_f32_16x16x32_bf16 v[104:107], v[158:161], v[198:201], v[104:107]
	v_mfma_f32_16x16x32_bf16 v[100:103], v[128:131], v[206:209], v[100:103]
	v_mfma_f32_16x16x32_bf16 v[96:99], v[158:161], v[206:209], v[96:99]
	v_mfma_f32_16x16x32_bf16 v[124:127], v[132:135], v[186:189], v[124:127]
	v_mfma_f32_16x16x32_bf16 v[120:123], v[162:165], v[186:189], v[120:123]
	v_mfma_f32_16x16x32_bf16 v[116:119], v[132:135], v[194:197], v[116:119]
	v_mfma_f32_16x16x32_bf16 v[112:115], v[162:165], v[194:197], v[112:115]
	v_mfma_f32_16x16x32_bf16 v[108:111], v[132:135], v[202:205], v[108:111]
	v_mfma_f32_16x16x32_bf16 v[104:107], v[162:165], v[202:205], v[104:107]
	v_mfma_f32_16x16x32_bf16 v[100:103], v[132:135], v[210:213], v[100:103]
	v_mfma_f32_16x16x32_bf16 v[96:99], v[162:165], v[210:213], v[96:99]
	s_setprio 0
	s_setprio 1
	v_mfma_f32_16x16x32_bf16 v[60:63], v[166:169], v[182:185], v[60:63]
	v_mfma_f32_16x16x32_bf16 v[56:59], v[174:177], v[182:185], v[56:59]
	v_mfma_f32_16x16x32_bf16 v[52:55], v[166:169], v[190:193], v[52:55]
	v_mfma_f32_16x16x32_bf16 v[48:51], v[174:177], v[190:193], v[48:51]
	v_mfma_f32_16x16x32_bf16 v[44:47], v[166:169], v[198:201], v[44:47]
	v_mfma_f32_16x16x32_bf16 v[40:43], v[174:177], v[198:201], v[40:43]
	v_mfma_f32_16x16x32_bf16 v[36:39], v[166:169], v[206:209], v[36:39]
	v_mfma_f32_16x16x32_bf16 v[32:35], v[174:177], v[206:209], v[32:35]
	v_mfma_f32_16x16x32_bf16 v[60:63], v[170:173], v[186:189], v[60:63]
	v_mfma_f32_16x16x32_bf16 v[56:59], v[178:181], v[186:189], v[56:59]
	v_mfma_f32_16x16x32_bf16 v[52:55], v[170:173], v[194:197], v[52:55]
	v_mfma_f32_16x16x32_bf16 v[48:51], v[178:181], v[194:197], v[48:51]
	v_mfma_f32_16x16x32_bf16 v[44:47], v[170:173], v[202:205], v[44:47]
	v_mfma_f32_16x16x32_bf16 v[40:43], v[178:181], v[202:205], v[40:43]
	s_setprio 2
	s_barrier
	v_mfma_f32_16x16x32_bf16 v[36:39], v[170:173], v[210:213], v[36:39]
	v_mfma_f32_16x16x32_bf16 v[32:35], v[178:181], v[210:213], v[32:35]
	s_setprio 0
	s_add_i32 s52, s93, s3
	v_lshl_add_u64 v[214:215], s[78:79], 0, v[138:139]
	s_mov_b32 m0, s52
	ds_read_b128 v[182:185], v232 offset:16384
	ds_read_b128 v[186:189], v232 offset:17408
	ds_read_b128 v[190:193], v232 offset:18432
	ds_read_b128 v[194:197], v232 offset:19456
	ds_read_b128 v[198:201], v232 offset:20480
	ds_read_b128 v[202:205], v232 offset:21504
	ds_read_b128 v[206:209], v232 offset:22528
	ds_read_b128 v[210:213], v232 offset:23552
	global_load_lds_dwordx4 v[214:215], off
	s_add_i32 m0, s52, 0x2000
	s_add_u32 s52, s78, 0x80000
	v_lshl_add_u64 v[216:217], s[78:79], 0, v[142:143]
	s_addc_u32 s53, s79, 0
	s_add_i32 s56, s10, s3
	global_load_lds_dwordx4 v[216:217], off
	v_lshl_add_u64 v[218:219], s[52:53], 0, v[138:139]
	s_mov_b32 m0, s56
	v_lshl_add_u64 v[220:221], s[80:81], 0, v[140:141]
	global_load_lds_dwordx4 v[218:219], off
	s_add_i32 m0, s56, 0x2000
	v_lshl_add_u64 v[218:219], s[52:53], 0, v[142:143]
	global_load_lds_dwordx4 v[218:219], off
	s_mov_b32 m0, s28
	v_lshl_add_u64 v[218:219], s[80:81], 0, v[136:137]
	global_load_lds_dwordx4 v[218:219], off
	s_mov_b32 m0, s29
	s_nop 0
	global_load_lds_dwordx4 v[220:221], off
	s_waitcnt vmcnt(8)
	s_waitcnt lgkmcnt(0)
	s_setprio 1
	s_barrier
; #define PG8_STAGE(bufoff, gbase, voff) do { _Pragma("unroll") for (int _i = 0; _i < 2; ++_i) \
;         __builtin_amdgcn_global_load_lds((const unsigned*)((const char*)(gbase) + (voff)[_i]), (PG8_LAS unsigned*)(lds + (bufoff) + ldsw + _i * 8192), 16, 0, 0); } while (0)
; #define PG8_LDA(dst, b, h) do { _Pragma("unroll") for (int m = 0; m < 4; ++m) _Pragma("unroll") for (int k = 0; k < 2; ++k) dst[m][k] = *(const PG8_LAS bf16x8*)(lds + PG8_SA(b, h) + aoff + m * 2048 + k * 1024); } while (0)
; #define PG8_LDB(dst, b, h) do { _Pragma("unroll") for (int n = 0; n < 2; ++n) _Pragma("unroll") for (int k = 0; k < 2; ++k) dst[n][k] = *(const PG8_LAS bf16x8*)(lds + PG8_SB(b, h) + boff + n * 2048 + k * 1024); } while (0)
; #define PG8_MMA(ai, bj, At, Bt) do { __builtin_amdgcn_s_setprio(1); _Pragma("unroll") for (int m = 0; m < 4; ++m) _Pragma("unroll") for (int n = 0; n < 2; ++n) _Pragma("unroll") for (int k = 0; k < 2; ++k) \
;         acc[ai][bj][m][n] = __builtin_amdgcn_mfma_f32_16x16x32_bf16(Bt[n][k], At[m][k], acc[ai][bj][m][n], 0, 0, 0); __builtin_amdgcn_s_setprio(0); } while (0)
; #define PG8_WAIT_V(n) asm volatile("s_waitcnt vmcnt(" #n ")" ::: "memory")
; #define PG8_WAIT_L(n) asm volatile("s_waitcnt lgkmcnt(" #n ")" ::: "memory")
; #define PG8_BAR __builtin_amdgcn_s_barrier()
; #define PG8_SCHED __builtin_amdgcn_sched_barrier(0)
; template <class Epi, class Sched, bool ALIGN_EPI = false, bool SP2 = false>
; __device__ __forceinline__ void gemm_phase(PG8_LAS unsigned char* lds, const Gemm g, const Sched& S, const Epi& E) {
;     ...
;             PG8_WAIT_V(8); PG8_WAIT_L(0); PG8_BAR; PG8_MMA(1, 0, At, B0); PG8_MMA(1, 1, At, B1); PG8_BAR; PG8_SCHED;
;             PG8_LDB(B0, 1, 0); PG8_LDB(B1, 1, 1); PG8_SCHED; PG8_LDA(At, 1, 0); PG8_STAGE(PG8_SA(0, 1), a2 + hstep, voffA);
;             PG8_WAIT_V(8); PG8_WAIT_L(0); PG8_BAR; PG8_MMA(0, 0, At, B0); PG8_MMA(0, 1, At, B1); PG8_BAR; PG8_SCHED;
	v_mfma_f32_16x16x32_bf16 v[92:95], v[128:131], v[182:185], v[92:95]
	v_mfma_f32_16x16x32_bf16 v[88:91], v[158:161], v[182:185], v[88:91]
	v_mfma_f32_16x16x32_bf16 v[84:87], v[128:131], v[190:193], v[84:87]
	v_mfma_f32_16x16x32_bf16 v[80:83], v[158:161], v[190:193], v[80:83]
	v_mfma_f32_16x16x32_bf16 v[76:79], v[128:131], v[198:201], v[76:79]
	v_mfma_f32_16x16x32_bf16 v[72:75], v[158:161], v[198:201], v[72:75]
	v_mfma_f32_16x16x32_bf16 v[68:71], v[128:131], v[206:209], v[68:71]
	v_mfma_f32_16x16x32_bf16 v[64:67], v[158:161], v[206:209], v[64:67]
	v_mfma_f32_16x16x32_bf16 v[92:95], v[132:135], v[186:189], v[92:95]
	v_mfma_f32_16x16x32_bf16 v[88:91], v[162:165], v[186:189], v[88:91]
	v_mfma_f32_16x16x32_bf16 v[84:87], v[132:135], v[194:197], v[84:87]
	v_mfma_f32_16x16x32_bf16 v[80:83], v[162:165], v[194:197], v[80:83]
	v_mfma_f32_16x16x32_bf16 v[76:79], v[132:135], v[202:205], v[76:79]
	v_mfma_f32_16x16x32_bf16 v[72:75], v[162:165], v[202:205], v[72:75]
	v_mfma_f32_16x16x32_bf16 v[68:71], v[132:135], v[210:213], v[68:71]
	v_mfma_f32_16x16x32_bf16 v[64:67], v[162:165], v[210:213], v[64:67]
	s_setprio 0
	s_setprio 1
	v_mfma_f32_16x16x32_bf16 v[28:31], v[166:169], v[182:185], v[28:31]
	v_mfma_f32_16x16x32_bf16 v[24:27], v[174:177], v[182:185], v[24:27]
	v_mfma_f32_16x16x32_bf16 v[20:23], v[166:169], v[190:193], v[20:23]
	v_mfma_f32_16x16x32_bf16 v[16:19], v[174:177], v[190:193], v[16:19]
	v_mfma_f32_16x16x32_bf16 v[12:15], v[166:169], v[198:201], v[12:15]
	v_mfma_f32_16x16x32_bf16 v[8:11], v[174:177], v[198:201], v[8:11]
	v_mfma_f32_16x16x32_bf16 v[4:7], v[166:169], v[206:209], v[4:7]
	v_mfma_f32_16x16x32_bf16 v[0:3], v[174:177], v[206:209], v[0:3]
	v_mfma_f32_16x16x32_bf16 v[28:31], v[170:173], v[186:189], v[28:31]
	v_mfma_f32_16x16x32_bf16 v[24:27], v[178:181], v[186:189], v[24:27]
	v_mfma_f32_16x16x32_bf16 v[20:23], v[170:173], v[194:197], v[20:23]
	v_mfma_f32_16x16x32_bf16 v[16:19], v[178:181], v[194:197], v[16:19]
	v_mfma_f32_16x16x32_bf16 v[12:15], v[170:173], v[202:205], v[12:15]
	v_mfma_f32_16x16x32_bf16 v[8:11], v[178:181], v[202:205], v[8:11]
	s_setprio 2
	s_barrier
	v_mfma_f32_16x16x32_bf16 v[4:7], v[170:173], v[210:213], v[4:7]
	v_mfma_f32_16x16x32_bf16 v[0:3], v[178:181], v[210:213], v[0:3]
	s_setprio 0
	s_add_i32 s56, 0, 0x18000
	s_add_i32 s57, 0, 0x1c000
	v_add_u32_e32 v162, s56, v228
	v_add_u32_e32 v178, s57, v228
	ds_read_b128 v[128:131], v162
	ds_read_b128 v[132:135], v162 offset:1024
	ds_read_b128 v[158:161], v162 offset:2048
	ds_read_b128 v[162:165], v162 offset:3072
	ds_read_b128 v[166:169], v178
	ds_read_b128 v[170:173], v178 offset:1024
	ds_read_b128 v[174:177], v178 offset:2048
	ds_read_b128 v[178:181], v178 offset:3072
	s_add_u32 s52, s80, 0x80000
	s_addc_u32 s53, s81, 0
	s_mov_b32 m0, s33
	v_lshl_add_u64 v[234:235], s[52:53], 0, v[136:137]
	ds_read_b128 v[182:185], v232 offset:32768
	ds_read_b128 v[186:189], v232 offset:33792
	ds_read_b128 v[190:193], v232 offset:34816
	ds_read_b128 v[194:197], v232 offset:35840
	ds_read_b128 v[198:201], v232 offset:36864
	ds_read_b128 v[202:205], v232 offset:37888
	ds_read_b128 v[206:209], v232 offset:38912
	ds_read_b128 v[210:213], v232 offset:39936
	global_load_lds_dwordx4 v[234:235], off
	s_mov_b32 m0, s38
	v_lshl_add_u64 v[234:235], s[52:53], 0, v[140:141]
	global_load_lds_dwordx4 v[234:235], off
	s_waitcnt vmcnt(8)
	s_waitcnt lgkmcnt(0)
	s_setprio 1
	s_barrier
	v_mfma_f32_16x16x32_bf16 v[124:127], v[128:131], v[182:185], v[124:127]
	v_mfma_f32_16x16x32_bf16 v[120:123], v[158:161], v[182:185], v[120:123]
	v_mfma_f32_16x16x32_bf16 v[116:119], v[128:131], v[190:193], v[116:119]
	v_mfma_f32_16x16x32_bf16 v[112:115], v[158:161], v[190:193], v[112:115]
	v_mfma_f32_16x16x32_bf16 v[108:111], v[128:131], v[198:201], v[108:111]
	v_mfma_f32_16x16x32_bf16 v[104:107], v[158:161], v[198:201], v[104:107]
	v_mfma_f32_16x16x32_bf16 v[100:103], v[128:131], v[206:209], v[100:103]
	v_mfma_f32_16x16x32_bf16 v[96:99], v[158:161], v[206:209], v[96:99]
	v_mfma_f32_16x16x32_bf16 v[124:127], v[132:135], v[186:189], v[124:127]
	v_mfma_f32_16x16x32_bf16 v[120:123], v[162:165], v[186:189], v[120:123]
	v_mfma_f32_16x16x32_bf16 v[116:119], v[132:135], v[194:197], v[116:119]
	v_mfma_f32_16x16x32_bf16 v[112:115], v[162:165], v[194:197], v[112:115]
	v_mfma_f32_16x16x32_bf16 v[108:111], v[132:135], v[202:205], v[108:111]
	v_mfma_f32_16x16x32_bf16 v[104:107], v[162:165], v[202:205], v[104:107]
	v_mfma_f32_16x16x32_bf16 v[100:103], v[132:135], v[210:213], v[100:103]
	v_mfma_f32_16x16x32_bf16 v[96:99], v[162:165], v[210:213], v[96:99]
	s_setprio 0
	s_setprio 1
	v_mfma_f32_16x16x32_bf16 v[60:63], v[166:169], v[182:185], v[60:63]
	v_mfma_f32_16x16x32_bf16 v[56:59], v[174:177], v[182:185], v[56:59]
	v_mfma_f32_16x16x32_bf16 v[52:55], v[166:169], v[190:193], v[52:55]
	v_mfma_f32_16x16x32_bf16 v[48:51], v[174:177], v[190:193], v[48:51]
	v_mfma_f32_16x16x32_bf16 v[44:47], v[166:169], v[198:201], v[44:47]
	v_mfma_f32_16x16x32_bf16 v[40:43], v[174:177], v[198:201], v[40:43]
	v_mfma_f32_16x16x32_bf16 v[36:39], v[166:169], v[206:209], v[36:39]
	v_mfma_f32_16x16x32_bf16 v[32:35], v[174:177], v[206:209], v[32:35]
	v_mfma_f32_16x16x32_bf16 v[60:63], v[170:173], v[186:189], v[60:63]
	v_mfma_f32_16x16x32_bf16 v[56:59], v[178:181], v[186:189], v[56:59]
	v_mfma_f32_16x16x32_bf16 v[52:55], v[170:173], v[194:197], v[52:55]
	v_mfma_f32_16x16x32_bf16 v[48:51], v[178:181], v[194:197], v[48:51]
	v_mfma_f32_16x16x32_bf16 v[44:47], v[170:173], v[202:205], v[44:47]
	v_mfma_f32_16x16x32_bf16 v[40:43], v[178:181], v[202:205], v[40:43]
	s_setprio 2
	s_barrier
; #define PG8_STAGE(bufoff, gbase, voff) do { _Pragma("unroll") for (int _i = 0; _i < 2; ++_i) \
;         __builtin_amdgcn_global_load_lds((const unsigned*)((const char*)(gbase) + (voff)[_i]), (PG8_LAS unsigned*)(lds + (bufoff) + ldsw + _i * 8192), 16, 0, 0); } while (0)
; #define PG8_LDA(dst, b, h) do { _Pragma("unroll") for (int m = 0; m < 4; ++m) _Pragma("unroll") for (int k = 0; k < 2; ++k) dst[m][k] = *(const PG8_LAS bf16x8*)(lds + PG8_SA(b, h) + aoff + m * 2048 + k * 1024); } while (0)
; #define PG8_MMA(ai, bj, At, Bt) do { __builtin_amdgcn_s_setprio(1); _Pragma("unroll") for (int m = 0; m < 4; ++m) _Pragma("unroll") for (int n = 0; n < 2; ++n) _Pragma("unroll") for (int k = 0; k < 2; ++k) \
;         acc[ai][bj][m][n] = __builtin_amdgcn_mfma_f32_16x16x32_bf16(Bt[n][k], At[m][k], acc[ai][bj][m][n], 0, 0, 0); __builtin_amdgcn_s_setprio(0); } while (0)
; #define PG8_WAIT_V(n) asm volatile("s_waitcnt vmcnt(" #n ")" ::: "memory")
; #define PG8_WAIT_L(n) asm volatile("s_waitcnt lgkmcnt(" #n ")" ::: "memory")
; #define PG8_BAR __builtin_amdgcn_s_barrier()
; #define PG8_SCHED __builtin_amdgcn_sched_barrier(0)
; template <class Epi, class Sched, bool ALIGN_EPI = false, bool SP2 = false>
; __device__ __forceinline__ void gemm_phase(PG8_LAS unsigned char* lds, const Gemm g, const Sched& S, const Epi& E) {
;     ...
;         for (int t = 0; t < nt; t += 2) {
;             const bool last = (t == nt - 2);
;     ...
;             PG8_WAIT_V(8); PG8_WAIT_L(0); PG8_BAR; PG8_MMA(0, 0, At, B0); PG8_MMA(0, 1, At, B1); PG8_BAR; PG8_SCHED;
;             PG8_LDA(At, 1, 1); PG8_STAGE(PG8_SB(1, 0), b3, voffB); PG8_STAGE(PG8_SB(1, 1), b3 + hstep, voffB); PG8_STAGE(PG8_SA(1, 0), a3, voffA);
;             PG8_WAIT_V(8); PG8_WAIT_L(0); PG8_BAR; PG8_MMA(1, 0, At, B0); PG8_MMA(1, 1, At, B1); PG8_BAR; PG8_SCHED;
	v_mfma_f32_16x16x32_bf16 v[36:39], v[170:173], v[210:213], v[36:39]
	v_mfma_f32_16x16x32_bf16 v[32:35], v[178:181], v[210:213], v[32:35]
	s_setprio 0
	s_add_i32 s52, s56, s3
	v_lshl_add_u64 v[214:215], v[214:215], 0, s[14:15]
	s_mov_b32 m0, s52
	ds_read_b128 v[182:185], v232 offset:49152
	ds_read_b128 v[186:189], v232 offset:50176
	ds_read_b128 v[190:193], v232 offset:51200
	ds_read_b128 v[194:197], v232 offset:52224
	ds_read_b128 v[198:201], v232 offset:53248
	ds_read_b128 v[202:205], v232 offset:54272
	ds_read_b128 v[206:209], v232 offset:55296
	ds_read_b128 v[210:213], v232 offset:56320
	global_load_lds_dwordx4 v[214:215], off
	s_add_i32 m0, s52, 0x2000
	s_add_u32 s52, s78, 0x80080
	v_lshl_add_u64 v[214:215], v[216:217], 0, s[14:15]
	s_addc_u32 s53, s79, 0
	s_add_i32 s56, s57, s3
	global_load_lds_dwordx4 v[214:215], off
	s_mov_b32 m0, s56
	v_lshl_add_u64 v[214:215], s[52:53], 0, v[138:139]
	global_load_lds_dwordx4 v[214:215], off
	s_add_i32 m0, s56, 0x2000
	v_lshl_add_u64 v[214:215], s[52:53], 0, v[142:143]
	global_load_lds_dwordx4 v[214:215], off
	s_mov_b32 m0, s88
	v_lshl_add_u64 v[214:215], v[218:219], 0, s[14:15]
	global_load_lds_dwordx4 v[214:215], off
	s_mov_b32 m0, s89
	v_lshl_add_u64 v[214:215], v[220:221], 0, s[14:15]
	global_load_lds_dwordx4 v[214:215], off
	s_waitcnt vmcnt(8)
	s_waitcnt lgkmcnt(0)
	s_setprio 1
	s_barrier
	v_mfma_f32_16x16x32_bf16 v[92:95], v[128:131], v[182:185], v[92:95]
	v_mfma_f32_16x16x32_bf16 v[88:91], v[158:161], v[182:185], v[88:91]
	v_mfma_f32_16x16x32_bf16 v[84:87], v[128:131], v[190:193], v[84:87]
	v_mfma_f32_16x16x32_bf16 v[80:83], v[158:161], v[190:193], v[80:83]
	v_mfma_f32_16x16x32_bf16 v[76:79], v[128:131], v[198:201], v[76:79]
	v_mfma_f32_16x16x32_bf16 v[72:75], v[158:161], v[198:201], v[72:75]
	v_mfma_f32_16x16x32_bf16 v[68:71], v[128:131], v[206:209], v[68:71]
	v_mfma_f32_16x16x32_bf16 v[64:67], v[158:161], v[206:209], v[64:67]
	v_mfma_f32_16x16x32_bf16 v[92:95], v[132:135], v[186:189], v[92:95]
	v_mfma_f32_16x16x32_bf16 v[88:91], v[162:165], v[186:189], v[88:91]
	v_mfma_f32_16x16x32_bf16 v[84:87], v[132:135], v[194:197], v[84:87]
	v_mfma_f32_16x16x32_bf16 v[80:83], v[162:165], v[194:197], v[80:83]
	v_mfma_f32_16x16x32_bf16 v[76:79], v[132:135], v[202:205], v[76:79]
	v_mfma_f32_16x16x32_bf16 v[72:75], v[162:165], v[202:205], v[72:75]
	v_mfma_f32_16x16x32_bf16 v[68:71], v[132:135], v[210:213], v[68:71]
	v_mfma_f32_16x16x32_bf16 v[64:67], v[162:165], v[210:213], v[64:67]
	s_setprio 0
	s_setprio 1
	v_mfma_f32_16x16x32_bf16 v[28:31], v[166:169], v[182:185], v[28:31]
	v_mfma_f32_16x16x32_bf16 v[24:27], v[174:177], v[182:185], v[24:27]
	v_mfma_f32_16x16x32_bf16 v[20:23], v[166:169], v[190:193], v[20:23]
	v_mfma_f32_16x16x32_bf16 v[16:19], v[174:177], v[190:193], v[16:19]
	v_mfma_f32_16x16x32_bf16 v[12:15], v[166:169], v[198:201], v[12:15]
	v_mfma_f32_16x16x32_bf16 v[8:11], v[174:177], v[198:201], v[8:11]
	v_mfma_f32_16x16x32_bf16 v[4:7], v[166:169], v[206:209], v[4:7]
	v_mfma_f32_16x16x32_bf16 v[0:3], v[174:177], v[206:209], v[0:3]
	v_mfma_f32_16x16x32_bf16 v[28:31], v[170:173], v[186:189], v[28:31]
	v_mfma_f32_16x16x32_bf16 v[24:27], v[178:181], v[186:189], v[24:27]
	v_mfma_f32_16x16x32_bf16 v[20:23], v[170:173], v[194:197], v[20:23]
	v_mfma_f32_16x16x32_bf16 v[16:19], v[178:181], v[194:197], v[16:19]
	v_mfma_f32_16x16x32_bf16 v[12:15], v[170:173], v[202:205], v[12:15]
	v_mfma_f32_16x16x32_bf16 v[8:11], v[178:181], v[202:205], v[8:11]
	s_setprio 2
	s_barrier
	v_mfma_f32_16x16x32_bf16 v[4:7], v[170:173], v[210:213], v[4:7]
	v_mfma_f32_16x16x32_bf16 v[0:3], v[178:181], v[210:213], v[0:3]
	s_setprio 0
	s_add_i32 vcc_hi, vcc_hi, 2
	s_add_u32 s76, s76, 0x100
	s_addc_u32 s77, s77, 0
	s_add_u32 s75, s75, 0x100
	s_addc_u32 vcc_lo, vcc_lo, 0
	s_cmp_gt_u32 vcc_hi, 29
	s_cbranch_scc0 .LBB0_374
	s_and_b64 vcc, exec, s[48:49]
	s_cbranch_vccz .LBB0_377
	s_barrier

; #define PG8_STAGE(bufoff, gbase, voff) do { _Pragma("unroll") for (int _i = 0; _i < 2; ++_i) \
;         __builtin_amdgcn_global_load_lds((const unsigned*)((const char*)(gbase) + (voff)[_i]), (PG8_LAS unsigned*)(lds + (bufoff) + ldsw + _i * 8192), 16, 0, 0); } while (0)
; #define PG8_LDA(dst, b, h) do { _Pragma("unroll") for (int m = 0; m < 4; ++m) _Pragma("unroll") for (int k = 0; k < 2; ++k) dst[m][k] = *(const PG8_LAS bf16x8*)(lds + PG8_SA(b, h) + aoff + m * 2048 + k * 1024); } while (0)
; #define PG8_LDB(dst, b, h) do { _Pragma("unroll") for (int n = 0; n < 2; ++n) _Pragma("unroll") for (int k = 0; k < 2; ++k) dst[n][k] = *(const PG8_LAS bf16x8*)(lds + PG8_SB(b, h) + boff + n * 2048 + k * 1024); } while (0)
; #define PG8_MMA(ai, bj, At, Bt) do { __builtin_amdgcn_s_setprio(1); _Pragma("unroll") for (int m = 0; m < 4; ++m) _Pragma("unroll") for (int n = 0; n < 2; ++n) _Pragma("unroll") for (int k = 0; k < 2; ++k) \
;         acc[ai][bj][m][n] = __builtin_amdgcn_mfma_f32_16x16x32_bf16(Bt[n][k], At[m][k], acc[ai][bj][m][n], 0, 0, 0); __builtin_amdgcn_s_setprio(0); } while (0)
; #define PG8_WAIT_V(n) asm volatile("s_waitcnt vmcnt(" #n ")" ::: "memory")
; #define PG8_WAIT_L(n) asm volatile("s_waitcnt lgkmcnt(" #n ")" ::: "memory")
; #define PG8_BAR __builtin_amdgcn_s_barrier()
; #define PG8_SCHED __builtin_amdgcn_sched_barrier(0)
; template <class Epi, class Sched, bool ALIGN_EPI = false, bool SP2 = false>
; __device__ __forceinline__ void gemm_phase(PG8_LAS unsigned char* lds, const Gemm g, const Sched& S, const Epi& E) {
;     ...
;         for (int t = 0; t < nt; t += 2) {
;             const bool last = (t == nt - 2);
;             const char* a1 = cA + (size_t)(t + 1) * kstep;
;             const char* a2 = last ? nA : cA + (size_t)(t + 2) * kstep; const char* b2 = last ? nB : cB + (size_t)(t + 2) * kstep;
;             const char* a3 = a2 + kstep; const char* b3 = b2 + kstep;
;             if constexpr (SP2) {
;             PG8_LDB(B0, 0, 0); PG8_LDB(B1, 0, 1); PG8_SCHED; PG8_LDA(At, 0, 0); PG8_STAGE(PG8_SA(1, 1), a1 + hstep, voffA);
;             PG8_WAIT_V(8); PG8_WAIT_L(0); PG8_BAR; PG8_MMA(0, 0, At, B0); PG8_MMA(0, 1, At, B1); PG8_BAR; PG8_SCHED;
;             PG8_LDA(At, 0, 1); PG8_STAGE(PG8_SB(0, 0), b2, voffB); PG8_STAGE(PG8_SB(0, 1), b2 + hstep, voffB); PG8_STAGE(PG8_SA(0, 0), a2, voffA);
.LBB0_410:
	ds_read_b128 v[166:169], v145
	ds_read_b128 v[170:173], v145 offset:1024
	ds_read_b128 v[174:177], v145 offset:2048
	ds_read_b128 v[178:181], v145 offset:3072
	ds_read_b128 v[182:185], v149
	ds_read_b128 v[186:189], v149 offset:1024
	ds_read_b128 v[190:193], v149 offset:2048
	ds_read_b128 v[194:197], v149 offset:3072
	s_add_u32 s52, s74, 0xfff80080
	s_addc_u32 s53, s75, -1
	s_cmp_eq_u32 s51, 4
	s_cselect_b32 s79, s55, s53
	s_cselect_b32 s78, s54, s52
	s_cselect_b32 s77, s69, s49
	s_cselect_b32 s76, s68, s37
	s_mov_b32 m0, s80
	v_lshl_add_u64 v[230:231], s[74:75], 0, v[160:161]
	ds_read_b128 v[198:201], v164
	ds_read_b128 v[202:205], v164 offset:1024
	ds_read_b128 v[206:209], v164 offset:2048
	ds_read_b128 v[210:213], v164 offset:3072
	ds_read_b128 v[214:217], v164 offset:4096
	ds_read_b128 v[218:221], v164 offset:5120
	ds_read_b128 v[222:225], v164 offset:6144
	ds_read_b128 v[226:229], v164 offset:7168
	global_load_lds_dwordx4 v[230:231], off
	s_mov_b32 m0, s81
	v_lshl_add_u64 v[230:231], s[74:75], 0, v[162:163]
	global_load_lds_dwordx4 v[230:231], off
	s_waitcnt vmcnt(8)
	s_waitcnt lgkmcnt(0)
	s_setprio 1
	s_barrier
	v_mfma_f32_16x16x32_bf16 v[124:127], v[166:169], v[198:201], v[124:127]
	v_mfma_f32_16x16x32_bf16 v[120:123], v[174:177], v[198:201], v[120:123]
	v_mfma_f32_16x16x32_bf16 v[116:119], v[166:169], v[206:209], v[116:119]
	v_mfma_f32_16x16x32_bf16 v[108:111], v[174:177], v[206:209], v[108:111]
	v_mfma_f32_16x16x32_bf16 v[100:103], v[166:169], v[214:217], v[100:103]
	v_mfma_f32_16x16x32_bf16 v[92:95], v[174:177], v[214:217], v[92:95]
	v_mfma_f32_16x16x32_bf16 v[84:87], v[166:169], v[222:225], v[84:87]
	v_mfma_f32_16x16x32_bf16 v[76:79], v[174:177], v[222:225], v[76:79]
	v_mfma_f32_16x16x32_bf16 v[124:127], v[170:173], v[202:205], v[124:127]
	v_mfma_f32_16x16x32_bf16 v[120:123], v[178:181], v[202:205], v[120:123]
	v_mfma_f32_16x16x32_bf16 v[116:119], v[170:173], v[210:213], v[116:119]
	v_mfma_f32_16x16x32_bf16 v[108:111], v[178:181], v[210:213], v[108:111]
	v_mfma_f32_16x16x32_bf16 v[100:103], v[170:173], v[218:221], v[100:103]
	v_mfma_f32_16x16x32_bf16 v[92:95], v[178:181], v[218:221], v[92:95]
	v_mfma_f32_16x16x32_bf16 v[84:87], v[170:173], v[226:229], v[84:87]
	v_mfma_f32_16x16x32_bf16 v[76:79], v[178:181], v[226:229], v[76:79]
	s_setprio 0
	s_setprio 1
	v_mfma_f32_16x16x32_bf16 v[112:115], v[182:185], v[198:201], v[112:115]
	v_mfma_f32_16x16x32_bf16 v[104:107], v[190:193], v[198:201], v[104:107]
	v_mfma_f32_16x16x32_bf16 v[96:99], v[182:185], v[206:209], v[96:99]
	v_mfma_f32_16x16x32_bf16 v[88:91], v[190:193], v[206:209], v[88:91]
	v_mfma_f32_16x16x32_bf16 v[80:83], v[182:185], v[214:217], v[80:83]
	v_mfma_f32_16x16x32_bf16 v[72:75], v[190:193], v[214:217], v[72:75]
	v_mfma_f32_16x16x32_bf16 v[68:71], v[182:185], v[222:225], v[68:71]
	v_mfma_f32_16x16x32_bf16 v[64:67], v[190:193], v[222:225], v[64:67]
	v_mfma_f32_16x16x32_bf16 v[112:115], v[186:189], v[202:205], v[112:115]
	v_mfma_f32_16x16x32_bf16 v[104:107], v[194:197], v[202:205], v[104:107]
	v_mfma_f32_16x16x32_bf16 v[96:99], v[186:189], v[210:213], v[96:99]
	v_mfma_f32_16x16x32_bf16 v[88:91], v[194:197], v[210:213], v[88:91]
	v_mfma_f32_16x16x32_bf16 v[80:83], v[186:189], v[218:221], v[80:83]
	v_mfma_f32_16x16x32_bf16 v[72:75], v[194:197], v[218:221], v[72:75]
	s_setprio 2
	s_barrier
	v_mfma_f32_16x16x32_bf16 v[68:71], v[186:189], v[226:229], v[68:71]
	v_mfma_f32_16x16x32_bf16 v[64:67], v[194:197], v[226:229], v[64:67]
	s_setprio 0
	s_mov_b32 m0, s84
	v_lshl_add_u64 v[230:231], s[76:77], 0, v[138:139]
	s_add_u32 s52, s76, 0x80000
	ds_read_b128 v[198:201], v164 offset:16384
	ds_read_b128 v[202:205], v164 offset:17408
	ds_read_b128 v[206:209], v164 offset:18432
	ds_read_b128 v[210:213], v164 offset:19456
	ds_read_b128 v[214:217], v164 offset:20480
	ds_read_b128 v[218:221], v164 offset:21504
	ds_read_b128 v[222:225], v164 offset:22528
	ds_read_b128 v[226:229], v164 offset:23552
	global_load_lds_dwordx4 v[230:231], off
	v_lshl_add_u64 v[232:233], s[76:77], 0, v[142:143]
	s_mov_b32 m0, s85
	s_addc_u32 s53, s77, 0
	global_load_lds_dwordx4 v[232:233], off
	v_lshl_add_u64 v[234:235], s[52:53], 0, v[138:139]
	s_mov_b32 m0, s86
	v_lshl_add_u64 v[236:237], s[78:79], 0, v[140:141]
	global_load_lds_dwordx4 v[234:235], off
	s_mov_b32 m0, s87
	v_lshl_add_u64 v[234:235], s[52:53], 0, v[142:143]
	global_load_lds_dwordx4 v[234:235], off
	s_mov_b32 m0, s10
	v_lshl_add_u64 v[234:235], s[78:79], 0, v[136:137]
	global_load_lds_dwordx4 v[234:235], off
	s_mov_b32 m0, s11
	s_nop 0
	global_load_lds_dwordx4 v[236:237], off
	s_waitcnt vmcnt(8)
	s_waitcnt lgkmcnt(0)
	s_setprio 1
	s_barrier
; #define PG8_STAGE(bufoff, gbase, voff) do { _Pragma("unroll") for (int _i = 0; _i < 2; ++_i) \
;         __builtin_amdgcn_global_load_lds((const unsigned*)((const char*)(gbase) + (voff)[_i]), (PG8_LAS unsigned*)(lds + (bufoff) + ldsw + _i * 8192), 16, 0, 0); } while (0)
; #define PG8_LDA(dst, b, h) do { _Pragma("unroll") for (int m = 0; m < 4; ++m) _Pragma("unroll") for (int k = 0; k < 2; ++k) dst[m][k] = *(const PG8_LAS bf16x8*)(lds + PG8_SA(b, h) + aoff + m * 2048 + k * 1024); } while (0)
; #define PG8_LDB(dst, b, h) do { _Pragma("unroll") for (int n = 0; n < 2; ++n) _Pragma("unroll") for (int k = 0; k < 2; ++k) dst[n][k] = *(const PG8_LAS bf16x8*)(lds + PG8_SB(b, h) + boff + n * 2048 + k * 1024); } while (0)
; #define PG8_MMA(ai, bj, At, Bt) do { __builtin_amdgcn_s_setprio(1); _Pragma("unroll") for (int m = 0; m < 4; ++m) _Pragma("unroll") for (int n = 0; n < 2; ++n) _Pragma("unroll") for (int k = 0; k < 2; ++k) \
;         acc[ai][bj][m][n] = __builtin_amdgcn_mfma_f32_16x16x32_bf16(Bt[n][k], At[m][k], acc[ai][bj][m][n], 0, 0, 0); __builtin_amdgcn_s_setprio(0); } while (0)
; #define PG8_WAIT_V(n) asm volatile("s_waitcnt vmcnt(" #n ")" ::: "memory")
; #define PG8_WAIT_L(n) asm volatile("s_waitcnt lgkmcnt(" #n ")" ::: "memory")
; #define PG8_BAR __builtin_amdgcn_s_barrier()
; #define PG8_SCHED __builtin_amdgcn_sched_barrier(0)
; template <class Epi, class Sched, bool ALIGN_EPI = false, bool SP2 = false>
; __device__ __forceinline__ void gemm_phase(PG8_LAS unsigned char* lds, const Gemm g, const Sched& S, const Epi& E) {
;     ...
;             PG8_WAIT_V(8); PG8_WAIT_L(0); PG8_BAR; PG8_MMA(1, 0, At, B0); PG8_MMA(1, 1, At, B1); PG8_BAR; PG8_SCHED;
;             PG8_LDB(B0, 1, 0); PG8_LDB(B1, 1, 1); PG8_SCHED; PG8_LDA(At, 1, 0); PG8_STAGE(PG8_SA(0, 1), a2 + hstep, voffA);
;             PG8_WAIT_V(8); PG8_WAIT_L(0); PG8_BAR; PG8_MMA(0, 0, At, B0); PG8_MMA(0, 1, At, B1); PG8_BAR; PG8_SCHED;
	v_mfma_f32_16x16x32_bf16 v[60:63], v[166:169], v[198:201], v[60:63]
	v_mfma_f32_16x16x32_bf16 v[56:59], v[174:177], v[198:201], v[56:59]
	v_mfma_f32_16x16x32_bf16 v[52:55], v[166:169], v[206:209], v[52:55]
	v_mfma_f32_16x16x32_bf16 v[44:47], v[174:177], v[206:209], v[44:47]
	v_mfma_f32_16x16x32_bf16 v[36:39], v[166:169], v[214:217], v[36:39]
	v_mfma_f32_16x16x32_bf16 v[28:31], v[174:177], v[214:217], v[28:31]
	v_mfma_f32_16x16x32_bf16 v[20:23], v[166:169], v[222:225], v[20:23]
	v_mfma_f32_16x16x32_bf16 v[12:15], v[174:177], v[222:225], v[12:15]
	v_mfma_f32_16x16x32_bf16 v[60:63], v[170:173], v[202:205], v[60:63]
	v_mfma_f32_16x16x32_bf16 v[56:59], v[178:181], v[202:205], v[56:59]
	v_mfma_f32_16x16x32_bf16 v[52:55], v[170:173], v[210:213], v[52:55]
	v_mfma_f32_16x16x32_bf16 v[44:47], v[178:181], v[210:213], v[44:47]
	v_mfma_f32_16x16x32_bf16 v[36:39], v[170:173], v[218:221], v[36:39]
	v_mfma_f32_16x16x32_bf16 v[28:31], v[178:181], v[218:221], v[28:31]
	v_mfma_f32_16x16x32_bf16 v[20:23], v[170:173], v[226:229], v[20:23]
	v_mfma_f32_16x16x32_bf16 v[12:15], v[178:181], v[226:229], v[12:15]
	s_setprio 0
	s_setprio 1
	v_mfma_f32_16x16x32_bf16 v[48:51], v[182:185], v[198:201], v[48:51]
	v_mfma_f32_16x16x32_bf16 v[40:43], v[190:193], v[198:201], v[40:43]
	v_mfma_f32_16x16x32_bf16 v[32:35], v[182:185], v[206:209], v[32:35]
	v_mfma_f32_16x16x32_bf16 v[24:27], v[190:193], v[206:209], v[24:27]
	v_mfma_f32_16x16x32_bf16 v[16:19], v[182:185], v[214:217], v[16:19]
	v_mfma_f32_16x16x32_bf16 v[8:11], v[190:193], v[214:217], v[8:11]
	v_mfma_f32_16x16x32_bf16 v[4:7], v[182:185], v[222:225], v[4:7]
	v_mfma_f32_16x16x32_bf16 v[0:3], v[190:193], v[222:225], v[0:3]
	v_mfma_f32_16x16x32_bf16 v[48:51], v[186:189], v[202:205], v[48:51]
	v_mfma_f32_16x16x32_bf16 v[40:43], v[194:197], v[202:205], v[40:43]
	v_mfma_f32_16x16x32_bf16 v[32:35], v[186:189], v[210:213], v[32:35]
	v_mfma_f32_16x16x32_bf16 v[24:27], v[194:197], v[210:213], v[24:27]
	v_mfma_f32_16x16x32_bf16 v[16:19], v[186:189], v[218:221], v[16:19]
	v_mfma_f32_16x16x32_bf16 v[8:11], v[194:197], v[218:221], v[8:11]
	s_setprio 2
	s_barrier
	v_mfma_f32_16x16x32_bf16 v[4:7], v[186:189], v[226:229], v[4:7]
	v_mfma_f32_16x16x32_bf16 v[0:3], v[194:197], v[226:229], v[0:3]
	s_setprio 0
	ds_read_b128 v[166:169], v148
	ds_read_b128 v[170:173], v148 offset:1024
	ds_read_b128 v[174:177], v148 offset:2048
	ds_read_b128 v[178:181], v148 offset:3072
	ds_read_b128 v[182:185], v165
	ds_read_b128 v[186:189], v165 offset:1024
	ds_read_b128 v[190:193], v165 offset:2048
	ds_read_b128 v[194:197], v165 offset:3072
	s_add_u32 s52, s78, 0x80000
	s_addc_u32 s53, s79, 0
	s_mov_b32 m0, s28
	v_lshl_add_u64 v[238:239], s[52:53], 0, v[136:137]
	ds_read_b128 v[198:201], v164 offset:32768
	ds_read_b128 v[202:205], v164 offset:33792
	ds_read_b128 v[206:209], v164 offset:34816
	ds_read_b128 v[210:213], v164 offset:35840
	ds_read_b128 v[214:217], v164 offset:36864
	ds_read_b128 v[218:221], v164 offset:37888
	ds_read_b128 v[222:225], v164 offset:38912
	ds_read_b128 v[226:229], v164 offset:39936
	global_load_lds_dwordx4 v[238:239], off
	s_mov_b32 m0, s29
	v_lshl_add_u64 v[238:239], s[52:53], 0, v[140:141]
	global_load_lds_dwordx4 v[238:239], off
	s_waitcnt vmcnt(8)
	s_waitcnt lgkmcnt(0)
	s_setprio 1
	s_barrier
	v_mfma_f32_16x16x32_bf16 v[124:127], v[166:169], v[198:201], v[124:127]
	v_mfma_f32_16x16x32_bf16 v[120:123], v[174:177], v[198:201], v[120:123]
	v_mfma_f32_16x16x32_bf16 v[116:119], v[166:169], v[206:209], v[116:119]
	v_mfma_f32_16x16x32_bf16 v[108:111], v[174:177], v[206:209], v[108:111]
	v_mfma_f32_16x16x32_bf16 v[100:103], v[166:169], v[214:217], v[100:103]
	v_mfma_f32_16x16x32_bf16 v[92:95], v[174:177], v[214:217], v[92:95]
	v_mfma_f32_16x16x32_bf16 v[84:87], v[166:169], v[222:225], v[84:87]
	v_mfma_f32_16x16x32_bf16 v[76:79], v[174:177], v[222:225], v[76:79]
	v_mfma_f32_16x16x32_bf16 v[124:127], v[170:173], v[202:205], v[124:127]
	v_mfma_f32_16x16x32_bf16 v[120:123], v[178:181], v[202:205], v[120:123]
	v_mfma_f32_16x16x32_bf16 v[116:119], v[170:173], v[210:213], v[116:119]
	v_mfma_f32_16x16x32_bf16 v[108:111], v[178:181], v[210:213], v[108:111]
	v_mfma_f32_16x16x32_bf16 v[100:103], v[170:173], v[218:221], v[100:103]
	v_mfma_f32_16x16x32_bf16 v[92:95], v[178:181], v[218:221], v[92:95]
	v_mfma_f32_16x16x32_bf16 v[84:87], v[170:173], v[226:229], v[84:87]
	v_mfma_f32_16x16x32_bf16 v[76:79], v[178:181], v[226:229], v[76:79]
	s_setprio 0
	s_setprio 1
	v_mfma_f32_16x16x32_bf16 v[112:115], v[182:185], v[198:201], v[112:115]
	v_mfma_f32_16x16x32_bf16 v[104:107], v[190:193], v[198:201], v[104:107]
	v_mfma_f32_16x16x32_bf16 v[96:99], v[182:185], v[206:209], v[96:99]
	v_mfma_f32_16x16x32_bf16 v[88:91], v[190:193], v[206:209], v[88:91]
	v_mfma_f32_16x16x32_bf16 v[80:83], v[182:185], v[214:217], v[80:83]
	v_mfma_f32_16x16x32_bf16 v[72:75], v[190:193], v[214:217], v[72:75]
	v_mfma_f32_16x16x32_bf16 v[68:71], v[182:185], v[222:225], v[68:71]
	v_mfma_f32_16x16x32_bf16 v[64:67], v[190:193], v[222:225], v[64:67]
	v_mfma_f32_16x16x32_bf16 v[112:115], v[186:189], v[202:205], v[112:115]
	v_mfma_f32_16x16x32_bf16 v[104:107], v[194:197], v[202:205], v[104:107]
	v_mfma_f32_16x16x32_bf16 v[96:99], v[186:189], v[210:213], v[96:99]
	v_mfma_f32_16x16x32_bf16 v[88:91], v[194:197], v[210:213], v[88:91]
	v_mfma_f32_16x16x32_bf16 v[80:83], v[186:189], v[218:221], v[80:83]
	v_mfma_f32_16x16x32_bf16 v[72:75], v[194:197], v[218:221], v[72:75]
	s_setprio 2
	s_barrier
; #define PG8_STAGE(bufoff, gbase, voff) do { _Pragma("unroll") for (int _i = 0; _i < 2; ++_i) \
;         __builtin_amdgcn_global_load_lds((const unsigned*)((const char*)(gbase) + (voff)[_i]), (PG8_LAS unsigned*)(lds + (bufoff) + ldsw + _i * 8192), 16, 0, 0); } while (0)
; #define PG8_LDA(dst, b, h) do { _Pragma("unroll") for (int m = 0; m < 4; ++m) _Pragma("unroll") for (int k = 0; k < 2; ++k) dst[m][k] = *(const PG8_LAS bf16x8*)(lds + PG8_SA(b, h) + aoff + m * 2048 + k * 1024); } while (0)
; #define PG8_MMA(ai, bj, At, Bt) do { __builtin_amdgcn_s_setprio(1); _Pragma("unroll") for (int m = 0; m < 4; ++m) _Pragma("unroll") for (int n = 0; n < 2; ++n) _Pragma("unroll") for (int k = 0; k < 2; ++k) \
;         acc[ai][bj][m][n] = __builtin_amdgcn_mfma_f32_16x16x32_bf16(Bt[n][k], At[m][k], acc[ai][bj][m][n], 0, 0, 0); __builtin_amdgcn_s_setprio(0); } while (0)
; #define PG8_WAIT_V(n) asm volatile("s_waitcnt vmcnt(" #n ")" ::: "memory")
; #define PG8_WAIT_L(n) asm volatile("s_waitcnt lgkmcnt(" #n ")" ::: "memory")
; #define PG8_BAR __builtin_amdgcn_s_barrier()
; #define PG8_SCHED __builtin_amdgcn_sched_barrier(0)
; template <class Epi, class Sched, bool ALIGN_EPI = false, bool SP2 = false>
; __device__ __forceinline__ void gemm_phase(PG8_LAS unsigned char* lds, const Gemm g, const Sched& S, const Epi& E) {
;     ...
;             PG8_WAIT_V(8); PG8_WAIT_L(0); PG8_BAR; PG8_MMA(0, 0, At, B0); PG8_MMA(0, 1, At, B1); PG8_BAR; PG8_SCHED;
;             PG8_LDA(At, 1, 1); PG8_STAGE(PG8_SB(1, 0), b3, voffB); PG8_STAGE(PG8_SB(1, 1), b3 + hstep, voffB); PG8_STAGE(PG8_SA(1, 0), a3, voffA);
;             PG8_WAIT_V(8); PG8_WAIT_L(0); PG8_BAR; PG8_MMA(1, 0, At, B0); PG8_MMA(1, 1, At, B1); PG8_BAR; PG8_SCHED;
;     ...
;         if constexpr (ALIGN_EPI) { if (wr == 0) PG8_BAR; }
	v_mfma_f32_16x16x32_bf16 v[68:71], v[186:189], v[226:229], v[68:71]
	v_mfma_f32_16x16x32_bf16 v[64:67], v[194:197], v[226:229], v[64:67]
	s_setprio 0
	s_mov_b32 m0, s89
	v_lshl_add_u64 v[230:231], v[230:231], 0, s[12:13]
	ds_read_b128 v[198:201], v164 offset:49152
	ds_read_b128 v[202:205], v164 offset:50176
	ds_read_b128 v[206:209], v164 offset:51200
	ds_read_b128 v[210:213], v164 offset:52224
	ds_read_b128 v[214:217], v164 offset:53248
	ds_read_b128 v[218:221], v164 offset:54272
	ds_read_b128 v[222:225], v164 offset:55296
	ds_read_b128 v[226:229], v164 offset:56320
	global_load_lds_dwordx4 v[230:231], off
	s_add_i32 m0, s89, 0x2000
	s_add_u32 s52, s76, 0x80080
	v_lshl_add_u64 v[230:231], v[232:233], 0, s[12:13]
	s_addc_u32 s53, s77, 0
	s_add_i32 s56, s88, s3
	global_load_lds_dwordx4 v[230:231], off
	s_mov_b32 m0, s56
	v_lshl_add_u64 v[230:231], s[52:53], 0, v[138:139]
	global_load_lds_dwordx4 v[230:231], off
	s_add_i32 m0, s56, 0x2000
	v_lshl_add_u64 v[230:231], s[52:53], 0, v[142:143]
	global_load_lds_dwordx4 v[230:231], off
	s_mov_b32 m0, s38
	v_lshl_add_u64 v[230:231], v[234:235], 0, s[12:13]
	global_load_lds_dwordx4 v[230:231], off
	s_mov_b32 m0, s39
	v_lshl_add_u64 v[230:231], v[236:237], 0, s[12:13]
	global_load_lds_dwordx4 v[230:231], off
	s_waitcnt vmcnt(8)
	s_waitcnt lgkmcnt(0)
	s_setprio 1
	s_barrier
	v_mfma_f32_16x16x32_bf16 v[60:63], v[166:169], v[198:201], v[60:63]
	v_mfma_f32_16x16x32_bf16 v[56:59], v[174:177], v[198:201], v[56:59]
	v_mfma_f32_16x16x32_bf16 v[52:55], v[166:169], v[206:209], v[52:55]
	v_mfma_f32_16x16x32_bf16 v[44:47], v[174:177], v[206:209], v[44:47]
	v_mfma_f32_16x16x32_bf16 v[36:39], v[166:169], v[214:217], v[36:39]
	v_mfma_f32_16x16x32_bf16 v[28:31], v[174:177], v[214:217], v[28:31]
	v_mfma_f32_16x16x32_bf16 v[20:23], v[166:169], v[222:225], v[20:23]
	v_mfma_f32_16x16x32_bf16 v[12:15], v[174:177], v[222:225], v[12:15]
	v_mfma_f32_16x16x32_bf16 v[60:63], v[170:173], v[202:205], v[60:63]
	v_mfma_f32_16x16x32_bf16 v[56:59], v[178:181], v[202:205], v[56:59]
	v_mfma_f32_16x16x32_bf16 v[52:55], v[170:173], v[210:213], v[52:55]
	v_mfma_f32_16x16x32_bf16 v[44:47], v[178:181], v[210:213], v[44:47]
	v_mfma_f32_16x16x32_bf16 v[36:39], v[170:173], v[218:221], v[36:39]
	v_mfma_f32_16x16x32_bf16 v[28:31], v[178:181], v[218:221], v[28:31]
	v_mfma_f32_16x16x32_bf16 v[20:23], v[170:173], v[226:229], v[20:23]
	v_mfma_f32_16x16x32_bf16 v[12:15], v[178:181], v[226:229], v[12:15]
	s_setprio 0
	s_setprio 1
	v_mfma_f32_16x16x32_bf16 v[48:51], v[182:185], v[198:201], v[48:51]
	v_mfma_f32_16x16x32_bf16 v[40:43], v[190:193], v[198:201], v[40:43]
	v_mfma_f32_16x16x32_bf16 v[32:35], v[182:185], v[206:209], v[32:35]
	v_mfma_f32_16x16x32_bf16 v[24:27], v[190:193], v[206:209], v[24:27]
	v_mfma_f32_16x16x32_bf16 v[16:19], v[182:185], v[214:217], v[16:19]
	v_mfma_f32_16x16x32_bf16 v[8:11], v[190:193], v[214:217], v[8:11]
	v_mfma_f32_16x16x32_bf16 v[4:7], v[182:185], v[222:225], v[4:7]
	v_mfma_f32_16x16x32_bf16 v[0:3], v[190:193], v[222:225], v[0:3]
	v_mfma_f32_16x16x32_bf16 v[48:51], v[186:189], v[202:205], v[48:51]
	v_mfma_f32_16x16x32_bf16 v[40:43], v[194:197], v[202:205], v[40:43]
	v_mfma_f32_16x16x32_bf16 v[32:35], v[186:189], v[210:213], v[32:35]
	v_mfma_f32_16x16x32_bf16 v[24:27], v[194:197], v[210:213], v[24:27]
	v_mfma_f32_16x16x32_bf16 v[16:19], v[186:189], v[218:221], v[16:19]
	v_mfma_f32_16x16x32_bf16 v[8:11], v[194:197], v[218:221], v[8:11]
	s_setprio 2
	s_barrier
	v_mfma_f32_16x16x32_bf16 v[4:7], v[186:189], v[226:229], v[4:7]
	v_mfma_f32_16x16x32_bf16 v[0:3], v[194:197], v[226:229], v[0:3]
	s_setprio 0
	s_add_i32 s51, s51, 2
	s_add_u32 s74, s74, 0x100
	s_addc_u32 s75, s75, 0
	s_add_u32 s37, s37, 0x100
	s_addc_u32 s49, s49, 0
	s_cmp_gt_u32 s51, 5
	s_cbranch_scc0 .LBB0_410
	s_and_b64 vcc, exec, s[14:15]
	s_cbranch_vccz .LBB0_413
	s_barrier

; #define PG8_STAGE(bufoff, gbase, voff) do { _Pragma("unroll") for (int _i = 0; _i < 2; ++_i) \
;         __builtin_amdgcn_global_load_lds((const unsigned*)((const char*)(gbase) + (voff)[_i]), (PG8_LAS unsigned*)(lds + (bufoff) + ldsw + _i * 8192), 16, 0, 0); } while (0)
; #define PG8_LDA(dst, b, h) do { _Pragma("unroll") for (int m = 0; m < 4; ++m) _Pragma("unroll") for (int k = 0; k < 2; ++k) dst[m][k] = *(const PG8_LAS bf16x8*)(lds + PG8_SA(b, h) + aoff + m * 2048 + k * 1024); } while (0)
; #define PG8_LDB(dst, b, h) do { _Pragma("unroll") for (int n = 0; n < 2; ++n) _Pragma("unroll") for (int k = 0; k < 2; ++k) dst[n][k] = *(const PG8_LAS bf16x8*)(lds + PG8_SB(b, h) + boff + n * 2048 + k * 1024); } while (0)
; #define PG8_MMA(ai, bj, At, Bt) do { __builtin_amdgcn_s_setprio(1); _Pragma("unroll") for (int m = 0; m < 4; ++m) _Pragma("unroll") for (int n = 0; n < 2; ++n) _Pragma("unroll") for (int k = 0; k < 2; ++k) \
;         acc[ai][bj][m][n] = __builtin_amdgcn_mfma_f32_16x16x32_bf16(Bt[n][k], At[m][k], acc[ai][bj][m][n], 0, 0, 0); __builtin_amdgcn_s_setprio(0); } while (0)
; #define PG8_WAIT_V(n) asm volatile("s_waitcnt vmcnt(" #n ")" ::: "memory")
; #define PG8_WAIT_L(n) asm volatile("s_waitcnt lgkmcnt(" #n ")" ::: "memory")
; #define PG8_BAR __builtin_amdgcn_s_barrier()
; template <class Epi, class Sched, bool ALIGN_EPI = false, bool SP2 = false>
; __device__ __forceinline__ void gemm_phase(PG8_LAS unsigned char* lds, const Gemm g, const Sched& S, const Epi& E) {
;     ...
;             const bool last = (t == nt - 2);
;             const char* a1 = cA + (size_t)(t + 1) * kstep;
;             const char* a2 = last ? nA : cA + (size_t)(t + 2) * kstep; const char* b2 = last ? nB : cB + (size_t)(t + 2) * kstep;
;             const char* a3 = a2 + kstep; const char* b3 = b2 + kstep;
;             if constexpr (SP2) {
;             PG8_LDB(B0, 0, 0); PG8_LDB(B1, 0, 1); PG8_SCHED; PG8_LDA(At, 0, 0); PG8_STAGE(PG8_SA(1, 1), a1 + hstep, voffA);
;             PG8_WAIT_V(8); PG8_WAIT_L(0); PG8_BAR; PG8_MMA(0, 0, At, B0); PG8_MMA(0, 1, At, B1); PG8_BAR; PG8_SCHED;
;             PG8_LDA(At, 0, 1); PG8_STAGE(PG8_SB(0, 0), b2, voffB); PG8_STAGE(PG8_SB(0, 1), b2 + hstep, voffB); PG8_STAGE(PG8_SA(0, 0), a2, voffA);
;             PG8_WAIT_V(8); PG8_WAIT_L(0); PG8_BAR; PG8_MMA(1, 0, At, B0); PG8_MMA(1, 1, At, B1); PG8_BAR; PG8_SCHED;
.LBB0_545:
	ds_read_b128 v[112:115], v174
	ds_read_b128 v[116:119], v174 offset:1024
	ds_read_b128 v[120:123], v174 offset:2048
	ds_read_b128 v[124:127], v174 offset:3072
	ds_read_b128 v[164:167], v175
	ds_read_b128 v[168:171], v175 offset:1024
	ds_read_b128 v[178:181], v175 offset:2048
	ds_read_b128 v[182:185], v175 offset:3072
	s_add_u32 s52, s68, 0xfff80080
	s_addc_u32 s53, s69, -1
	s_cmp_eq_u32 s88, 28
	s_cselect_b32 s73, s41, s53
	s_cselect_b32 s72, s84, s52
	s_cselect_b32 s71, s37, s87
	s_cselect_b32 s70, s85, s86
	v_lshl_add_u64 v[218:219], s[68:69], 0, v[156:157]
	s_add_i32 m0, s39, 0xc000
	ds_read_b128 v[186:189], v176
	ds_read_b128 v[190:193], v176 offset:1024
	ds_read_b128 v[194:197], v176 offset:2048
	ds_read_b128 v[198:201], v176 offset:3072
	ds_read_b128 v[202:205], v176 offset:4096
	ds_read_b128 v[206:209], v176 offset:5120
	ds_read_b128 v[210:213], v176 offset:6144
	ds_read_b128 v[214:217], v176 offset:7168
	global_load_lds_dwordx4 v[218:219], off
	s_add_i32 m0, s39, 0xe000
	v_lshl_add_u64 v[218:219], s[68:69], 0, v[158:159]
	global_load_lds_dwordx4 v[218:219], off
	s_waitcnt vmcnt(8)
	s_waitcnt lgkmcnt(0)
	s_setprio 1
	s_barrier
	v_mfma_f32_16x16x32_bf16 v[140:143], v[112:115], v[186:189], v[140:143]
	v_mfma_f32_16x16x32_bf16 v[136:139], v[120:123], v[186:189], v[136:139]
	v_mfma_f32_16x16x32_bf16 v[108:111], v[112:115], v[194:197], v[108:111]
	v_mfma_f32_16x16x32_bf16 v[104:107], v[120:123], v[194:197], v[104:107]
	v_mfma_f32_16x16x32_bf16 v[92:95], v[112:115], v[202:205], v[92:95]
	v_mfma_f32_16x16x32_bf16 v[88:91], v[120:123], v[202:205], v[88:91]
	v_mfma_f32_16x16x32_bf16 v[76:79], v[112:115], v[210:213], v[76:79]
	v_mfma_f32_16x16x32_bf16 v[72:75], v[120:123], v[210:213], v[72:75]
	v_mfma_f32_16x16x32_bf16 v[140:143], v[116:119], v[190:193], v[140:143]
	v_mfma_f32_16x16x32_bf16 v[136:139], v[124:127], v[190:193], v[136:139]
	v_mfma_f32_16x16x32_bf16 v[108:111], v[116:119], v[198:201], v[108:111]
	v_mfma_f32_16x16x32_bf16 v[104:107], v[124:127], v[198:201], v[104:107]
	v_mfma_f32_16x16x32_bf16 v[92:95], v[116:119], v[206:209], v[92:95]
	v_mfma_f32_16x16x32_bf16 v[88:91], v[124:127], v[206:209], v[88:91]
	v_mfma_f32_16x16x32_bf16 v[76:79], v[116:119], v[214:217], v[76:79]
	v_mfma_f32_16x16x32_bf16 v[72:75], v[124:127], v[214:217], v[72:75]
	s_setprio 0
	s_setprio 1
	v_mfma_f32_16x16x32_bf16 v[132:135], v[164:167], v[186:189], v[132:135]
	v_mfma_f32_16x16x32_bf16 v[128:131], v[178:181], v[186:189], v[128:131]
	v_mfma_f32_16x16x32_bf16 v[100:103], v[164:167], v[194:197], v[100:103]
	v_mfma_f32_16x16x32_bf16 v[96:99], v[178:181], v[194:197], v[96:99]
	v_mfma_f32_16x16x32_bf16 v[84:87], v[164:167], v[202:205], v[84:87]
	v_mfma_f32_16x16x32_bf16 v[80:83], v[178:181], v[202:205], v[80:83]
	v_mfma_f32_16x16x32_bf16 v[68:71], v[164:167], v[210:213], v[68:71]
	v_mfma_f32_16x16x32_bf16 v[64:67], v[178:181], v[210:213], v[64:67]
	v_mfma_f32_16x16x32_bf16 v[132:135], v[168:171], v[190:193], v[132:135]
	v_mfma_f32_16x16x32_bf16 v[128:131], v[182:185], v[190:193], v[128:131]
	v_mfma_f32_16x16x32_bf16 v[100:103], v[168:171], v[198:201], v[100:103]
	v_mfma_f32_16x16x32_bf16 v[96:99], v[182:185], v[198:201], v[96:99]
	v_mfma_f32_16x16x32_bf16 v[84:87], v[168:171], v[206:209], v[84:87]
	v_mfma_f32_16x16x32_bf16 v[80:83], v[182:185], v[206:209], v[80:83]
	s_setprio 2
	s_barrier
	v_mfma_f32_16x16x32_bf16 v[68:71], v[168:171], v[214:217], v[68:71]
	v_mfma_f32_16x16x32_bf16 v[64:67], v[182:185], v[214:217], v[64:67]
	s_setprio 0
	s_add_i32 s52, s81, s29
	v_lshl_add_u64 v[218:219], s[70:71], 0, v[152:153]
	s_mov_b32 m0, s52
	ds_read_b128 v[186:189], v176 offset:16384
	ds_read_b128 v[190:193], v176 offset:17408
	ds_read_b128 v[194:197], v176 offset:18432
	ds_read_b128 v[198:201], v176 offset:19456
	ds_read_b128 v[202:205], v176 offset:20480
	ds_read_b128 v[206:209], v176 offset:21504
	ds_read_b128 v[210:213], v176 offset:22528
	ds_read_b128 v[214:217], v176 offset:23552
	global_load_lds_dwordx4 v[218:219], off
	s_add_i32 m0, s52, 0x2000
	s_add_u32 s52, s70, 0x80000
	v_lshl_add_u64 v[220:221], s[70:71], 0, v[148:149]
	s_addc_u32 s53, s71, 0
	s_add_i32 s56, s82, s29
	global_load_lds_dwordx4 v[220:221], off
	v_lshl_add_u64 v[222:223], s[52:53], 0, v[152:153]
	s_mov_b32 m0, s56
	v_lshl_add_u64 v[224:225], s[72:73], 0, v[150:151]
	global_load_lds_dwordx4 v[222:223], off
	s_add_i32 m0, s56, 0x2000
	v_lshl_add_u64 v[222:223], s[52:53], 0, v[148:149]
	global_load_lds_dwordx4 v[222:223], off
	s_mov_b32 m0, s39
	v_lshl_add_u64 v[222:223], s[72:73], 0, v[154:155]
	global_load_lds_dwordx4 v[222:223], off
	s_mov_b32 m0, s55
	s_nop 0
	global_load_lds_dwordx4 v[224:225], off
	s_waitcnt vmcnt(8)
	s_waitcnt lgkmcnt(0)
	s_setprio 1
	s_barrier
; #define PG8_STAGE(bufoff, gbase, voff) do { _Pragma("unroll") for (int _i = 0; _i < 2; ++_i) \
;         __builtin_amdgcn_global_load_lds((const unsigned*)((const char*)(gbase) + (voff)[_i]), (PG8_LAS unsigned*)(lds + (bufoff) + ldsw + _i * 8192), 16, 0, 0); } while (0)
; #define PG8_LDA(dst, b, h) do { _Pragma("unroll") for (int m = 0; m < 4; ++m) _Pragma("unroll") for (int k = 0; k < 2; ++k) dst[m][k] = *(const PG8_LAS bf16x8*)(lds + PG8_SA(b, h) + aoff + m * 2048 + k * 1024); } while (0)
; #define PG8_LDB(dst, b, h) do { _Pragma("unroll") for (int n = 0; n < 2; ++n) _Pragma("unroll") for (int k = 0; k < 2; ++k) dst[n][k] = *(const PG8_LAS bf16x8*)(lds + PG8_SB(b, h) + boff + n * 2048 + k * 1024); } while (0)
; #define PG8_MMA(ai, bj, At, Bt) do { __builtin_amdgcn_s_setprio(1); _Pragma("unroll") for (int m = 0; m < 4; ++m) _Pragma("unroll") for (int n = 0; n < 2; ++n) _Pragma("unroll") for (int k = 0; k < 2; ++k) \
;         acc[ai][bj][m][n] = __builtin_amdgcn_mfma_f32_16x16x32_bf16(Bt[n][k], At[m][k], acc[ai][bj][m][n], 0, 0, 0); __builtin_amdgcn_s_setprio(0); } while (0)
; #define PG8_WAIT_V(n) asm volatile("s_waitcnt vmcnt(" #n ")" ::: "memory")
; #define PG8_WAIT_L(n) asm volatile("s_waitcnt lgkmcnt(" #n ")" ::: "memory")
; #define PG8_BAR __builtin_amdgcn_s_barrier()
; #define PG8_SCHED __builtin_amdgcn_sched_barrier(0)
; template <class Epi, class Sched, bool ALIGN_EPI = false, bool SP2 = false>
; __device__ __forceinline__ void gemm_phase(PG8_LAS unsigned char* lds, const Gemm g, const Sched& S, const Epi& E) {
;     ...
;             PG8_WAIT_V(8); PG8_WAIT_L(0); PG8_BAR; PG8_MMA(1, 0, At, B0); PG8_MMA(1, 1, At, B1); PG8_BAR; PG8_SCHED;
;             PG8_LDB(B0, 1, 0); PG8_LDB(B1, 1, 1); PG8_SCHED; PG8_LDA(At, 1, 0); PG8_STAGE(PG8_SA(0, 1), a2 + hstep, voffA);
;             PG8_WAIT_V(8); PG8_WAIT_L(0); PG8_BAR; PG8_MMA(0, 0, At, B0); PG8_MMA(0, 1, At, B1); PG8_BAR; PG8_SCHED;
	v_mfma_f32_16x16x32_bf16 v[60:63], v[112:115], v[186:189], v[60:63]
	v_mfma_f32_16x16x32_bf16 v[56:59], v[120:123], v[186:189], v[56:59]
	v_mfma_f32_16x16x32_bf16 v[44:47], v[112:115], v[194:197], v[44:47]
	v_mfma_f32_16x16x32_bf16 v[40:43], v[120:123], v[194:197], v[40:43]
	v_mfma_f32_16x16x32_bf16 v[28:31], v[112:115], v[202:205], v[28:31]
	v_mfma_f32_16x16x32_bf16 v[24:27], v[120:123], v[202:205], v[24:27]
	v_mfma_f32_16x16x32_bf16 v[12:15], v[112:115], v[210:213], v[12:15]
	v_mfma_f32_16x16x32_bf16 v[8:11], v[120:123], v[210:213], v[8:11]
	v_mfma_f32_16x16x32_bf16 v[60:63], v[116:119], v[190:193], v[60:63]
	v_mfma_f32_16x16x32_bf16 v[56:59], v[124:127], v[190:193], v[56:59]
	v_mfma_f32_16x16x32_bf16 v[44:47], v[116:119], v[198:201], v[44:47]
	v_mfma_f32_16x16x32_bf16 v[40:43], v[124:127], v[198:201], v[40:43]
	v_mfma_f32_16x16x32_bf16 v[28:31], v[116:119], v[206:209], v[28:31]
	v_mfma_f32_16x16x32_bf16 v[24:27], v[124:127], v[206:209], v[24:27]
	v_mfma_f32_16x16x32_bf16 v[12:15], v[116:119], v[214:217], v[12:15]
	v_mfma_f32_16x16x32_bf16 v[8:11], v[124:127], v[214:217], v[8:11]
	s_setprio 0
	s_setprio 1
	v_mfma_f32_16x16x32_bf16 v[52:55], v[164:167], v[186:189], v[52:55]
	v_mfma_f32_16x16x32_bf16 v[48:51], v[178:181], v[186:189], v[48:51]
	v_mfma_f32_16x16x32_bf16 v[36:39], v[164:167], v[194:197], v[36:39]
	v_mfma_f32_16x16x32_bf16 v[32:35], v[178:181], v[194:197], v[32:35]
	v_mfma_f32_16x16x32_bf16 v[20:23], v[164:167], v[202:205], v[20:23]
	v_mfma_f32_16x16x32_bf16 v[16:19], v[178:181], v[202:205], v[16:19]
	v_mfma_f32_16x16x32_bf16 v[4:7], v[164:167], v[210:213], v[4:7]
	v_mfma_f32_16x16x32_bf16 v[0:3], v[178:181], v[210:213], v[0:3]
	v_mfma_f32_16x16x32_bf16 v[52:55], v[168:171], v[190:193], v[52:55]
	v_mfma_f32_16x16x32_bf16 v[48:51], v[182:185], v[190:193], v[48:51]
	v_mfma_f32_16x16x32_bf16 v[36:39], v[168:171], v[198:201], v[36:39]
	v_mfma_f32_16x16x32_bf16 v[32:35], v[182:185], v[198:201], v[32:35]
	v_mfma_f32_16x16x32_bf16 v[20:23], v[168:171], v[206:209], v[20:23]
	v_mfma_f32_16x16x32_bf16 v[16:19], v[182:185], v[206:209], v[16:19]
	s_setprio 2
	s_barrier
	v_mfma_f32_16x16x32_bf16 v[4:7], v[168:171], v[214:217], v[4:7]
	v_mfma_f32_16x16x32_bf16 v[0:3], v[182:185], v[214:217], v[0:3]
	s_setprio 0
	s_add_i32 s56, 0, 0x18000
	s_add_i32 s57, 0, 0x1c000
	v_add_u32_e32 v124, s56, v172
	v_add_u32_e32 v177, s57, v172
	ds_read_b128 v[112:115], v124
	ds_read_b128 v[116:119], v124 offset:1024
	ds_read_b128 v[120:123], v124 offset:2048
	ds_read_b128 v[124:127], v124 offset:3072
	ds_read_b128 v[164:167], v177
	ds_read_b128 v[168:171], v177 offset:1024
	ds_read_b128 v[178:181], v177 offset:2048
	ds_read_b128 v[182:185], v177 offset:3072
	s_add_u32 s52, s72, 0x80000
	s_addc_u32 s53, s73, 0
	s_mov_b32 m0, s74
	v_lshl_add_u64 v[226:227], s[52:53], 0, v[154:155]
	ds_read_b128 v[186:189], v176 offset:32768
	ds_read_b128 v[190:193], v176 offset:33792
	ds_read_b128 v[194:197], v176 offset:34816
	ds_read_b128 v[198:201], v176 offset:35840
	ds_read_b128 v[202:205], v176 offset:36864
	ds_read_b128 v[206:209], v176 offset:37888
	ds_read_b128 v[210:213], v176 offset:38912
	ds_read_b128 v[214:217], v176 offset:39936
	global_load_lds_dwordx4 v[226:227], off
	s_mov_b32 m0, s75
	v_lshl_add_u64 v[226:227], s[52:53], 0, v[150:151]
	global_load_lds_dwordx4 v[226:227], off
	s_waitcnt vmcnt(8)
	s_waitcnt lgkmcnt(0)
	s_setprio 1
	s_barrier
	v_mfma_f32_16x16x32_bf16 v[140:143], v[112:115], v[186:189], v[140:143]
	v_mfma_f32_16x16x32_bf16 v[136:139], v[120:123], v[186:189], v[136:139]
	v_mfma_f32_16x16x32_bf16 v[108:111], v[112:115], v[194:197], v[108:111]
	v_mfma_f32_16x16x32_bf16 v[104:107], v[120:123], v[194:197], v[104:107]
	v_mfma_f32_16x16x32_bf16 v[92:95], v[112:115], v[202:205], v[92:95]
	v_mfma_f32_16x16x32_bf16 v[88:91], v[120:123], v[202:205], v[88:91]
	v_mfma_f32_16x16x32_bf16 v[76:79], v[112:115], v[210:213], v[76:79]
	v_mfma_f32_16x16x32_bf16 v[72:75], v[120:123], v[210:213], v[72:75]
	v_mfma_f32_16x16x32_bf16 v[140:143], v[116:119], v[190:193], v[140:143]
	v_mfma_f32_16x16x32_bf16 v[136:139], v[124:127], v[190:193], v[136:139]
	v_mfma_f32_16x16x32_bf16 v[108:111], v[116:119], v[198:201], v[108:111]
	v_mfma_f32_16x16x32_bf16 v[104:107], v[124:127], v[198:201], v[104:107]
	v_mfma_f32_16x16x32_bf16 v[92:95], v[116:119], v[206:209], v[92:95]
	v_mfma_f32_16x16x32_bf16 v[88:91], v[124:127], v[206:209], v[88:91]
	v_mfma_f32_16x16x32_bf16 v[76:79], v[116:119], v[214:217], v[76:79]
	v_mfma_f32_16x16x32_bf16 v[72:75], v[124:127], v[214:217], v[72:75]
	s_setprio 0
	s_setprio 1
	v_mfma_f32_16x16x32_bf16 v[132:135], v[164:167], v[186:189], v[132:135]
	v_mfma_f32_16x16x32_bf16 v[128:131], v[178:181], v[186:189], v[128:131]
	v_mfma_f32_16x16x32_bf16 v[100:103], v[164:167], v[194:197], v[100:103]
	v_mfma_f32_16x16x32_bf16 v[96:99], v[178:181], v[194:197], v[96:99]
	v_mfma_f32_16x16x32_bf16 v[84:87], v[164:167], v[202:205], v[84:87]
	v_mfma_f32_16x16x32_bf16 v[80:83], v[178:181], v[202:205], v[80:83]
	v_mfma_f32_16x16x32_bf16 v[68:71], v[164:167], v[210:213], v[68:71]
	v_mfma_f32_16x16x32_bf16 v[64:67], v[178:181], v[210:213], v[64:67]
	v_mfma_f32_16x16x32_bf16 v[132:135], v[168:171], v[190:193], v[132:135]
	v_mfma_f32_16x16x32_bf16 v[128:131], v[182:185], v[190:193], v[128:131]
	v_mfma_f32_16x16x32_bf16 v[100:103], v[168:171], v[198:201], v[100:103]
	v_mfma_f32_16x16x32_bf16 v[96:99], v[182:185], v[198:201], v[96:99]
	v_mfma_f32_16x16x32_bf16 v[84:87], v[168:171], v[206:209], v[84:87]
	v_mfma_f32_16x16x32_bf16 v[80:83], v[182:185], v[206:209], v[80:83]
	s_setprio 2
	s_barrier
; #define PG8_STAGE(bufoff, gbase, voff) do { _Pragma("unroll") for (int _i = 0; _i < 2; ++_i) \
;         __builtin_amdgcn_global_load_lds((const unsigned*)((const char*)(gbase) + (voff)[_i]), (PG8_LAS unsigned*)(lds + (bufoff) + ldsw + _i * 8192), 16, 0, 0); } while (0)
; #define PG8_LDA(dst, b, h) do { _Pragma("unroll") for (int m = 0; m < 4; ++m) _Pragma("unroll") for (int k = 0; k < 2; ++k) dst[m][k] = *(const PG8_LAS bf16x8*)(lds + PG8_SA(b, h) + aoff + m * 2048 + k * 1024); } while (0)
; #define PG8_MMA(ai, bj, At, Bt) do { __builtin_amdgcn_s_setprio(1); _Pragma("unroll") for (int m = 0; m < 4; ++m) _Pragma("unroll") for (int n = 0; n < 2; ++n) _Pragma("unroll") for (int k = 0; k < 2; ++k) \
;         acc[ai][bj][m][n] = __builtin_amdgcn_mfma_f32_16x16x32_bf16(Bt[n][k], At[m][k], acc[ai][bj][m][n], 0, 0, 0); __builtin_amdgcn_s_setprio(0); } while (0)
; #define PG8_WAIT_V(n) asm volatile("s_waitcnt vmcnt(" #n ")" ::: "memory")
; #define PG8_WAIT_L(n) asm volatile("s_waitcnt lgkmcnt(" #n ")" ::: "memory")
; #define PG8_BAR __builtin_amdgcn_s_barrier()
; #define PG8_SCHED __builtin_amdgcn_sched_barrier(0)
; template <class Epi, class Sched, bool ALIGN_EPI = false, bool SP2 = false>
; __device__ __forceinline__ void gemm_phase(PG8_LAS unsigned char* lds, const Gemm g, const Sched& S, const Epi& E) {
;     ...
;             PG8_WAIT_V(8); PG8_WAIT_L(0); PG8_BAR; PG8_MMA(0, 0, At, B0); PG8_MMA(0, 1, At, B1); PG8_BAR; PG8_SCHED;
;             PG8_LDA(At, 1, 1); PG8_STAGE(PG8_SB(1, 0), b3, voffB); PG8_STAGE(PG8_SB(1, 1), b3 + hstep, voffB); PG8_STAGE(PG8_SA(1, 0), a3, voffA);
;             PG8_WAIT_V(8); PG8_WAIT_L(0); PG8_BAR; PG8_MMA(1, 0, At, B0); PG8_MMA(1, 1, At, B1); PG8_BAR; PG8_SCHED;
;     ...
;         if constexpr (ALIGN_EPI) { if (wr == 0) PG8_BAR; }
	v_mfma_f32_16x16x32_bf16 v[68:71], v[168:171], v[214:217], v[68:71]
	v_mfma_f32_16x16x32_bf16 v[64:67], v[182:185], v[214:217], v[64:67]
	s_setprio 0
	s_add_i32 s52, s56, s29
	v_lshl_add_u64 v[218:219], v[218:219], 0, s[12:13]
	s_mov_b32 m0, s52
	ds_read_b128 v[186:189], v176 offset:49152
	ds_read_b128 v[190:193], v176 offset:50176
	ds_read_b128 v[194:197], v176 offset:51200
	ds_read_b128 v[198:201], v176 offset:52224
	ds_read_b128 v[202:205], v176 offset:53248
	ds_read_b128 v[206:209], v176 offset:54272
	ds_read_b128 v[210:213], v176 offset:55296
	ds_read_b128 v[214:217], v176 offset:56320
	global_load_lds_dwordx4 v[218:219], off
	s_add_i32 m0, s52, 0x2000
	s_add_u32 s52, s70, 0x80080
	v_lshl_add_u64 v[218:219], v[220:221], 0, s[12:13]
	s_addc_u32 s53, s71, 0
	s_add_i32 s56, s57, s29
	global_load_lds_dwordx4 v[218:219], off
	s_mov_b32 m0, s56
	v_lshl_add_u64 v[218:219], s[52:53], 0, v[152:153]
	global_load_lds_dwordx4 v[218:219], off
	s_add_i32 m0, s56, 0x2000
	v_lshl_add_u64 v[218:219], s[52:53], 0, v[148:149]
	global_load_lds_dwordx4 v[218:219], off
	s_mov_b32 m0, s77
	v_lshl_add_u64 v[218:219], v[222:223], 0, s[12:13]
	global_load_lds_dwordx4 v[218:219], off
	s_mov_b32 m0, s78
	v_lshl_add_u64 v[218:219], v[224:225], 0, s[12:13]
	global_load_lds_dwordx4 v[218:219], off
	s_waitcnt vmcnt(8)
	s_waitcnt lgkmcnt(0)
	s_setprio 1
	s_barrier
	v_mfma_f32_16x16x32_bf16 v[60:63], v[112:115], v[186:189], v[60:63]
	v_mfma_f32_16x16x32_bf16 v[56:59], v[120:123], v[186:189], v[56:59]
	v_mfma_f32_16x16x32_bf16 v[44:47], v[112:115], v[194:197], v[44:47]
	v_mfma_f32_16x16x32_bf16 v[40:43], v[120:123], v[194:197], v[40:43]
	v_mfma_f32_16x16x32_bf16 v[28:31], v[112:115], v[202:205], v[28:31]
	v_mfma_f32_16x16x32_bf16 v[24:27], v[120:123], v[202:205], v[24:27]
	v_mfma_f32_16x16x32_bf16 v[12:15], v[112:115], v[210:213], v[12:15]
	v_mfma_f32_16x16x32_bf16 v[8:11], v[120:123], v[210:213], v[8:11]
	v_mfma_f32_16x16x32_bf16 v[60:63], v[116:119], v[190:193], v[60:63]
	v_mfma_f32_16x16x32_bf16 v[56:59], v[124:127], v[190:193], v[56:59]
	v_mfma_f32_16x16x32_bf16 v[44:47], v[116:119], v[198:201], v[44:47]
	v_mfma_f32_16x16x32_bf16 v[40:43], v[124:127], v[198:201], v[40:43]
	v_mfma_f32_16x16x32_bf16 v[28:31], v[116:119], v[206:209], v[28:31]
	v_mfma_f32_16x16x32_bf16 v[24:27], v[124:127], v[206:209], v[24:27]
	v_mfma_f32_16x16x32_bf16 v[12:15], v[116:119], v[214:217], v[12:15]
	v_mfma_f32_16x16x32_bf16 v[8:11], v[124:127], v[214:217], v[8:11]
	s_setprio 0
	s_setprio 1
	v_mfma_f32_16x16x32_bf16 v[52:55], v[164:167], v[186:189], v[52:55]
	v_mfma_f32_16x16x32_bf16 v[48:51], v[178:181], v[186:189], v[48:51]
	v_mfma_f32_16x16x32_bf16 v[36:39], v[164:167], v[194:197], v[36:39]
	v_mfma_f32_16x16x32_bf16 v[32:35], v[178:181], v[194:197], v[32:35]
	v_mfma_f32_16x16x32_bf16 v[20:23], v[164:167], v[202:205], v[20:23]
	v_mfma_f32_16x16x32_bf16 v[16:19], v[178:181], v[202:205], v[16:19]
	v_mfma_f32_16x16x32_bf16 v[4:7], v[164:167], v[210:213], v[4:7]
	v_mfma_f32_16x16x32_bf16 v[0:3], v[178:181], v[210:213], v[0:3]
	v_mfma_f32_16x16x32_bf16 v[52:55], v[168:171], v[190:193], v[52:55]
	v_mfma_f32_16x16x32_bf16 v[48:51], v[182:185], v[190:193], v[48:51]
	v_mfma_f32_16x16x32_bf16 v[36:39], v[168:171], v[198:201], v[36:39]
	v_mfma_f32_16x16x32_bf16 v[32:35], v[182:185], v[198:201], v[32:35]
	v_mfma_f32_16x16x32_bf16 v[20:23], v[168:171], v[206:209], v[20:23]
	v_mfma_f32_16x16x32_bf16 v[16:19], v[182:185], v[206:209], v[16:19]
	s_setprio 2
	s_barrier
	v_mfma_f32_16x16x32_bf16 v[4:7], v[168:171], v[214:217], v[4:7]
	v_mfma_f32_16x16x32_bf16 v[0:3], v[182:185], v[214:217], v[0:3]
	s_setprio 0
	s_add_i32 s88, s88, 2
	s_add_u32 s68, s68, 0x100
	s_addc_u32 s69, s69, 0
	s_add_u32 s86, s86, 0x100
	s_addc_u32 s87, s87, 0
	s_cmp_gt_u32 s88, 29
	s_cbranch_scc0 .LBB0_545
	s_and_b64 vcc, exec, s[14:15]
	s_cbranch_vccz .LBB0_548
	s_barrier

; #define PG8_STAGE(bufoff, gbase, voff) do { _Pragma("unroll") for (int _i = 0; _i < 2; ++_i) \
;         __builtin_amdgcn_global_load_lds((const unsigned*)((const char*)(gbase) + (voff)[_i]), (PG8_LAS unsigned*)(lds + (bufoff) + ldsw + _i * 8192), 16, 0, 0); } while (0)
; #define PG8_LDA(dst, b, h) do { _Pragma("unroll") for (int m = 0; m < 4; ++m) _Pragma("unroll") for (int k = 0; k < 2; ++k) dst[m][k] = *(const PG8_LAS bf16x8*)(lds + PG8_SA(b, h) + aoff + m * 2048 + k * 1024); } while (0)
; #define PG8_LDB(dst, b, h) do { _Pragma("unroll") for (int n = 0; n < 2; ++n) _Pragma("unroll") for (int k = 0; k < 2; ++k) dst[n][k] = *(const PG8_LAS bf16x8*)(lds + PG8_SB(b, h) + boff + n * 2048 + k * 1024); } while (0)
; #define PG8_MMA(ai, bj, At, Bt) do { __builtin_amdgcn_s_setprio(1); _Pragma("unroll") for (int m = 0; m < 4; ++m) _Pragma("unroll") for (int n = 0; n < 2; ++n) _Pragma("unroll") for (int k = 0; k < 2; ++k) \
;         acc[ai][bj][m][n] = __builtin_amdgcn_mfma_f32_16x16x32_bf16(Bt[n][k], At[m][k], acc[ai][bj][m][n], 0, 0, 0); __builtin_amdgcn_s_setprio(0); } while (0)
; #define PG8_WAIT_V(n) asm volatile("s_waitcnt vmcnt(" #n ")" ::: "memory")
; #define PG8_WAIT_L(n) asm volatile("s_waitcnt lgkmcnt(" #n ")" ::: "memory")
; #define PG8_BAR __builtin_amdgcn_s_barrier()
; template <class Epi, class Sched, bool ALIGN_EPI = false, bool SP2 = false>
; __device__ __forceinline__ void gemm_phase(PG8_LAS unsigned char* lds, const Gemm g, const Sched& S, const Epi& E) {
;     ...
;             const bool last = (t == nt - 2);
;             const char* a1 = cA + (size_t)(t + 1) * kstep;
;             const char* a2 = last ? nA : cA + (size_t)(t + 2) * kstep; const char* b2 = last ? nB : cB + (size_t)(t + 2) * kstep;
;             const char* a3 = a2 + kstep; const char* b3 = b2 + kstep;
;             if constexpr (SP2) {
;             PG8_LDB(B0, 0, 0); PG8_LDB(B1, 0, 1); PG8_SCHED; PG8_LDA(At, 0, 0); PG8_STAGE(PG8_SA(1, 1), a1 + hstep, voffA);
;             PG8_WAIT_V(8); PG8_WAIT_L(0); PG8_BAR; PG8_MMA(0, 0, At, B0); PG8_MMA(0, 1, At, B1); PG8_BAR; PG8_SCHED;
;             PG8_LDA(At, 0, 1); PG8_STAGE(PG8_SB(0, 0), b2, voffB); PG8_STAGE(PG8_SB(0, 1), b2 + hstep, voffB); PG8_STAGE(PG8_SA(0, 0), a2, voffA);
;             PG8_WAIT_V(8); PG8_WAIT_L(0); PG8_BAR; PG8_MMA(1, 0, At, B0); PG8_MMA(1, 1, At, B1); PG8_BAR; PG8_SCHED;
.LBB0_624:
	ds_read_b128 v[128:131], v214
	ds_read_b128 v[132:135], v214 offset:1024
	ds_read_b128 v[158:161], v214 offset:2048
	ds_read_b128 v[162:165], v214 offset:3072
	ds_read_b128 v[166:169], v215
	ds_read_b128 v[170:173], v215 offset:1024
	ds_read_b128 v[174:177], v215 offset:2048
	ds_read_b128 v[178:181], v215 offset:3072
	s_add_u32 s52, s74, 0xffe00080
	s_addc_u32 s53, s75, -1
	s_cmpk_eq_i32 vcc_hi, 0x7c
	s_cselect_b32 s79, s51, s53
	s_cselect_b32 s78, s71, s52
	s_cselect_b32 s77, s49, vcc_lo
	s_cselect_b32 s76, s73, s93
	v_lshl_add_u64 v[226:227], s[74:75], 0, v[150:151]
	s_add_i32 m0, s83, 0xc000
	ds_read_b128 v[182:185], v216
	ds_read_b128 v[186:189], v216 offset:1024
	ds_read_b128 v[190:193], v216 offset:2048
	ds_read_b128 v[194:197], v216 offset:3072
	ds_read_b128 v[198:201], v216 offset:4096
	ds_read_b128 v[202:205], v216 offset:5120
	ds_read_b128 v[218:221], v216 offset:6144
	ds_read_b128 v[222:225], v216 offset:7168
	global_load_lds_dwordx4 v[226:227], off
	s_add_i32 m0, s83, 0xe000
	v_lshl_add_u64 v[226:227], s[74:75], 0, v[152:153]
	global_load_lds_dwordx4 v[226:227], off
	s_waitcnt vmcnt(8)
	s_waitcnt lgkmcnt(0)
	s_setprio 1
	s_barrier
	v_mfma_f32_16x16x32_bf16 v[124:127], v[128:131], v[182:185], v[124:127]
	v_mfma_f32_16x16x32_bf16 v[120:123], v[158:161], v[182:185], v[120:123]
	v_mfma_f32_16x16x32_bf16 v[116:119], v[128:131], v[190:193], v[116:119]
	v_mfma_f32_16x16x32_bf16 v[112:115], v[158:161], v[190:193], v[112:115]
	v_mfma_f32_16x16x32_bf16 v[108:111], v[128:131], v[198:201], v[108:111]
	v_mfma_f32_16x16x32_bf16 v[104:107], v[158:161], v[198:201], v[104:107]
	v_mfma_f32_16x16x32_bf16 v[100:103], v[128:131], v[218:221], v[100:103]
	v_mfma_f32_16x16x32_bf16 v[96:99], v[158:161], v[218:221], v[96:99]
	v_mfma_f32_16x16x32_bf16 v[124:127], v[132:135], v[186:189], v[124:127]
	v_mfma_f32_16x16x32_bf16 v[120:123], v[162:165], v[186:189], v[120:123]
	v_mfma_f32_16x16x32_bf16 v[116:119], v[132:135], v[194:197], v[116:119]
	v_mfma_f32_16x16x32_bf16 v[112:115], v[162:165], v[194:197], v[112:115]
	v_mfma_f32_16x16x32_bf16 v[108:111], v[132:135], v[202:205], v[108:111]
	v_mfma_f32_16x16x32_bf16 v[104:107], v[162:165], v[202:205], v[104:107]
	v_mfma_f32_16x16x32_bf16 v[100:103], v[132:135], v[222:225], v[100:103]
	v_mfma_f32_16x16x32_bf16 v[96:99], v[162:165], v[222:225], v[96:99]
	s_setprio 0
	s_setprio 1
	v_mfma_f32_16x16x32_bf16 v[60:63], v[166:169], v[182:185], v[60:63]
	v_mfma_f32_16x16x32_bf16 v[56:59], v[174:177], v[182:185], v[56:59]
	v_mfma_f32_16x16x32_bf16 v[52:55], v[166:169], v[190:193], v[52:55]
	v_mfma_f32_16x16x32_bf16 v[48:51], v[174:177], v[190:193], v[48:51]
	v_mfma_f32_16x16x32_bf16 v[44:47], v[166:169], v[198:201], v[44:47]
	v_mfma_f32_16x16x32_bf16 v[40:43], v[174:177], v[198:201], v[40:43]
	v_mfma_f32_16x16x32_bf16 v[36:39], v[166:169], v[218:221], v[36:39]
	v_mfma_f32_16x16x32_bf16 v[32:35], v[174:177], v[218:221], v[32:35]
	v_mfma_f32_16x16x32_bf16 v[60:63], v[170:173], v[186:189], v[60:63]
	v_mfma_f32_16x16x32_bf16 v[56:59], v[178:181], v[186:189], v[56:59]
	v_mfma_f32_16x16x32_bf16 v[52:55], v[170:173], v[194:197], v[52:55]
	v_mfma_f32_16x16x32_bf16 v[48:51], v[178:181], v[194:197], v[48:51]
	v_mfma_f32_16x16x32_bf16 v[44:47], v[170:173], v[202:205], v[44:47]
	v_mfma_f32_16x16x32_bf16 v[40:43], v[178:181], v[202:205], v[40:43]
	s_setprio 2
	s_barrier
	v_mfma_f32_16x16x32_bf16 v[36:39], v[170:173], v[222:225], v[36:39]
	v_mfma_f32_16x16x32_bf16 v[32:35], v[178:181], v[222:225], v[32:35]
	s_setprio 0
	s_add_i32 s52, s33, s82
	v_lshl_add_u64 v[226:227], s[76:77], 0, v[138:139]
	s_mov_b32 m0, s52
	ds_read_b128 v[182:185], v216 offset:16384
	ds_read_b128 v[186:189], v216 offset:17408
	ds_read_b128 v[190:193], v216 offset:18432
	ds_read_b128 v[194:197], v216 offset:19456
	ds_read_b128 v[198:201], v216 offset:20480
	ds_read_b128 v[202:205], v216 offset:21504
	ds_read_b128 v[218:221], v216 offset:22528
	ds_read_b128 v[222:225], v216 offset:23552
	global_load_lds_dwordx4 v[226:227], off
	s_add_i32 m0, s52, 0x2000
	s_add_u32 s52, s76, 0x200000
	v_lshl_add_u64 v[228:229], s[76:77], 0, v[142:143]
	s_addc_u32 s53, s77, 0
	s_add_i32 s56, s92, s82
	global_load_lds_dwordx4 v[228:229], off
	v_lshl_add_u64 v[230:231], s[52:53], 0, v[138:139]
	s_mov_b32 m0, s56
	v_lshl_add_u64 v[232:233], s[78:79], 0, v[140:141]
	global_load_lds_dwordx4 v[230:231], off
	s_add_i32 m0, s56, 0x2000
	v_lshl_add_u64 v[230:231], s[52:53], 0, v[142:143]
	global_load_lds_dwordx4 v[230:231], off
	s_mov_b32 m0, s83
	v_lshl_add_u64 v[230:231], s[78:79], 0, v[136:137]
	global_load_lds_dwordx4 v[230:231], off
	s_mov_b32 m0, s84
	s_nop 0
	global_load_lds_dwordx4 v[232:233], off
	s_waitcnt vmcnt(8)
	s_waitcnt lgkmcnt(0)
	s_setprio 1
	s_barrier
; #define PG8_STAGE(bufoff, gbase, voff) do { _Pragma("unroll") for (int _i = 0; _i < 2; ++_i) \
;         __builtin_amdgcn_global_load_lds((const unsigned*)((const char*)(gbase) + (voff)[_i]), (PG8_LAS unsigned*)(lds + (bufoff) + ldsw + _i * 8192), 16, 0, 0); } while (0)
; #define PG8_LDA(dst, b, h) do { _Pragma("unroll") for (int m = 0; m < 4; ++m) _Pragma("unroll") for (int k = 0; k < 2; ++k) dst[m][k] = *(const PG8_LAS bf16x8*)(lds + PG8_SA(b, h) + aoff + m * 2048 + k * 1024); } while (0)
; #define PG8_LDB(dst, b, h) do { _Pragma("unroll") for (int n = 0; n < 2; ++n) _Pragma("unroll") for (int k = 0; k < 2; ++k) dst[n][k] = *(const PG8_LAS bf16x8*)(lds + PG8_SB(b, h) + boff + n * 2048 + k * 1024); } while (0)
; #define PG8_MMA(ai, bj, At, Bt) do { __builtin_amdgcn_s_setprio(1); _Pragma("unroll") for (int m = 0; m < 4; ++m) _Pragma("unroll") for (int n = 0; n < 2; ++n) _Pragma("unroll") for (int k = 0; k < 2; ++k) \
;         acc[ai][bj][m][n] = __builtin_amdgcn_mfma_f32_16x16x32_bf16(Bt[n][k], At[m][k], acc[ai][bj][m][n], 0, 0, 0); __builtin_amdgcn_s_setprio(0); } while (0)
; #define PG8_WAIT_V(n) asm volatile("s_waitcnt vmcnt(" #n ")" ::: "memory")
; #define PG8_WAIT_L(n) asm volatile("s_waitcnt lgkmcnt(" #n ")" ::: "memory")
; #define PG8_BAR __builtin_amdgcn_s_barrier()
; #define PG8_SCHED __builtin_amdgcn_sched_barrier(0)
; template <class Epi, class Sched, bool ALIGN_EPI = false, bool SP2 = false>
; __device__ __forceinline__ void gemm_phase(PG8_LAS unsigned char* lds, const Gemm g, const Sched& S, const Epi& E) {
;     ...
;             PG8_WAIT_V(8); PG8_WAIT_L(0); PG8_BAR; PG8_MMA(1, 0, At, B0); PG8_MMA(1, 1, At, B1); PG8_BAR; PG8_SCHED;
;             PG8_LDB(B0, 1, 0); PG8_LDB(B1, 1, 1); PG8_SCHED; PG8_LDA(At, 1, 0); PG8_STAGE(PG8_SA(0, 1), a2 + hstep, voffA);
;             PG8_WAIT_V(8); PG8_WAIT_L(0); PG8_BAR; PG8_MMA(0, 0, At, B0); PG8_MMA(0, 1, At, B1); PG8_BAR; PG8_SCHED;
	v_mfma_f32_16x16x32_bf16 v[92:95], v[128:131], v[182:185], v[92:95]
	v_mfma_f32_16x16x32_bf16 v[88:91], v[158:161], v[182:185], v[88:91]
	v_mfma_f32_16x16x32_bf16 v[84:87], v[128:131], v[190:193], v[84:87]
	v_mfma_f32_16x16x32_bf16 v[80:83], v[158:161], v[190:193], v[80:83]
	v_mfma_f32_16x16x32_bf16 v[76:79], v[128:131], v[198:201], v[76:79]
	v_mfma_f32_16x16x32_bf16 v[72:75], v[158:161], v[198:201], v[72:75]
	v_mfma_f32_16x16x32_bf16 v[68:71], v[128:131], v[218:221], v[68:71]
	v_mfma_f32_16x16x32_bf16 v[64:67], v[158:161], v[218:221], v[64:67]
	v_mfma_f32_16x16x32_bf16 v[92:95], v[132:135], v[186:189], v[92:95]
	v_mfma_f32_16x16x32_bf16 v[88:91], v[162:165], v[186:189], v[88:91]
	v_mfma_f32_16x16x32_bf16 v[84:87], v[132:135], v[194:197], v[84:87]
	v_mfma_f32_16x16x32_bf16 v[80:83], v[162:165], v[194:197], v[80:83]
	v_mfma_f32_16x16x32_bf16 v[76:79], v[132:135], v[202:205], v[76:79]
	v_mfma_f32_16x16x32_bf16 v[72:75], v[162:165], v[202:205], v[72:75]
	v_mfma_f32_16x16x32_bf16 v[68:71], v[132:135], v[222:225], v[68:71]
	v_mfma_f32_16x16x32_bf16 v[64:67], v[162:165], v[222:225], v[64:67]
	s_setprio 0
	s_setprio 1
	v_mfma_f32_16x16x32_bf16 v[28:31], v[166:169], v[182:185], v[28:31]
	v_mfma_f32_16x16x32_bf16 v[24:27], v[174:177], v[182:185], v[24:27]
	v_mfma_f32_16x16x32_bf16 v[20:23], v[166:169], v[190:193], v[20:23]
	v_mfma_f32_16x16x32_bf16 v[16:19], v[174:177], v[190:193], v[16:19]
	v_mfma_f32_16x16x32_bf16 v[12:15], v[166:169], v[198:201], v[12:15]
	v_mfma_f32_16x16x32_bf16 v[8:11], v[174:177], v[198:201], v[8:11]
	v_mfma_f32_16x16x32_bf16 v[4:7], v[166:169], v[218:221], v[4:7]
	v_mfma_f32_16x16x32_bf16 v[0:3], v[174:177], v[218:221], v[0:3]
	v_mfma_f32_16x16x32_bf16 v[28:31], v[170:173], v[186:189], v[28:31]
	v_mfma_f32_16x16x32_bf16 v[24:27], v[178:181], v[186:189], v[24:27]
	v_mfma_f32_16x16x32_bf16 v[20:23], v[170:173], v[194:197], v[20:23]
	v_mfma_f32_16x16x32_bf16 v[16:19], v[178:181], v[194:197], v[16:19]
	v_mfma_f32_16x16x32_bf16 v[12:15], v[170:173], v[202:205], v[12:15]
	v_mfma_f32_16x16x32_bf16 v[8:11], v[178:181], v[202:205], v[8:11]
	s_setprio 2
	s_barrier
	v_mfma_f32_16x16x32_bf16 v[4:7], v[170:173], v[222:225], v[4:7]
	v_mfma_f32_16x16x32_bf16 v[0:3], v[178:181], v[222:225], v[0:3]
	s_setprio 0
	s_add_i32 s56, 0, 0x18000
	s_add_i32 s57, 0, 0x1c000
	v_add_u32_e32 v162, s56, v212
	v_add_u32_e32 v178, s57, v212
	ds_read_b128 v[128:131], v162
	ds_read_b128 v[132:135], v162 offset:1024
	ds_read_b128 v[158:161], v162 offset:2048
	ds_read_b128 v[162:165], v162 offset:3072
	ds_read_b128 v[166:169], v178
	ds_read_b128 v[170:173], v178 offset:1024
	ds_read_b128 v[174:177], v178 offset:2048
	ds_read_b128 v[178:181], v178 offset:3072
	s_add_u32 s52, s78, 0x200000
	s_addc_u32 s53, s79, 0
	s_mov_b32 m0, s85
	v_lshl_add_u64 v[234:235], s[52:53], 0, v[136:137]
	ds_read_b128 v[182:185], v216 offset:32768
	ds_read_b128 v[186:189], v216 offset:33792
	ds_read_b128 v[190:193], v216 offset:34816
	ds_read_b128 v[194:197], v216 offset:35840
	ds_read_b128 v[198:201], v216 offset:36864
	ds_read_b128 v[202:205], v216 offset:37888
	ds_read_b128 v[218:221], v216 offset:38912
	ds_read_b128 v[222:225], v216 offset:39936
	global_load_lds_dwordx4 v[234:235], off
	s_mov_b32 m0, s86
	v_lshl_add_u64 v[234:235], s[52:53], 0, v[140:141]
	global_load_lds_dwordx4 v[234:235], off
	s_waitcnt vmcnt(8)
	s_waitcnt lgkmcnt(0)
	s_setprio 1
	s_barrier
	v_mfma_f32_16x16x32_bf16 v[124:127], v[128:131], v[182:185], v[124:127]
	v_mfma_f32_16x16x32_bf16 v[120:123], v[158:161], v[182:185], v[120:123]
	v_mfma_f32_16x16x32_bf16 v[116:119], v[128:131], v[190:193], v[116:119]
	v_mfma_f32_16x16x32_bf16 v[112:115], v[158:161], v[190:193], v[112:115]
	v_mfma_f32_16x16x32_bf16 v[108:111], v[128:131], v[198:201], v[108:111]
	v_mfma_f32_16x16x32_bf16 v[104:107], v[158:161], v[198:201], v[104:107]
	v_mfma_f32_16x16x32_bf16 v[100:103], v[128:131], v[218:221], v[100:103]
	v_mfma_f32_16x16x32_bf16 v[96:99], v[158:161], v[218:221], v[96:99]
	v_mfma_f32_16x16x32_bf16 v[124:127], v[132:135], v[186:189], v[124:127]
	v_mfma_f32_16x16x32_bf16 v[120:123], v[162:165], v[186:189], v[120:123]
	v_mfma_f32_16x16x32_bf16 v[116:119], v[132:135], v[194:197], v[116:119]
	v_mfma_f32_16x16x32_bf16 v[112:115], v[162:165], v[194:197], v[112:115]
	v_mfma_f32_16x16x32_bf16 v[108:111], v[132:135], v[202:205], v[108:111]
	v_mfma_f32_16x16x32_bf16 v[104:107], v[162:165], v[202:205], v[104:107]
	v_mfma_f32_16x16x32_bf16 v[100:103], v[132:135], v[222:225], v[100:103]
	v_mfma_f32_16x16x32_bf16 v[96:99], v[162:165], v[222:225], v[96:99]
	s_setprio 0
	s_setprio 1
	v_mfma_f32_16x16x32_bf16 v[60:63], v[166:169], v[182:185], v[60:63]
	v_mfma_f32_16x16x32_bf16 v[56:59], v[174:177], v[182:185], v[56:59]
	v_mfma_f32_16x16x32_bf16 v[52:55], v[166:169], v[190:193], v[52:55]
	v_mfma_f32_16x16x32_bf16 v[48:51], v[174:177], v[190:193], v[48:51]
	v_mfma_f32_16x16x32_bf16 v[44:47], v[166:169], v[198:201], v[44:47]
	v_mfma_f32_16x16x32_bf16 v[40:43], v[174:177], v[198:201], v[40:43]
	v_mfma_f32_16x16x32_bf16 v[36:39], v[166:169], v[218:221], v[36:39]
	v_mfma_f32_16x16x32_bf16 v[32:35], v[174:177], v[218:221], v[32:35]
	v_mfma_f32_16x16x32_bf16 v[60:63], v[170:173], v[186:189], v[60:63]
	v_mfma_f32_16x16x32_bf16 v[56:59], v[178:181], v[186:189], v[56:59]
	v_mfma_f32_16x16x32_bf16 v[52:55], v[170:173], v[194:197], v[52:55]
	v_mfma_f32_16x16x32_bf16 v[48:51], v[178:181], v[194:197], v[48:51]
	v_mfma_f32_16x16x32_bf16 v[44:47], v[170:173], v[202:205], v[44:47]
	v_mfma_f32_16x16x32_bf16 v[40:43], v[178:181], v[202:205], v[40:43]
	s_setprio 2
	s_barrier
; #define PG8_STAGE(bufoff, gbase, voff) do { _Pragma("unroll") for (int _i = 0; _i < 2; ++_i) \
;         __builtin_amdgcn_global_load_lds((const unsigned*)((const char*)(gbase) + (voff)[_i]), (PG8_LAS unsigned*)(lds + (bufoff) + ldsw + _i * 8192), 16, 0, 0); } while (0)
; #define PG8_LDA(dst, b, h) do { _Pragma("unroll") for (int m = 0; m < 4; ++m) _Pragma("unroll") for (int k = 0; k < 2; ++k) dst[m][k] = *(const PG8_LAS bf16x8*)(lds + PG8_SA(b, h) + aoff + m * 2048 + k * 1024); } while (0)
; #define PG8_MMA(ai, bj, At, Bt) do { __builtin_amdgcn_s_setprio(1); _Pragma("unroll") for (int m = 0; m < 4; ++m) _Pragma("unroll") for (int n = 0; n < 2; ++n) _Pragma("unroll") for (int k = 0; k < 2; ++k) \
;         acc[ai][bj][m][n] = __builtin_amdgcn_mfma_f32_16x16x32_bf16(Bt[n][k], At[m][k], acc[ai][bj][m][n], 0, 0, 0); __builtin_amdgcn_s_setprio(0); } while (0)
; #define PG8_WAIT_V(n) asm volatile("s_waitcnt vmcnt(" #n ")" ::: "memory")
; #define PG8_WAIT_L(n) asm volatile("s_waitcnt lgkmcnt(" #n ")" ::: "memory")
; #define PG8_BAR __builtin_amdgcn_s_barrier()
; #define PG8_SCHED __builtin_amdgcn_sched_barrier(0)
; template <class Epi, class Sched, bool ALIGN_EPI = false, bool SP2 = false>
; __device__ __forceinline__ void gemm_phase(PG8_LAS unsigned char* lds, const Gemm g, const Sched& S, const Epi& E) {
;     ...
;             PG8_WAIT_V(8); PG8_WAIT_L(0); PG8_BAR; PG8_MMA(0, 0, At, B0); PG8_MMA(0, 1, At, B1); PG8_BAR; PG8_SCHED;
;             PG8_LDA(At, 1, 1); PG8_STAGE(PG8_SB(1, 0), b3, voffB); PG8_STAGE(PG8_SB(1, 1), b3 + hstep, voffB); PG8_STAGE(PG8_SA(1, 0), a3, voffA);
;             PG8_WAIT_V(8); PG8_WAIT_L(0); PG8_BAR; PG8_MMA(1, 0, At, B0); PG8_MMA(1, 1, At, B1); PG8_BAR; PG8_SCHED;
;     ...
;         if constexpr (ALIGN_EPI) { if (wr == 0) PG8_BAR; }
	v_mfma_f32_16x16x32_bf16 v[36:39], v[170:173], v[222:225], v[36:39]
	v_mfma_f32_16x16x32_bf16 v[32:35], v[178:181], v[222:225], v[32:35]
	s_setprio 0
	s_add_i32 s52, s56, s82
	v_lshl_add_u64 v[226:227], v[226:227], 0, s[36:37]
	s_mov_b32 m0, s52
	ds_read_b128 v[182:185], v216 offset:49152
	ds_read_b128 v[186:189], v216 offset:50176
	ds_read_b128 v[190:193], v216 offset:51200
	ds_read_b128 v[194:197], v216 offset:52224
	ds_read_b128 v[198:201], v216 offset:53248
	ds_read_b128 v[202:205], v216 offset:54272
	ds_read_b128 v[218:221], v216 offset:55296
	ds_read_b128 v[222:225], v216 offset:56320
	global_load_lds_dwordx4 v[226:227], off
	s_add_i32 m0, s52, 0x2000
	s_add_u32 s52, s76, 0x200080
	v_lshl_add_u64 v[226:227], v[228:229], 0, s[36:37]
	s_addc_u32 s53, s77, 0
	s_add_i32 s56, s57, s82
	global_load_lds_dwordx4 v[226:227], off
	s_mov_b32 m0, s56
	v_lshl_add_u64 v[226:227], s[52:53], 0, v[138:139]
	global_load_lds_dwordx4 v[226:227], off
	s_add_i32 m0, s56, 0x2000
	v_lshl_add_u64 v[226:227], s[52:53], 0, v[142:143]
	global_load_lds_dwordx4 v[226:227], off
	s_mov_b32 m0, s94
	v_lshl_add_u64 v[226:227], v[230:231], 0, s[36:37]
	global_load_lds_dwordx4 v[226:227], off
	s_mov_b32 m0, s95
	v_lshl_add_u64 v[226:227], v[232:233], 0, s[36:37]
	global_load_lds_dwordx4 v[226:227], off
	s_waitcnt vmcnt(8)
	s_waitcnt lgkmcnt(0)
	s_setprio 1
	s_barrier
	v_mfma_f32_16x16x32_bf16 v[92:95], v[128:131], v[182:185], v[92:95]
	v_mfma_f32_16x16x32_bf16 v[88:91], v[158:161], v[182:185], v[88:91]
	v_mfma_f32_16x16x32_bf16 v[84:87], v[128:131], v[190:193], v[84:87]
	v_mfma_f32_16x16x32_bf16 v[80:83], v[158:161], v[190:193], v[80:83]
	v_mfma_f32_16x16x32_bf16 v[76:79], v[128:131], v[198:201], v[76:79]
	v_mfma_f32_16x16x32_bf16 v[72:75], v[158:161], v[198:201], v[72:75]
	v_mfma_f32_16x16x32_bf16 v[68:71], v[128:131], v[218:221], v[68:71]
	v_mfma_f32_16x16x32_bf16 v[64:67], v[158:161], v[218:221], v[64:67]
	v_mfma_f32_16x16x32_bf16 v[92:95], v[132:135], v[186:189], v[92:95]
	v_mfma_f32_16x16x32_bf16 v[88:91], v[162:165], v[186:189], v[88:91]
	v_mfma_f32_16x16x32_bf16 v[84:87], v[132:135], v[194:197], v[84:87]
	v_mfma_f32_16x16x32_bf16 v[80:83], v[162:165], v[194:197], v[80:83]
	v_mfma_f32_16x16x32_bf16 v[76:79], v[132:135], v[202:205], v[76:79]
	v_mfma_f32_16x16x32_bf16 v[72:75], v[162:165], v[202:205], v[72:75]
	v_mfma_f32_16x16x32_bf16 v[68:71], v[132:135], v[222:225], v[68:71]
	v_mfma_f32_16x16x32_bf16 v[64:67], v[162:165], v[222:225], v[64:67]
	s_setprio 0
	s_setprio 1
	v_mfma_f32_16x16x32_bf16 v[28:31], v[166:169], v[182:185], v[28:31]
	v_mfma_f32_16x16x32_bf16 v[24:27], v[174:177], v[182:185], v[24:27]
	v_mfma_f32_16x16x32_bf16 v[20:23], v[166:169], v[190:193], v[20:23]
	v_mfma_f32_16x16x32_bf16 v[16:19], v[174:177], v[190:193], v[16:19]
	v_mfma_f32_16x16x32_bf16 v[12:15], v[166:169], v[198:201], v[12:15]
	v_mfma_f32_16x16x32_bf16 v[8:11], v[174:177], v[198:201], v[8:11]
	v_mfma_f32_16x16x32_bf16 v[4:7], v[166:169], v[218:221], v[4:7]
	v_mfma_f32_16x16x32_bf16 v[0:3], v[174:177], v[218:221], v[0:3]
	v_mfma_f32_16x16x32_bf16 v[28:31], v[170:173], v[186:189], v[28:31]
	v_mfma_f32_16x16x32_bf16 v[24:27], v[178:181], v[186:189], v[24:27]
	v_mfma_f32_16x16x32_bf16 v[20:23], v[170:173], v[194:197], v[20:23]
	v_mfma_f32_16x16x32_bf16 v[16:19], v[178:181], v[194:197], v[16:19]
	v_mfma_f32_16x16x32_bf16 v[12:15], v[170:173], v[202:205], v[12:15]
	v_mfma_f32_16x16x32_bf16 v[8:11], v[178:181], v[202:205], v[8:11]
	s_setprio 2
	s_barrier
	v_mfma_f32_16x16x32_bf16 v[4:7], v[170:173], v[222:225], v[4:7]
	v_mfma_f32_16x16x32_bf16 v[0:3], v[178:181], v[222:225], v[0:3]
	s_setprio 0
	s_add_i32 vcc_hi, vcc_hi, 2
	s_add_u32 s74, s74, 0x100
	s_addc_u32 s75, s75, 0
	s_add_u32 s93, s93, 0x100
	s_addc_u32 vcc_lo, vcc_lo, 0
	s_cmpk_gt_u32 vcc_hi, 0x7d
	s_cbranch_scc0 .LBB0_624
	s_and_b64 vcc, exec, s[40:41]
	s_cbranch_vccz .LBB0_627
	s_barrier

; #define PG8_STAGE(bufoff, gbase, voff) do { _Pragma("unroll") for (int _i = 0; _i < 2; ++_i) \
;         __builtin_amdgcn_global_load_lds((const unsigned*)((const char*)(gbase) + (voff)[_i]), (PG8_LAS unsigned*)(lds + (bufoff) + ldsw + _i * 8192), 16, 0, 0); } while (0)
; #define PG8_LDA(dst, b, h) do { _Pragma("unroll") for (int m = 0; m < 4; ++m) _Pragma("unroll") for (int k = 0; k < 2; ++k) dst[m][k] = *(const PG8_LAS bf16x8*)(lds + PG8_SA(b, h) + aoff + m * 2048 + k * 1024); } while (0)
; #define PG8_LDB(dst, b, h) do { _Pragma("unroll") for (int n = 0; n < 2; ++n) _Pragma("unroll") for (int k = 0; k < 2; ++k) dst[n][k] = *(const PG8_LAS bf16x8*)(lds + PG8_SB(b, h) + boff + n * 2048 + k * 1024); } while (0)
; #define PG8_MMA(ai, bj, At, Bt) do { __builtin_amdgcn_s_setprio(1); _Pragma("unroll") for (int m = 0; m < 4; ++m) _Pragma("unroll") for (int n = 0; n < 2; ++n) _Pragma("unroll") for (int k = 0; k < 2; ++k) \
;         acc[ai][bj][m][n] = __builtin_amdgcn_mfma_f32_16x16x32_bf16(Bt[n][k], At[m][k], acc[ai][bj][m][n], 0, 0, 0); __builtin_amdgcn_s_setprio(0); } while (0)
; #define PG8_WAIT_V(n) asm volatile("s_waitcnt vmcnt(" #n ")" ::: "memory")
; #define PG8_WAIT_L(n) asm volatile("s_waitcnt lgkmcnt(" #n ")" ::: "memory")
; #define PG8_BAR __builtin_amdgcn_s_barrier()
; template <class Epi, class Sched, bool ALIGN_EPI = false, bool SP2 = false>
; __device__ __forceinline__ void gemm_phase(PG8_LAS unsigned char* lds, const Gemm g, const Sched& S, const Epi& E) {
;     ...
;             const bool last = (t == nt - 2);
;             const char* a1 = cA + (size_t)(t + 1) * kstep;
;             const char* a2 = last ? nA : cA + (size_t)(t + 2) * kstep; const char* b2 = last ? nB : cB + (size_t)(t + 2) * kstep;
;             const char* a3 = a2 + kstep; const char* b3 = b2 + kstep;
;             if constexpr (SP2) {
;             PG8_LDB(B0, 0, 0); PG8_LDB(B1, 0, 1); PG8_SCHED; PG8_LDA(At, 0, 0); PG8_STAGE(PG8_SA(1, 1), a1 + hstep, voffA);
;             PG8_WAIT_V(8); PG8_WAIT_L(0); PG8_BAR; PG8_MMA(0, 0, At, B0); PG8_MMA(0, 1, At, B1); PG8_BAR; PG8_SCHED;
;             PG8_LDA(At, 0, 1); PG8_STAGE(PG8_SB(0, 0), b2, voffB); PG8_STAGE(PG8_SB(0, 1), b2 + hstep, voffB); PG8_STAGE(PG8_SA(0, 0), a2, voffA);
;             PG8_WAIT_V(8); PG8_WAIT_L(0); PG8_BAR; PG8_MMA(1, 0, At, B0); PG8_MMA(1, 1, At, B1); PG8_BAR; PG8_SCHED;
.LBB0_660:
	ds_read_b128 v[166:169], v145
	ds_read_b128 v[170:173], v145 offset:1024
	ds_read_b128 v[174:177], v145 offset:2048
	ds_read_b128 v[178:181], v145 offset:3072
	ds_read_b128 v[182:185], v149
	ds_read_b128 v[186:189], v149 offset:1024
	ds_read_b128 v[190:193], v149 offset:2048
	ds_read_b128 v[194:197], v149 offset:3072
	s_add_u32 s52, s72, 0xffe00080
	s_addc_u32 s53, s73, -1
	s_cmp_eq_u32 s49, 28
	s_cselect_b32 s77, s51, s53
	s_cselect_b32 s76, s50, s52
	s_cselect_b32 s75, s55, s41
	s_cselect_b32 s74, s54, s37
	s_mov_b32 m0, s82
	v_lshl_add_u64 v[230:231], s[72:73], 0, v[160:161]
	ds_read_b128 v[198:201], v164
	ds_read_b128 v[202:205], v164 offset:1024
	ds_read_b128 v[206:209], v164 offset:2048
	ds_read_b128 v[210:213], v164 offset:3072
	ds_read_b128 v[214:217], v164 offset:4096
	ds_read_b128 v[218:221], v164 offset:5120
	ds_read_b128 v[222:225], v164 offset:6144
	ds_read_b128 v[226:229], v164 offset:7168
	global_load_lds_dwordx4 v[230:231], off
	s_mov_b32 m0, s83
	v_lshl_add_u64 v[230:231], s[72:73], 0, v[162:163]
	global_load_lds_dwordx4 v[230:231], off
	s_waitcnt vmcnt(8)
	s_waitcnt lgkmcnt(0)
	s_setprio 1
	s_barrier
	v_mfma_f32_16x16x32_bf16 v[124:127], v[166:169], v[198:201], v[124:127]
	v_mfma_f32_16x16x32_bf16 v[120:123], v[174:177], v[198:201], v[120:123]
	v_mfma_f32_16x16x32_bf16 v[116:119], v[166:169], v[206:209], v[116:119]
	v_mfma_f32_16x16x32_bf16 v[108:111], v[174:177], v[206:209], v[108:111]
	v_mfma_f32_16x16x32_bf16 v[100:103], v[166:169], v[214:217], v[100:103]
	v_mfma_f32_16x16x32_bf16 v[92:95], v[174:177], v[214:217], v[92:95]
	v_mfma_f32_16x16x32_bf16 v[84:87], v[166:169], v[222:225], v[84:87]
	v_mfma_f32_16x16x32_bf16 v[76:79], v[174:177], v[222:225], v[76:79]
	v_mfma_f32_16x16x32_bf16 v[124:127], v[170:173], v[202:205], v[124:127]
	v_mfma_f32_16x16x32_bf16 v[120:123], v[178:181], v[202:205], v[120:123]
	v_mfma_f32_16x16x32_bf16 v[116:119], v[170:173], v[210:213], v[116:119]
	v_mfma_f32_16x16x32_bf16 v[108:111], v[178:181], v[210:213], v[108:111]
	v_mfma_f32_16x16x32_bf16 v[100:103], v[170:173], v[218:221], v[100:103]
	v_mfma_f32_16x16x32_bf16 v[92:95], v[178:181], v[218:221], v[92:95]
	v_mfma_f32_16x16x32_bf16 v[84:87], v[170:173], v[226:229], v[84:87]
	v_mfma_f32_16x16x32_bf16 v[76:79], v[178:181], v[226:229], v[76:79]
	s_setprio 0
	s_setprio 1
	v_mfma_f32_16x16x32_bf16 v[112:115], v[182:185], v[198:201], v[112:115]
	v_mfma_f32_16x16x32_bf16 v[104:107], v[190:193], v[198:201], v[104:107]
	v_mfma_f32_16x16x32_bf16 v[96:99], v[182:185], v[206:209], v[96:99]
	v_mfma_f32_16x16x32_bf16 v[88:91], v[190:193], v[206:209], v[88:91]
	v_mfma_f32_16x16x32_bf16 v[80:83], v[182:185], v[214:217], v[80:83]
	v_mfma_f32_16x16x32_bf16 v[72:75], v[190:193], v[214:217], v[72:75]
	v_mfma_f32_16x16x32_bf16 v[68:71], v[182:185], v[222:225], v[68:71]
	v_mfma_f32_16x16x32_bf16 v[64:67], v[190:193], v[222:225], v[64:67]
	v_mfma_f32_16x16x32_bf16 v[112:115], v[186:189], v[202:205], v[112:115]
	v_mfma_f32_16x16x32_bf16 v[104:107], v[194:197], v[202:205], v[104:107]
	v_mfma_f32_16x16x32_bf16 v[96:99], v[186:189], v[210:213], v[96:99]
	v_mfma_f32_16x16x32_bf16 v[88:91], v[194:197], v[210:213], v[88:91]
	v_mfma_f32_16x16x32_bf16 v[80:83], v[186:189], v[218:221], v[80:83]
	v_mfma_f32_16x16x32_bf16 v[72:75], v[194:197], v[218:221], v[72:75]
	s_setprio 2
	s_barrier
	v_mfma_f32_16x16x32_bf16 v[68:71], v[186:189], v[226:229], v[68:71]
	v_mfma_f32_16x16x32_bf16 v[64:67], v[194:197], v[226:229], v[64:67]
	s_setprio 0
	s_mov_b32 m0, s84
	v_lshl_add_u64 v[230:231], s[74:75], 0, v[138:139]
	s_add_u32 s52, s74, 0x200000
	ds_read_b128 v[198:201], v164 offset:16384
	ds_read_b128 v[202:205], v164 offset:17408
	ds_read_b128 v[206:209], v164 offset:18432
	ds_read_b128 v[210:213], v164 offset:19456
	ds_read_b128 v[214:217], v164 offset:20480
	ds_read_b128 v[218:221], v164 offset:21504
	ds_read_b128 v[222:225], v164 offset:22528
	ds_read_b128 v[226:229], v164 offset:23552
	global_load_lds_dwordx4 v[230:231], off
	v_lshl_add_u64 v[232:233], s[74:75], 0, v[142:143]
	s_mov_b32 m0, s85
	s_addc_u32 s53, s75, 0
	global_load_lds_dwordx4 v[232:233], off
	v_lshl_add_u64 v[234:235], s[52:53], 0, v[138:139]
	s_mov_b32 m0, s86
	v_lshl_add_u64 v[236:237], s[76:77], 0, v[140:141]
	global_load_lds_dwordx4 v[234:235], off
	s_mov_b32 m0, s87
	v_lshl_add_u64 v[234:235], s[52:53], 0, v[142:143]
	global_load_lds_dwordx4 v[234:235], off
	s_mov_b32 m0, s28
	v_lshl_add_u64 v[234:235], s[76:77], 0, v[136:137]
	global_load_lds_dwordx4 v[234:235], off
	s_mov_b32 m0, s29
	s_nop 0
	global_load_lds_dwordx4 v[236:237], off
	s_waitcnt vmcnt(8)
	s_waitcnt lgkmcnt(0)
	s_setprio 1
	s_barrier
; #define PG8_STAGE(bufoff, gbase, voff) do { _Pragma("unroll") for (int _i = 0; _i < 2; ++_i) \
;         __builtin_amdgcn_global_load_lds((const unsigned*)((const char*)(gbase) + (voff)[_i]), (PG8_LAS unsigned*)(lds + (bufoff) + ldsw + _i * 8192), 16, 0, 0); } while (0)
; #define PG8_LDA(dst, b, h) do { _Pragma("unroll") for (int m = 0; m < 4; ++m) _Pragma("unroll") for (int k = 0; k < 2; ++k) dst[m][k] = *(const PG8_LAS bf16x8*)(lds + PG8_SA(b, h) + aoff + m * 2048 + k * 1024); } while (0)
; #define PG8_LDB(dst, b, h) do { _Pragma("unroll") for (int n = 0; n < 2; ++n) _Pragma("unroll") for (int k = 0; k < 2; ++k) dst[n][k] = *(const PG8_LAS bf16x8*)(lds + PG8_SB(b, h) + boff + n * 2048 + k * 1024); } while (0)
; #define PG8_MMA(ai, bj, At, Bt) do { __builtin_amdgcn_s_setprio(1); _Pragma("unroll") for (int m = 0; m < 4; ++m) _Pragma("unroll") for (int n = 0; n < 2; ++n) _Pragma("unroll") for (int k = 0; k < 2; ++k) \
;         acc[ai][bj][m][n] = __builtin_amdgcn_mfma_f32_16x16x32_bf16(Bt[n][k], At[m][k], acc[ai][bj][m][n], 0, 0, 0); __builtin_amdgcn_s_setprio(0); } while (0)
; #define PG8_WAIT_V(n) asm volatile("s_waitcnt vmcnt(" #n ")" ::: "memory")
; #define PG8_WAIT_L(n) asm volatile("s_waitcnt lgkmcnt(" #n ")" ::: "memory")
; #define PG8_BAR __builtin_amdgcn_s_barrier()
; #define PG8_SCHED __builtin_amdgcn_sched_barrier(0)
; template <class Epi, class Sched, bool ALIGN_EPI = false, bool SP2 = false>
; __device__ __forceinline__ void gemm_phase(PG8_LAS unsigned char* lds, const Gemm g, const Sched& S, const Epi& E) {
;     ...
;             PG8_WAIT_V(8); PG8_WAIT_L(0); PG8_BAR; PG8_MMA(1, 0, At, B0); PG8_MMA(1, 1, At, B1); PG8_BAR; PG8_SCHED;
;             PG8_LDB(B0, 1, 0); PG8_LDB(B1, 1, 1); PG8_SCHED; PG8_LDA(At, 1, 0); PG8_STAGE(PG8_SA(0, 1), a2 + hstep, voffA);
;             PG8_WAIT_V(8); PG8_WAIT_L(0); PG8_BAR; PG8_MMA(0, 0, At, B0); PG8_MMA(0, 1, At, B1); PG8_BAR; PG8_SCHED;
	v_mfma_f32_16x16x32_bf16 v[60:63], v[166:169], v[198:201], v[60:63]
	v_mfma_f32_16x16x32_bf16 v[56:59], v[174:177], v[198:201], v[56:59]
	v_mfma_f32_16x16x32_bf16 v[52:55], v[166:169], v[206:209], v[52:55]
	v_mfma_f32_16x16x32_bf16 v[44:47], v[174:177], v[206:209], v[44:47]
	v_mfma_f32_16x16x32_bf16 v[36:39], v[166:169], v[214:217], v[36:39]
	v_mfma_f32_16x16x32_bf16 v[28:31], v[174:177], v[214:217], v[28:31]
	v_mfma_f32_16x16x32_bf16 v[20:23], v[166:169], v[222:225], v[20:23]
	v_mfma_f32_16x16x32_bf16 v[12:15], v[174:177], v[222:225], v[12:15]
	v_mfma_f32_16x16x32_bf16 v[60:63], v[170:173], v[202:205], v[60:63]
	v_mfma_f32_16x16x32_bf16 v[56:59], v[178:181], v[202:205], v[56:59]
	v_mfma_f32_16x16x32_bf16 v[52:55], v[170:173], v[210:213], v[52:55]
	v_mfma_f32_16x16x32_bf16 v[44:47], v[178:181], v[210:213], v[44:47]
	v_mfma_f32_16x16x32_bf16 v[36:39], v[170:173], v[218:221], v[36:39]
	v_mfma_f32_16x16x32_bf16 v[28:31], v[178:181], v[218:221], v[28:31]
	v_mfma_f32_16x16x32_bf16 v[20:23], v[170:173], v[226:229], v[20:23]
	v_mfma_f32_16x16x32_bf16 v[12:15], v[178:181], v[226:229], v[12:15]
	s_setprio 0
	s_setprio 1
	v_mfma_f32_16x16x32_bf16 v[48:51], v[182:185], v[198:201], v[48:51]
	v_mfma_f32_16x16x32_bf16 v[40:43], v[190:193], v[198:201], v[40:43]
	v_mfma_f32_16x16x32_bf16 v[32:35], v[182:185], v[206:209], v[32:35]
	v_mfma_f32_16x16x32_bf16 v[24:27], v[190:193], v[206:209], v[24:27]
	v_mfma_f32_16x16x32_bf16 v[16:19], v[182:185], v[214:217], v[16:19]
	v_mfma_f32_16x16x32_bf16 v[8:11], v[190:193], v[214:217], v[8:11]
	v_mfma_f32_16x16x32_bf16 v[4:7], v[182:185], v[222:225], v[4:7]
	v_mfma_f32_16x16x32_bf16 v[0:3], v[190:193], v[222:225], v[0:3]
	v_mfma_f32_16x16x32_bf16 v[48:51], v[186:189], v[202:205], v[48:51]
	v_mfma_f32_16x16x32_bf16 v[40:43], v[194:197], v[202:205], v[40:43]
	v_mfma_f32_16x16x32_bf16 v[32:35], v[186:189], v[210:213], v[32:35]
	v_mfma_f32_16x16x32_bf16 v[24:27], v[194:197], v[210:213], v[24:27]
	v_mfma_f32_16x16x32_bf16 v[16:19], v[186:189], v[218:221], v[16:19]
	v_mfma_f32_16x16x32_bf16 v[8:11], v[194:197], v[218:221], v[8:11]
	s_setprio 2
	s_barrier
	v_mfma_f32_16x16x32_bf16 v[4:7], v[186:189], v[226:229], v[4:7]
	v_mfma_f32_16x16x32_bf16 v[0:3], v[194:197], v[226:229], v[0:3]
	s_setprio 0
	ds_read_b128 v[166:169], v148
	ds_read_b128 v[170:173], v148 offset:1024
	ds_read_b128 v[174:177], v148 offset:2048
	ds_read_b128 v[178:181], v148 offset:3072
	ds_read_b128 v[182:185], v165
	ds_read_b128 v[186:189], v165 offset:1024
	ds_read_b128 v[190:193], v165 offset:2048
	ds_read_b128 v[194:197], v165 offset:3072
	s_add_u32 s52, s76, 0x200000
	s_addc_u32 s53, s77, 0
	s_mov_b32 m0, s33
	v_lshl_add_u64 v[238:239], s[52:53], 0, v[136:137]
	ds_read_b128 v[198:201], v164 offset:32768
	ds_read_b128 v[202:205], v164 offset:33792
	ds_read_b128 v[206:209], v164 offset:34816
	ds_read_b128 v[210:213], v164 offset:35840
	ds_read_b128 v[214:217], v164 offset:36864
	ds_read_b128 v[218:221], v164 offset:37888
	ds_read_b128 v[222:225], v164 offset:38912
	ds_read_b128 v[226:229], v164 offset:39936
	global_load_lds_dwordx4 v[238:239], off
	s_mov_b32 m0, s38
	v_lshl_add_u64 v[238:239], s[52:53], 0, v[140:141]
	global_load_lds_dwordx4 v[238:239], off
	s_waitcnt vmcnt(8)
	s_waitcnt lgkmcnt(0)
	s_setprio 1
	s_barrier
	v_mfma_f32_16x16x32_bf16 v[124:127], v[166:169], v[198:201], v[124:127]
	v_mfma_f32_16x16x32_bf16 v[120:123], v[174:177], v[198:201], v[120:123]
	v_mfma_f32_16x16x32_bf16 v[116:119], v[166:169], v[206:209], v[116:119]
	v_mfma_f32_16x16x32_bf16 v[108:111], v[174:177], v[206:209], v[108:111]
	v_mfma_f32_16x16x32_bf16 v[100:103], v[166:169], v[214:217], v[100:103]
	v_mfma_f32_16x16x32_bf16 v[92:95], v[174:177], v[214:217], v[92:95]
	v_mfma_f32_16x16x32_bf16 v[84:87], v[166:169], v[222:225], v[84:87]
	v_mfma_f32_16x16x32_bf16 v[76:79], v[174:177], v[222:225], v[76:79]
	v_mfma_f32_16x16x32_bf16 v[124:127], v[170:173], v[202:205], v[124:127]
	v_mfma_f32_16x16x32_bf16 v[120:123], v[178:181], v[202:205], v[120:123]
	v_mfma_f32_16x16x32_bf16 v[116:119], v[170:173], v[210:213], v[116:119]
	v_mfma_f32_16x16x32_bf16 v[108:111], v[178:181], v[210:213], v[108:111]
	v_mfma_f32_16x16x32_bf16 v[100:103], v[170:173], v[218:221], v[100:103]
	v_mfma_f32_16x16x32_bf16 v[92:95], v[178:181], v[218:221], v[92:95]
	v_mfma_f32_16x16x32_bf16 v[84:87], v[170:173], v[226:229], v[84:87]
	v_mfma_f32_16x16x32_bf16 v[76:79], v[178:181], v[226:229], v[76:79]
	s_setprio 0
	s_setprio 1
	v_mfma_f32_16x16x32_bf16 v[112:115], v[182:185], v[198:201], v[112:115]
	v_mfma_f32_16x16x32_bf16 v[104:107], v[190:193], v[198:201], v[104:107]
	v_mfma_f32_16x16x32_bf16 v[96:99], v[182:185], v[206:209], v[96:99]
	v_mfma_f32_16x16x32_bf16 v[88:91], v[190:193], v[206:209], v[88:91]
	v_mfma_f32_16x16x32_bf16 v[80:83], v[182:185], v[214:217], v[80:83]
	v_mfma_f32_16x16x32_bf16 v[72:75], v[190:193], v[214:217], v[72:75]
	v_mfma_f32_16x16x32_bf16 v[68:71], v[182:185], v[222:225], v[68:71]
	v_mfma_f32_16x16x32_bf16 v[64:67], v[190:193], v[222:225], v[64:67]
	v_mfma_f32_16x16x32_bf16 v[112:115], v[186:189], v[202:205], v[112:115]
	v_mfma_f32_16x16x32_bf16 v[104:107], v[194:197], v[202:205], v[104:107]
	v_mfma_f32_16x16x32_bf16 v[96:99], v[186:189], v[210:213], v[96:99]
	v_mfma_f32_16x16x32_bf16 v[88:91], v[194:197], v[210:213], v[88:91]
	v_mfma_f32_16x16x32_bf16 v[80:83], v[186:189], v[218:221], v[80:83]
	v_mfma_f32_16x16x32_bf16 v[72:75], v[194:197], v[218:221], v[72:75]
	s_setprio 2
	s_barrier
; #define PG8_STAGE(bufoff, gbase, voff) do { _Pragma("unroll") for (int _i = 0; _i < 2; ++_i) \
;         __builtin_amdgcn_global_load_lds((const unsigned*)((const char*)(gbase) + (voff)[_i]), (PG8_LAS unsigned*)(lds + (bufoff) + ldsw + _i * 8192), 16, 0, 0); } while (0)
; #define PG8_LDA(dst, b, h) do { _Pragma("unroll") for (int m = 0; m < 4; ++m) _Pragma("unroll") for (int k = 0; k < 2; ++k) dst[m][k] = *(const PG8_LAS bf16x8*)(lds + PG8_SA(b, h) + aoff + m * 2048 + k * 1024); } while (0)
; #define PG8_MMA(ai, bj, At, Bt) do { __builtin_amdgcn_s_setprio(1); _Pragma("unroll") for (int m = 0; m < 4; ++m) _Pragma("unroll") for (int n = 0; n < 2; ++n) _Pragma("unroll") for (int k = 0; k < 2; ++k) \
;         acc[ai][bj][m][n] = __builtin_amdgcn_mfma_f32_16x16x32_bf16(Bt[n][k], At[m][k], acc[ai][bj][m][n], 0, 0, 0); __builtin_amdgcn_s_setprio(0); } while (0)
; #define PG8_WAIT_V(n) asm volatile("s_waitcnt vmcnt(" #n ")" ::: "memory")
; #define PG8_WAIT_L(n) asm volatile("s_waitcnt lgkmcnt(" #n ")" ::: "memory")
; #define PG8_BAR __builtin_amdgcn_s_barrier()
; #define PG8_SCHED __builtin_amdgcn_sched_barrier(0)
; template <class Epi, class Sched, bool ALIGN_EPI = false, bool SP2 = false>
; __device__ __forceinline__ void gemm_phase(PG8_LAS unsigned char* lds, const Gemm g, const Sched& S, const Epi& E) {
;     ...
;             PG8_WAIT_V(8); PG8_WAIT_L(0); PG8_BAR; PG8_MMA(0, 0, At, B0); PG8_MMA(0, 1, At, B1); PG8_BAR; PG8_SCHED;
;             PG8_LDA(At, 1, 1); PG8_STAGE(PG8_SB(1, 0), b3, voffB); PG8_STAGE(PG8_SB(1, 1), b3 + hstep, voffB); PG8_STAGE(PG8_SA(1, 0), a3, voffA);
;             PG8_WAIT_V(8); PG8_WAIT_L(0); PG8_BAR; PG8_MMA(1, 0, At, B0); PG8_MMA(1, 1, At, B1); PG8_BAR; PG8_SCHED;
;     ...
;         if constexpr (ALIGN_EPI) { if (wr == 0) PG8_BAR; }
	v_mfma_f32_16x16x32_bf16 v[68:71], v[186:189], v[226:229], v[68:71]
	v_mfma_f32_16x16x32_bf16 v[64:67], v[194:197], v[226:229], v[64:67]
	s_setprio 0
	s_mov_b32 m0, s89
	v_lshl_add_u64 v[230:231], v[230:231], 0, s[12:13]
	ds_read_b128 v[198:201], v164 offset:49152
	ds_read_b128 v[202:205], v164 offset:50176
	ds_read_b128 v[206:209], v164 offset:51200
	ds_read_b128 v[210:213], v164 offset:52224
	ds_read_b128 v[214:217], v164 offset:53248
	ds_read_b128 v[218:221], v164 offset:54272
	ds_read_b128 v[222:225], v164 offset:55296
	ds_read_b128 v[226:229], v164 offset:56320
	global_load_lds_dwordx4 v[230:231], off
	s_add_i32 m0, s89, 0x2000
	s_add_u32 s52, s74, 0x200080
	v_lshl_add_u64 v[230:231], v[232:233], 0, s[12:13]
	s_addc_u32 s53, s75, 0
	s_add_i32 s56, s88, s3
	global_load_lds_dwordx4 v[230:231], off
	s_mov_b32 m0, s56
	v_lshl_add_u64 v[230:231], s[52:53], 0, v[138:139]
	global_load_lds_dwordx4 v[230:231], off
	s_add_i32 m0, s56, 0x2000
	v_lshl_add_u64 v[230:231], s[52:53], 0, v[142:143]
	global_load_lds_dwordx4 v[230:231], off
	s_mov_b32 m0, s71
	v_lshl_add_u64 v[230:231], v[234:235], 0, s[12:13]
	global_load_lds_dwordx4 v[230:231], off
	s_mov_b32 m0, s78
	v_lshl_add_u64 v[230:231], v[236:237], 0, s[12:13]
	global_load_lds_dwordx4 v[230:231], off
	s_waitcnt vmcnt(8)
	s_waitcnt lgkmcnt(0)
	s_setprio 1
	s_barrier
	v_mfma_f32_16x16x32_bf16 v[60:63], v[166:169], v[198:201], v[60:63]
	v_mfma_f32_16x16x32_bf16 v[56:59], v[174:177], v[198:201], v[56:59]
	v_mfma_f32_16x16x32_bf16 v[52:55], v[166:169], v[206:209], v[52:55]
	v_mfma_f32_16x16x32_bf16 v[44:47], v[174:177], v[206:209], v[44:47]
	v_mfma_f32_16x16x32_bf16 v[36:39], v[166:169], v[214:217], v[36:39]
	v_mfma_f32_16x16x32_bf16 v[28:31], v[174:177], v[214:217], v[28:31]
	v_mfma_f32_16x16x32_bf16 v[20:23], v[166:169], v[222:225], v[20:23]
	v_mfma_f32_16x16x32_bf16 v[12:15], v[174:177], v[222:225], v[12:15]
	v_mfma_f32_16x16x32_bf16 v[60:63], v[170:173], v[202:205], v[60:63]
	v_mfma_f32_16x16x32_bf16 v[56:59], v[178:181], v[202:205], v[56:59]
	v_mfma_f32_16x16x32_bf16 v[52:55], v[170:173], v[210:213], v[52:55]
	v_mfma_f32_16x16x32_bf16 v[44:47], v[178:181], v[210:213], v[44:47]
	v_mfma_f32_16x16x32_bf16 v[36:39], v[170:173], v[218:221], v[36:39]
	v_mfma_f32_16x16x32_bf16 v[28:31], v[178:181], v[218:221], v[28:31]
	v_mfma_f32_16x16x32_bf16 v[20:23], v[170:173], v[226:229], v[20:23]
	v_mfma_f32_16x16x32_bf16 v[12:15], v[178:181], v[226:229], v[12:15]
	s_setprio 0
	s_setprio 1
	v_mfma_f32_16x16x32_bf16 v[48:51], v[182:185], v[198:201], v[48:51]
	v_mfma_f32_16x16x32_bf16 v[40:43], v[190:193], v[198:201], v[40:43]
	v_mfma_f32_16x16x32_bf16 v[32:35], v[182:185], v[206:209], v[32:35]
	v_mfma_f32_16x16x32_bf16 v[24:27], v[190:193], v[206:209], v[24:27]
	v_mfma_f32_16x16x32_bf16 v[16:19], v[182:185], v[214:217], v[16:19]
	v_mfma_f32_16x16x32_bf16 v[8:11], v[190:193], v[214:217], v[8:11]
	v_mfma_f32_16x16x32_bf16 v[4:7], v[182:185], v[222:225], v[4:7]
	v_mfma_f32_16x16x32_bf16 v[0:3], v[190:193], v[222:225], v[0:3]
	v_mfma_f32_16x16x32_bf16 v[48:51], v[186:189], v[202:205], v[48:51]
	v_mfma_f32_16x16x32_bf16 v[40:43], v[194:197], v[202:205], v[40:43]
	v_mfma_f32_16x16x32_bf16 v[32:35], v[186:189], v[210:213], v[32:35]
	v_mfma_f32_16x16x32_bf16 v[24:27], v[194:197], v[210:213], v[24:27]
	v_mfma_f32_16x16x32_bf16 v[16:19], v[186:189], v[218:221], v[16:19]
	v_mfma_f32_16x16x32_bf16 v[8:11], v[194:197], v[218:221], v[8:11]
	s_setprio 2
	s_barrier
	v_mfma_f32_16x16x32_bf16 v[4:7], v[186:189], v[226:229], v[4:7]
	v_mfma_f32_16x16x32_bf16 v[0:3], v[194:197], v[226:229], v[0:3]
	s_setprio 0
	s_add_i32 s49, s49, 2
	s_add_u32 s72, s72, 0x100
	s_addc_u32 s73, s73, 0
	s_add_u32 s37, s37, 0x100
	s_addc_u32 s41, s41, 0
	s_cmp_gt_u32 s49, 29
	s_cbranch_scc0 .LBB0_660
	s_and_b64 vcc, exec, s[14:15]
	s_cbranch_vccz .LBB0_663
	s_barrier

; #define PG8_STAGE(bufoff, gbase, voff) do { _Pragma("unroll") for (int _i = 0; _i < 2; ++_i) \
;         __builtin_amdgcn_global_load_lds((const unsigned*)((const char*)(gbase) + (voff)[_i]), (PG8_LAS unsigned*)(lds + (bufoff) + ldsw + _i * 8192), 16, 0, 0); } while (0)
; #define PG8_LDA(dst, b, h) do { _Pragma("unroll") for (int m = 0; m < 4; ++m) _Pragma("unroll") for (int k = 0; k < 2; ++k) dst[m][k] = *(const PG8_LAS bf16x8*)(lds + PG8_SA(b, h) + aoff + m * 2048 + k * 1024); } while (0)
; #define PG8_LDB(dst, b, h) do { _Pragma("unroll") for (int n = 0; n < 2; ++n) _Pragma("unroll") for (int k = 0; k < 2; ++k) dst[n][k] = *(const PG8_LAS bf16x8*)(lds + PG8_SB(b, h) + boff + n * 2048 + k * 1024); } while (0)
; #define PG8_MMA(ai, bj, At, Bt) do { __builtin_amdgcn_s_setprio(1); _Pragma("unroll") for (int m = 0; m < 4; ++m) _Pragma("unroll") for (int n = 0; n < 2; ++n) _Pragma("unroll") for (int k = 0; k < 2; ++k) \
;         acc[ai][bj][m][n] = __builtin_amdgcn_mfma_f32_16x16x32_bf16(Bt[n][k], At[m][k], acc[ai][bj][m][n], 0, 0, 0); __builtin_amdgcn_s_setprio(0); } while (0)
; #define PG8_WAIT_V(n) asm volatile("s_waitcnt vmcnt(" #n ")" ::: "memory")
; #define PG8_WAIT_L(n) asm volatile("s_waitcnt lgkmcnt(" #n ")" ::: "memory")
; #define PG8_BAR __builtin_amdgcn_s_barrier()
; template <class Epi, class Sched, bool ALIGN_EPI = false, bool SP2 = false>
; __device__ __forceinline__ void gemm_phase(PG8_LAS unsigned char* lds, const Gemm g, const Sched& S, const Epi& E) {
;     ...
;             const bool last = (t == nt - 2);
;             const char* a1 = cA + (size_t)(t + 1) * kstep;
;             const char* a2 = last ? nA : cA + (size_t)(t + 2) * kstep; const char* b2 = last ? nB : cB + (size_t)(t + 2) * kstep;
;             const char* a3 = a2 + kstep; const char* b3 = b2 + kstep;
;             if constexpr (SP2) {
;             PG8_LDB(B0, 0, 0); PG8_LDB(B1, 0, 1); PG8_SCHED; PG8_LDA(At, 0, 0); PG8_STAGE(PG8_SA(1, 1), a1 + hstep, voffA);
;             PG8_WAIT_V(8); PG8_WAIT_L(0); PG8_BAR; PG8_MMA(0, 0, At, B0); PG8_MMA(0, 1, At, B1); PG8_BAR; PG8_SCHED;
;             PG8_LDA(At, 0, 1); PG8_STAGE(PG8_SB(0, 0), b2, voffB); PG8_STAGE(PG8_SB(0, 1), b2 + hstep, voffB); PG8_STAGE(PG8_SA(0, 0), a2, voffA);
;             PG8_WAIT_V(8); PG8_WAIT_L(0); PG8_BAR; PG8_MMA(1, 0, At, B0); PG8_MMA(1, 1, At, B1); PG8_BAR; PG8_SCHED;
.LBB0_809:
	ds_read_b128 v[128:131], v180
	ds_read_b128 v[132:135], v180 offset:1024
	ds_read_b128 v[136:139], v180 offset:2048
	ds_read_b128 v[140:143], v180 offset:3072
	ds_read_b128 v[160:163], v181
	ds_read_b128 v[164:167], v181 offset:1024
	ds_read_b128 v[184:187], v181 offset:2048
	ds_read_b128 v[188:191], v181 offset:3072
	s_add_u32 s52, s72, 0xfff80080
	s_addc_u32 s53, s73, -1
	s_cmp_eq_u32 s92, 28
	s_cselect_b32 s77, s5, s53
	s_cselect_b32 s76, s49, s52
	s_cselect_b32 s75, s45, s91
	s_cselect_b32 s74, s89, s90
	v_lshl_add_u64 v[168:169], s[72:73], 0, v[154:155]
	s_add_i32 m0, s71, 0xc000
	ds_read_b128 v[192:195], v182
	ds_read_b128 v[196:199], v182 offset:1024
	ds_read_b128 v[200:203], v182 offset:2048
	ds_read_b128 v[204:207], v182 offset:3072
	ds_read_b128 v[208:211], v182 offset:4096
	ds_read_b128 v[212:215], v182 offset:5120
	ds_read_b128 v[216:219], v182 offset:6144
	ds_read_b128 v[220:223], v182 offset:7168
	global_load_lds_dwordx4 v[168:169], off
	s_add_i32 m0, s71, 0xe000
	v_lshl_add_u64 v[168:169], s[72:73], 0, v[156:157]
	global_load_lds_dwordx4 v[168:169], off
	s_waitcnt vmcnt(8)
	s_waitcnt lgkmcnt(0)
	s_setprio 1
	s_barrier
	v_mfma_f32_16x16x32_bf16 v[124:127], v[128:131], v[192:195], v[124:127]
	v_mfma_f32_16x16x32_bf16 v[120:123], v[136:139], v[192:195], v[120:123]
	v_mfma_f32_16x16x32_bf16 v[108:111], v[128:131], v[200:203], v[108:111]
	v_mfma_f32_16x16x32_bf16 v[104:107], v[136:139], v[200:203], v[104:107]
	v_mfma_f32_16x16x32_bf16 v[92:95], v[128:131], v[208:211], v[92:95]
	v_mfma_f32_16x16x32_bf16 v[88:91], v[136:139], v[208:211], v[88:91]
	v_mfma_f32_16x16x32_bf16 v[76:79], v[128:131], v[216:219], v[76:79]
	v_mfma_f32_16x16x32_bf16 v[72:75], v[136:139], v[216:219], v[72:75]
	v_mfma_f32_16x16x32_bf16 v[124:127], v[132:135], v[196:199], v[124:127]
	v_mfma_f32_16x16x32_bf16 v[120:123], v[140:143], v[196:199], v[120:123]
	v_mfma_f32_16x16x32_bf16 v[108:111], v[132:135], v[204:207], v[108:111]
	v_mfma_f32_16x16x32_bf16 v[104:107], v[140:143], v[204:207], v[104:107]
	v_mfma_f32_16x16x32_bf16 v[92:95], v[132:135], v[212:215], v[92:95]
	v_mfma_f32_16x16x32_bf16 v[88:91], v[140:143], v[212:215], v[88:91]
	v_mfma_f32_16x16x32_bf16 v[76:79], v[132:135], v[220:223], v[76:79]
	v_mfma_f32_16x16x32_bf16 v[72:75], v[140:143], v[220:223], v[72:75]
	s_setprio 0
	s_setprio 1
	v_mfma_f32_16x16x32_bf16 v[116:119], v[160:163], v[192:195], v[116:119]
	v_mfma_f32_16x16x32_bf16 v[112:115], v[184:187], v[192:195], v[112:115]
	v_mfma_f32_16x16x32_bf16 v[100:103], v[160:163], v[200:203], v[100:103]
	v_mfma_f32_16x16x32_bf16 v[96:99], v[184:187], v[200:203], v[96:99]
	v_mfma_f32_16x16x32_bf16 v[84:87], v[160:163], v[208:211], v[84:87]
	v_mfma_f32_16x16x32_bf16 v[80:83], v[184:187], v[208:211], v[80:83]
	v_mfma_f32_16x16x32_bf16 v[68:71], v[160:163], v[216:219], v[68:71]
	v_mfma_f32_16x16x32_bf16 v[64:67], v[184:187], v[216:219], v[64:67]
	v_mfma_f32_16x16x32_bf16 v[116:119], v[164:167], v[196:199], v[116:119]
	v_mfma_f32_16x16x32_bf16 v[112:115], v[188:191], v[196:199], v[112:115]
	v_mfma_f32_16x16x32_bf16 v[100:103], v[164:167], v[204:207], v[100:103]
	v_mfma_f32_16x16x32_bf16 v[96:99], v[188:191], v[204:207], v[96:99]
	v_mfma_f32_16x16x32_bf16 v[84:87], v[164:167], v[212:215], v[84:87]
	v_mfma_f32_16x16x32_bf16 v[80:83], v[188:191], v[212:215], v[80:83]
	s_setprio 2
	s_barrier
	v_mfma_f32_16x16x32_bf16 v[68:71], v[164:167], v[220:223], v[68:71]
	v_mfma_f32_16x16x32_bf16 v[64:67], v[188:191], v[220:223], v[64:67]
	s_setprio 0
	s_add_i32 s52, s83, s78
	v_lshl_add_u64 v[168:169], s[74:75], 0, v[148:149]
	s_mov_b32 m0, s52
	ds_read_b128 v[192:195], v182 offset:16384
	ds_read_b128 v[196:199], v182 offset:17408
	ds_read_b128 v[200:203], v182 offset:18432
	ds_read_b128 v[204:207], v182 offset:19456
	ds_read_b128 v[208:211], v182 offset:20480
	ds_read_b128 v[212:215], v182 offset:21504
	ds_read_b128 v[216:219], v182 offset:22528
	ds_read_b128 v[220:223], v182 offset:23552
	global_load_lds_dwordx4 v[168:169], off
	s_add_i32 m0, s52, 0x2000
	s_add_u32 s52, s74, 0x80000
	v_lshl_add_u64 v[224:225], s[74:75], 0, v[152:153]
	s_addc_u32 s53, s75, 0
	s_add_i32 s56, s84, s78
	global_load_lds_dwordx4 v[224:225], off
	v_lshl_add_u64 v[226:227], s[52:53], 0, v[148:149]
	s_mov_b32 m0, s56
	v_lshl_add_u64 v[228:229], s[76:77], 0, v[150:151]
	global_load_lds_dwordx4 v[226:227], off
	s_add_i32 m0, s56, 0x2000
	v_lshl_add_u64 v[226:227], s[52:53], 0, v[152:153]
	global_load_lds_dwordx4 v[226:227], off
	s_mov_b32 m0, s71
	v_lshl_add_u64 v[226:227], s[76:77], 0, v[144:145]
	global_load_lds_dwordx4 v[226:227], off
	s_mov_b32 m0, s79
	s_nop 0
	global_load_lds_dwordx4 v[228:229], off
	s_waitcnt vmcnt(8)
	s_waitcnt lgkmcnt(0)
	s_setprio 1
	s_barrier
; #define PG8_STAGE(bufoff, gbase, voff) do { _Pragma("unroll") for (int _i = 0; _i < 2; ++_i) \
;         __builtin_amdgcn_global_load_lds((const unsigned*)((const char*)(gbase) + (voff)[_i]), (PG8_LAS unsigned*)(lds + (bufoff) + ldsw + _i * 8192), 16, 0, 0); } while (0)
; #define PG8_LDA(dst, b, h) do { _Pragma("unroll") for (int m = 0; m < 4; ++m) _Pragma("unroll") for (int k = 0; k < 2; ++k) dst[m][k] = *(const PG8_LAS bf16x8*)(lds + PG8_SA(b, h) + aoff + m * 2048 + k * 1024); } while (0)
; #define PG8_LDB(dst, b, h) do { _Pragma("unroll") for (int n = 0; n < 2; ++n) _Pragma("unroll") for (int k = 0; k < 2; ++k) dst[n][k] = *(const PG8_LAS bf16x8*)(lds + PG8_SB(b, h) + boff + n * 2048 + k * 1024); } while (0)
; #define PG8_MMA(ai, bj, At, Bt) do { __builtin_amdgcn_s_setprio(1); _Pragma("unroll") for (int m = 0; m < 4; ++m) _Pragma("unroll") for (int n = 0; n < 2; ++n) _Pragma("unroll") for (int k = 0; k < 2; ++k) \
;         acc[ai][bj][m][n] = __builtin_amdgcn_mfma_f32_16x16x32_bf16(Bt[n][k], At[m][k], acc[ai][bj][m][n], 0, 0, 0); __builtin_amdgcn_s_setprio(0); } while (0)
; #define PG8_WAIT_V(n) asm volatile("s_waitcnt vmcnt(" #n ")" ::: "memory")
; #define PG8_WAIT_L(n) asm volatile("s_waitcnt lgkmcnt(" #n ")" ::: "memory")
; #define PG8_BAR __builtin_amdgcn_s_barrier()
; #define PG8_SCHED __builtin_amdgcn_sched_barrier(0)
; template <class Epi, class Sched, bool ALIGN_EPI = false, bool SP2 = false>
; __device__ __forceinline__ void gemm_phase(PG8_LAS unsigned char* lds, const Gemm g, const Sched& S, const Epi& E) {
;     ...
;             PG8_WAIT_V(8); PG8_WAIT_L(0); PG8_BAR; PG8_MMA(1, 0, At, B0); PG8_MMA(1, 1, At, B1); PG8_BAR; PG8_SCHED;
;             PG8_LDB(B0, 1, 0); PG8_LDB(B1, 1, 1); PG8_SCHED; PG8_LDA(At, 1, 0); PG8_STAGE(PG8_SA(0, 1), a2 + hstep, voffA);
;             PG8_WAIT_V(8); PG8_WAIT_L(0); PG8_BAR; PG8_MMA(0, 0, At, B0); PG8_MMA(0, 1, At, B1); PG8_BAR; PG8_SCHED;
	v_mfma_f32_16x16x32_bf16 v[60:63], v[128:131], v[192:195], v[60:63]
	v_mfma_f32_16x16x32_bf16 v[56:59], v[136:139], v[192:195], v[56:59]
	v_mfma_f32_16x16x32_bf16 v[44:47], v[128:131], v[200:203], v[44:47]
	v_mfma_f32_16x16x32_bf16 v[40:43], v[136:139], v[200:203], v[40:43]
	v_mfma_f32_16x16x32_bf16 v[28:31], v[128:131], v[208:211], v[28:31]
	v_mfma_f32_16x16x32_bf16 v[24:27], v[136:139], v[208:211], v[24:27]
	v_mfma_f32_16x16x32_bf16 v[12:15], v[128:131], v[216:219], v[12:15]
	v_mfma_f32_16x16x32_bf16 v[8:11], v[136:139], v[216:219], v[8:11]
	v_mfma_f32_16x16x32_bf16 v[60:63], v[132:135], v[196:199], v[60:63]
	v_mfma_f32_16x16x32_bf16 v[56:59], v[140:143], v[196:199], v[56:59]
	v_mfma_f32_16x16x32_bf16 v[44:47], v[132:135], v[204:207], v[44:47]
	v_mfma_f32_16x16x32_bf16 v[40:43], v[140:143], v[204:207], v[40:43]
	v_mfma_f32_16x16x32_bf16 v[28:31], v[132:135], v[212:215], v[28:31]
	v_mfma_f32_16x16x32_bf16 v[24:27], v[140:143], v[212:215], v[24:27]
	v_mfma_f32_16x16x32_bf16 v[12:15], v[132:135], v[220:223], v[12:15]
	v_mfma_f32_16x16x32_bf16 v[8:11], v[140:143], v[220:223], v[8:11]
	s_setprio 0
	s_setprio 1
	v_mfma_f32_16x16x32_bf16 v[52:55], v[160:163], v[192:195], v[52:55]
	v_mfma_f32_16x16x32_bf16 v[48:51], v[184:187], v[192:195], v[48:51]
	v_mfma_f32_16x16x32_bf16 v[36:39], v[160:163], v[200:203], v[36:39]
	v_mfma_f32_16x16x32_bf16 v[32:35], v[184:187], v[200:203], v[32:35]
	v_mfma_f32_16x16x32_bf16 v[20:23], v[160:163], v[208:211], v[20:23]
	v_mfma_f32_16x16x32_bf16 v[16:19], v[184:187], v[208:211], v[16:19]
	v_mfma_f32_16x16x32_bf16 v[4:7], v[160:163], v[216:219], v[4:7]
	v_mfma_f32_16x16x32_bf16 v[0:3], v[184:187], v[216:219], v[0:3]
	v_mfma_f32_16x16x32_bf16 v[52:55], v[164:167], v[196:199], v[52:55]
	v_mfma_f32_16x16x32_bf16 v[48:51], v[188:191], v[196:199], v[48:51]
	v_mfma_f32_16x16x32_bf16 v[36:39], v[164:167], v[204:207], v[36:39]
	v_mfma_f32_16x16x32_bf16 v[32:35], v[188:191], v[204:207], v[32:35]
	v_mfma_f32_16x16x32_bf16 v[20:23], v[164:167], v[212:215], v[20:23]
	v_mfma_f32_16x16x32_bf16 v[16:19], v[188:191], v[212:215], v[16:19]
	s_setprio 2
	s_barrier
	v_mfma_f32_16x16x32_bf16 v[4:7], v[164:167], v[220:223], v[4:7]
	v_mfma_f32_16x16x32_bf16 v[0:3], v[188:191], v[220:223], v[0:3]
	s_setprio 0
	s_add_i32 s56, 0, 0x18000
	s_add_i32 s57, 0, 0x1c000
	v_add_u32_e32 v140, s56, v171
	v_add_u32_e32 v188, s57, v171
	ds_read_b128 v[128:131], v140
	ds_read_b128 v[132:135], v140 offset:1024
	ds_read_b128 v[136:139], v140 offset:2048
	ds_read_b128 v[140:143], v140 offset:3072
	ds_read_b128 v[160:163], v188
	ds_read_b128 v[164:167], v188 offset:1024
	ds_read_b128 v[184:187], v188 offset:2048
	ds_read_b128 v[188:191], v188 offset:3072
	s_add_u32 s52, s76, 0x80000
	s_addc_u32 s53, s77, 0
	s_mov_b32 m0, s80
	v_lshl_add_u64 v[230:231], s[52:53], 0, v[144:145]
	ds_read_b128 v[192:195], v182 offset:32768
	ds_read_b128 v[196:199], v182 offset:33792
	ds_read_b128 v[200:203], v182 offset:34816
	ds_read_b128 v[204:207], v182 offset:35840
	ds_read_b128 v[208:211], v182 offset:36864
	ds_read_b128 v[212:215], v182 offset:37888
	ds_read_b128 v[216:219], v182 offset:38912
	ds_read_b128 v[220:223], v182 offset:39936
	global_load_lds_dwordx4 v[230:231], off
	s_mov_b32 m0, s81
	v_lshl_add_u64 v[230:231], s[52:53], 0, v[150:151]
	global_load_lds_dwordx4 v[230:231], off
	s_waitcnt vmcnt(8)
	s_waitcnt lgkmcnt(0)
	s_setprio 1
	s_barrier
	v_mfma_f32_16x16x32_bf16 v[124:127], v[128:131], v[192:195], v[124:127]
	v_mfma_f32_16x16x32_bf16 v[120:123], v[136:139], v[192:195], v[120:123]
	v_mfma_f32_16x16x32_bf16 v[108:111], v[128:131], v[200:203], v[108:111]
	v_mfma_f32_16x16x32_bf16 v[104:107], v[136:139], v[200:203], v[104:107]
	v_mfma_f32_16x16x32_bf16 v[92:95], v[128:131], v[208:211], v[92:95]
	v_mfma_f32_16x16x32_bf16 v[88:91], v[136:139], v[208:211], v[88:91]
	v_mfma_f32_16x16x32_bf16 v[76:79], v[128:131], v[216:219], v[76:79]
	v_mfma_f32_16x16x32_bf16 v[72:75], v[136:139], v[216:219], v[72:75]
	v_mfma_f32_16x16x32_bf16 v[124:127], v[132:135], v[196:199], v[124:127]
	v_mfma_f32_16x16x32_bf16 v[120:123], v[140:143], v[196:199], v[120:123]
	v_mfma_f32_16x16x32_bf16 v[108:111], v[132:135], v[204:207], v[108:111]
	v_mfma_f32_16x16x32_bf16 v[104:107], v[140:143], v[204:207], v[104:107]
	v_mfma_f32_16x16x32_bf16 v[92:95], v[132:135], v[212:215], v[92:95]
	v_mfma_f32_16x16x32_bf16 v[88:91], v[140:143], v[212:215], v[88:91]
	v_mfma_f32_16x16x32_bf16 v[76:79], v[132:135], v[220:223], v[76:79]
	v_mfma_f32_16x16x32_bf16 v[72:75], v[140:143], v[220:223], v[72:75]
	s_setprio 0
	s_setprio 1
	v_mfma_f32_16x16x32_bf16 v[116:119], v[160:163], v[192:195], v[116:119]
	v_mfma_f32_16x16x32_bf16 v[112:115], v[184:187], v[192:195], v[112:115]
	v_mfma_f32_16x16x32_bf16 v[100:103], v[160:163], v[200:203], v[100:103]
	v_mfma_f32_16x16x32_bf16 v[96:99], v[184:187], v[200:203], v[96:99]
	v_mfma_f32_16x16x32_bf16 v[84:87], v[160:163], v[208:211], v[84:87]
	v_mfma_f32_16x16x32_bf16 v[80:83], v[184:187], v[208:211], v[80:83]
	v_mfma_f32_16x16x32_bf16 v[68:71], v[160:163], v[216:219], v[68:71]
	v_mfma_f32_16x16x32_bf16 v[64:67], v[184:187], v[216:219], v[64:67]
	v_mfma_f32_16x16x32_bf16 v[116:119], v[164:167], v[196:199], v[116:119]
	v_mfma_f32_16x16x32_bf16 v[112:115], v[188:191], v[196:199], v[112:115]
	v_mfma_f32_16x16x32_bf16 v[100:103], v[164:167], v[204:207], v[100:103]
	v_mfma_f32_16x16x32_bf16 v[96:99], v[188:191], v[204:207], v[96:99]
	v_mfma_f32_16x16x32_bf16 v[84:87], v[164:167], v[212:215], v[84:87]
	v_mfma_f32_16x16x32_bf16 v[80:83], v[188:191], v[212:215], v[80:83]
	s_setprio 2
	s_barrier
; #define PG8_STAGE(bufoff, gbase, voff) do { _Pragma("unroll") for (int _i = 0; _i < 2; ++_i) \
;         __builtin_amdgcn_global_load_lds((const unsigned*)((const char*)(gbase) + (voff)[_i]), (PG8_LAS unsigned*)(lds + (bufoff) + ldsw + _i * 8192), 16, 0, 0); } while (0)
; #define PG8_LDA(dst, b, h) do { _Pragma("unroll") for (int m = 0; m < 4; ++m) _Pragma("unroll") for (int k = 0; k < 2; ++k) dst[m][k] = *(const PG8_LAS bf16x8*)(lds + PG8_SA(b, h) + aoff + m * 2048 + k * 1024); } while (0)
; #define PG8_MMA(ai, bj, At, Bt) do { __builtin_amdgcn_s_setprio(1); _Pragma("unroll") for (int m = 0; m < 4; ++m) _Pragma("unroll") for (int n = 0; n < 2; ++n) _Pragma("unroll") for (int k = 0; k < 2; ++k) \
;         acc[ai][bj][m][n] = __builtin_amdgcn_mfma_f32_16x16x32_bf16(Bt[n][k], At[m][k], acc[ai][bj][m][n], 0, 0, 0); __builtin_amdgcn_s_setprio(0); } while (0)
; #define PG8_WAIT_V(n) asm volatile("s_waitcnt vmcnt(" #n ")" ::: "memory")
; #define PG8_WAIT_L(n) asm volatile("s_waitcnt lgkmcnt(" #n ")" ::: "memory")
; #define PG8_BAR __builtin_amdgcn_s_barrier()
; #define PG8_SCHED __builtin_amdgcn_sched_barrier(0)
; template <class Epi, class Sched, bool ALIGN_EPI = false, bool SP2 = false>
; __device__ __forceinline__ void gemm_phase(PG8_LAS unsigned char* lds, const Gemm g, const Sched& S, const Epi& E) {
;     ...
;             PG8_WAIT_V(8); PG8_WAIT_L(0); PG8_BAR; PG8_MMA(0, 0, At, B0); PG8_MMA(0, 1, At, B1); PG8_BAR; PG8_SCHED;
;             PG8_LDA(At, 1, 1); PG8_STAGE(PG8_SB(1, 0), b3, voffB); PG8_STAGE(PG8_SB(1, 1), b3 + hstep, voffB); PG8_STAGE(PG8_SA(1, 0), a3, voffA);
;             PG8_WAIT_V(8); PG8_WAIT_L(0); PG8_BAR; PG8_MMA(1, 0, At, B0); PG8_MMA(1, 1, At, B1); PG8_BAR; PG8_SCHED;
;     ...
;         if constexpr (ALIGN_EPI) { if (wr == 0) PG8_BAR; }
	v_mfma_f32_16x16x32_bf16 v[68:71], v[164:167], v[220:223], v[68:71]
	v_mfma_f32_16x16x32_bf16 v[64:67], v[188:191], v[220:223], v[64:67]
	s_setprio 0
	s_add_i32 s52, s56, s78
	v_lshl_add_u64 v[168:169], v[168:169], 0, s[40:41]
	s_mov_b32 m0, s52
	ds_read_b128 v[192:195], v182 offset:49152
	ds_read_b128 v[196:199], v182 offset:50176
	ds_read_b128 v[200:203], v182 offset:51200
	ds_read_b128 v[204:207], v182 offset:52224
	ds_read_b128 v[208:211], v182 offset:53248
	ds_read_b128 v[212:215], v182 offset:54272
	ds_read_b128 v[216:219], v182 offset:55296
	ds_read_b128 v[220:223], v182 offset:56320
	global_load_lds_dwordx4 v[168:169], off
	s_add_i32 m0, s52, 0x2000
	s_add_u32 s52, s74, 0x80080
	v_lshl_add_u64 v[168:169], v[224:225], 0, s[40:41]
	s_addc_u32 s53, s75, 0
	s_add_i32 s56, s57, s78
	global_load_lds_dwordx4 v[168:169], off
	s_mov_b32 m0, s56
	v_lshl_add_u64 v[168:169], s[52:53], 0, v[148:149]
	global_load_lds_dwordx4 v[168:169], off
	s_add_i32 m0, s56, 0x2000
	v_lshl_add_u64 v[168:169], s[52:53], 0, v[152:153]
	global_load_lds_dwordx4 v[168:169], off
	s_mov_b32 m0, s3
	v_lshl_add_u64 v[168:169], v[226:227], 0, s[40:41]
	global_load_lds_dwordx4 v[168:169], off
	s_mov_b32 m0, s28
	v_lshl_add_u64 v[168:169], v[228:229], 0, s[40:41]
	global_load_lds_dwordx4 v[168:169], off
	s_waitcnt vmcnt(8)
	s_waitcnt lgkmcnt(0)
	s_setprio 1
	s_barrier
	v_mfma_f32_16x16x32_bf16 v[60:63], v[128:131], v[192:195], v[60:63]
	v_mfma_f32_16x16x32_bf16 v[56:59], v[136:139], v[192:195], v[56:59]
	v_mfma_f32_16x16x32_bf16 v[44:47], v[128:131], v[200:203], v[44:47]
	v_mfma_f32_16x16x32_bf16 v[40:43], v[136:139], v[200:203], v[40:43]
	v_mfma_f32_16x16x32_bf16 v[28:31], v[128:131], v[208:211], v[28:31]
	v_mfma_f32_16x16x32_bf16 v[24:27], v[136:139], v[208:211], v[24:27]
	v_mfma_f32_16x16x32_bf16 v[12:15], v[128:131], v[216:219], v[12:15]
	v_mfma_f32_16x16x32_bf16 v[8:11], v[136:139], v[216:219], v[8:11]
	v_mfma_f32_16x16x32_bf16 v[60:63], v[132:135], v[196:199], v[60:63]
	v_mfma_f32_16x16x32_bf16 v[56:59], v[140:143], v[196:199], v[56:59]
	v_mfma_f32_16x16x32_bf16 v[44:47], v[132:135], v[204:207], v[44:47]
	v_mfma_f32_16x16x32_bf16 v[40:43], v[140:143], v[204:207], v[40:43]
	v_mfma_f32_16x16x32_bf16 v[28:31], v[132:135], v[212:215], v[28:31]
	v_mfma_f32_16x16x32_bf16 v[24:27], v[140:143], v[212:215], v[24:27]
	v_mfma_f32_16x16x32_bf16 v[12:15], v[132:135], v[220:223], v[12:15]
	v_mfma_f32_16x16x32_bf16 v[8:11], v[140:143], v[220:223], v[8:11]
	s_setprio 0
	s_setprio 1
	v_mfma_f32_16x16x32_bf16 v[52:55], v[160:163], v[192:195], v[52:55]
	v_mfma_f32_16x16x32_bf16 v[48:51], v[184:187], v[192:195], v[48:51]
	v_mfma_f32_16x16x32_bf16 v[36:39], v[160:163], v[200:203], v[36:39]
	v_mfma_f32_16x16x32_bf16 v[32:35], v[184:187], v[200:203], v[32:35]
	v_mfma_f32_16x16x32_bf16 v[20:23], v[160:163], v[208:211], v[20:23]
	v_mfma_f32_16x16x32_bf16 v[16:19], v[184:187], v[208:211], v[16:19]
	v_mfma_f32_16x16x32_bf16 v[4:7], v[160:163], v[216:219], v[4:7]
	v_mfma_f32_16x16x32_bf16 v[0:3], v[184:187], v[216:219], v[0:3]
	v_mfma_f32_16x16x32_bf16 v[52:55], v[164:167], v[196:199], v[52:55]
	v_mfma_f32_16x16x32_bf16 v[48:51], v[188:191], v[196:199], v[48:51]
	v_mfma_f32_16x16x32_bf16 v[36:39], v[164:167], v[204:207], v[36:39]
	v_mfma_f32_16x16x32_bf16 v[32:35], v[188:191], v[204:207], v[32:35]
	v_mfma_f32_16x16x32_bf16 v[20:23], v[164:167], v[212:215], v[20:23]
	v_mfma_f32_16x16x32_bf16 v[16:19], v[188:191], v[212:215], v[16:19]
	s_setprio 2
	s_barrier
	v_mfma_f32_16x16x32_bf16 v[4:7], v[164:167], v[220:223], v[4:7]
	v_mfma_f32_16x16x32_bf16 v[0:3], v[188:191], v[220:223], v[0:3]
	s_setprio 0
	s_add_i32 s92, s92, 2
	s_add_u32 s72, s72, 0x100
	s_addc_u32 s73, s73, 0
	s_add_u32 s90, s90, 0x100
	s_addc_u32 s91, s91, 0
	s_cmp_gt_u32 s92, 29
	s_cbranch_scc0 .LBB0_809
	s_and_b64 vcc, exec, s[42:43]
	s_cbranch_vccz .LBB0_812
	s_barrier

; #define PG8_STAGE(bufoff, gbase, voff) do { _Pragma("unroll") for (int _i = 0; _i < 2; ++_i) \
;         __builtin_amdgcn_global_load_lds((const unsigned*)((const char*)(gbase) + (voff)[_i]), (PG8_LAS unsigned*)(lds + (bufoff) + ldsw + _i * 8192), 16, 0, 0); } while (0)
; #define PG8_LDA(dst, b, h) do { _Pragma("unroll") for (int m = 0; m < 4; ++m) _Pragma("unroll") for (int k = 0; k < 2; ++k) dst[m][k] = *(const PG8_LAS bf16x8*)(lds + PG8_SA(b, h) + aoff + m * 2048 + k * 1024); } while (0)
; #define PG8_LDB(dst, b, h) do { _Pragma("unroll") for (int n = 0; n < 2; ++n) _Pragma("unroll") for (int k = 0; k < 2; ++k) dst[n][k] = *(const PG8_LAS bf16x8*)(lds + PG8_SB(b, h) + boff + n * 2048 + k * 1024); } while (0)
; #define PG8_MMA(ai, bj, At, Bt) do { __builtin_amdgcn_s_setprio(1); _Pragma("unroll") for (int m = 0; m < 4; ++m) _Pragma("unroll") for (int n = 0; n < 2; ++n) _Pragma("unroll") for (int k = 0; k < 2; ++k) \
;         acc[ai][bj][m][n] = __builtin_amdgcn_mfma_f32_16x16x32_bf16(Bt[n][k], At[m][k], acc[ai][bj][m][n], 0, 0, 0); __builtin_amdgcn_s_setprio(0); } while (0)
; #define PG8_WAIT_V(n) asm volatile("s_waitcnt vmcnt(" #n ")" ::: "memory")
; #define PG8_WAIT_L(n) asm volatile("s_waitcnt lgkmcnt(" #n ")" ::: "memory")
; #define PG8_BAR __builtin_amdgcn_s_barrier()
; template <class Epi, class Sched, bool ALIGN_EPI = false, bool SP2 = false>
; __device__ __forceinline__ void gemm_phase(PG8_LAS unsigned char* lds, const Gemm g, const Sched& S, const Epi& E) {
;     ...
;             const bool last = (t == nt - 2);
;             const char* a1 = cA + (size_t)(t + 1) * kstep;
;             const char* a2 = last ? nA : cA + (size_t)(t + 2) * kstep; const char* b2 = last ? nB : cB + (size_t)(t + 2) * kstep;
;             const char* a3 = a2 + kstep; const char* b3 = b2 + kstep;
;             if constexpr (SP2) {
;             PG8_LDB(B0, 0, 0); PG8_LDB(B1, 0, 1); PG8_SCHED; PG8_LDA(At, 0, 0); PG8_STAGE(PG8_SA(1, 1), a1 + hstep, voffA);
;             PG8_WAIT_V(8); PG8_WAIT_L(0); PG8_BAR; PG8_MMA(0, 0, At, B0); PG8_MMA(0, 1, At, B1); PG8_BAR; PG8_SCHED;
;             PG8_LDA(At, 0, 1); PG8_STAGE(PG8_SB(0, 0), b2, voffB); PG8_STAGE(PG8_SB(0, 1), b2 + hstep, voffB); PG8_STAGE(PG8_SA(0, 0), a2, voffA);
;             PG8_WAIT_V(8); PG8_WAIT_L(0); PG8_BAR; PG8_MMA(1, 0, At, B0); PG8_MMA(1, 1, At, B1); PG8_BAR; PG8_SCHED;
.LBB0_1051:
	ds_read_b128 v[128:131], v205
	ds_read_b128 v[132:135], v205 offset:1024
	ds_read_b128 v[154:157], v205 offset:2048
	ds_read_b128 v[158:161], v205 offset:3072
	ds_read_b128 v[162:165], v206
	ds_read_b128 v[166:169], v206 offset:1024
	ds_read_b128 v[170:173], v206 offset:2048
	ds_read_b128 v[174:177], v206 offset:3072
	s_add_u32 s54, s52, 0xfff80080
	s_addc_u32 s55, s53, -1
	s_cmp_eq_u32 s77, 28
	s_cselect_b32 s57, s43, s55
	s_cselect_b32 s56, s49, s54
	s_cselect_b32 s55, s37, s76
	s_cselect_b32 s54, s51, s75
	v_lshl_add_u64 v[218:219], s[52:53], 0, v[144:145]
	s_add_i32 m0, s61, 0xc000
	ds_read_b128 v[178:181], v207
	ds_read_b128 v[182:185], v207 offset:1024
	ds_read_b128 v[186:189], v207 offset:2048
	ds_read_b128 v[190:193], v207 offset:3072
	ds_read_b128 v[194:197], v207 offset:4096
	ds_read_b128 v[198:201], v207 offset:5120
	ds_read_b128 v[210:213], v207 offset:6144
	ds_read_b128 v[214:217], v207 offset:7168
	global_load_lds_dwordx4 v[218:219], off
	s_add_i32 m0, s61, 0xe000
	v_lshl_add_u64 v[218:219], s[52:53], 0, v[148:149]
	global_load_lds_dwordx4 v[218:219], off
	s_waitcnt vmcnt(8)
	s_waitcnt lgkmcnt(0)
	s_setprio 1
	s_barrier
	v_mfma_f32_16x16x32_bf16 v[124:127], v[128:131], v[178:181], v[124:127]
	v_mfma_f32_16x16x32_bf16 v[120:123], v[154:157], v[178:181], v[120:123]
	v_mfma_f32_16x16x32_bf16 v[116:119], v[128:131], v[186:189], v[116:119]
	v_mfma_f32_16x16x32_bf16 v[112:115], v[154:157], v[186:189], v[112:115]
	v_mfma_f32_16x16x32_bf16 v[108:111], v[128:131], v[194:197], v[108:111]
	v_mfma_f32_16x16x32_bf16 v[104:107], v[154:157], v[194:197], v[104:107]
	v_mfma_f32_16x16x32_bf16 v[100:103], v[128:131], v[210:213], v[100:103]
	v_mfma_f32_16x16x32_bf16 v[96:99], v[154:157], v[210:213], v[96:99]
	v_mfma_f32_16x16x32_bf16 v[124:127], v[132:135], v[182:185], v[124:127]
	v_mfma_f32_16x16x32_bf16 v[120:123], v[158:161], v[182:185], v[120:123]
	v_mfma_f32_16x16x32_bf16 v[116:119], v[132:135], v[190:193], v[116:119]
	v_mfma_f32_16x16x32_bf16 v[112:115], v[158:161], v[190:193], v[112:115]
	v_mfma_f32_16x16x32_bf16 v[108:111], v[132:135], v[198:201], v[108:111]
	v_mfma_f32_16x16x32_bf16 v[104:107], v[158:161], v[198:201], v[104:107]
	v_mfma_f32_16x16x32_bf16 v[100:103], v[132:135], v[214:217], v[100:103]
	v_mfma_f32_16x16x32_bf16 v[96:99], v[158:161], v[214:217], v[96:99]
	s_setprio 0
	s_setprio 1
	v_mfma_f32_16x16x32_bf16 v[60:63], v[162:165], v[178:181], v[60:63]
	v_mfma_f32_16x16x32_bf16 v[56:59], v[170:173], v[178:181], v[56:59]
	v_mfma_f32_16x16x32_bf16 v[52:55], v[162:165], v[186:189], v[52:55]
	v_mfma_f32_16x16x32_bf16 v[48:51], v[170:173], v[186:189], v[48:51]
	v_mfma_f32_16x16x32_bf16 v[44:47], v[162:165], v[194:197], v[44:47]
	v_mfma_f32_16x16x32_bf16 v[40:43], v[170:173], v[194:197], v[40:43]
	v_mfma_f32_16x16x32_bf16 v[36:39], v[162:165], v[210:213], v[36:39]
	v_mfma_f32_16x16x32_bf16 v[32:35], v[170:173], v[210:213], v[32:35]
	v_mfma_f32_16x16x32_bf16 v[60:63], v[166:169], v[182:185], v[60:63]
	v_mfma_f32_16x16x32_bf16 v[56:59], v[174:177], v[182:185], v[56:59]
	v_mfma_f32_16x16x32_bf16 v[52:55], v[166:169], v[190:193], v[52:55]
	v_mfma_f32_16x16x32_bf16 v[48:51], v[174:177], v[190:193], v[48:51]
	v_mfma_f32_16x16x32_bf16 v[44:47], v[166:169], v[198:201], v[44:47]
	v_mfma_f32_16x16x32_bf16 v[40:43], v[174:177], v[198:201], v[40:43]
	s_setprio 2
	s_barrier
	v_mfma_f32_16x16x32_bf16 v[36:39], v[166:169], v[214:217], v[36:39]
	v_mfma_f32_16x16x32_bf16 v[32:35], v[174:177], v[214:217], v[32:35]
	s_setprio 0
	s_add_i32 s78, s33, s60
	v_lshl_add_u64 v[218:219], s[54:55], 0, v[138:139]
	s_mov_b32 m0, s78
	ds_read_b128 v[178:181], v207 offset:16384
	ds_read_b128 v[182:185], v207 offset:17408
	ds_read_b128 v[186:189], v207 offset:18432
	ds_read_b128 v[190:193], v207 offset:19456
	ds_read_b128 v[194:197], v207 offset:20480
	ds_read_b128 v[198:201], v207 offset:21504
	ds_read_b128 v[210:213], v207 offset:22528
	ds_read_b128 v[214:217], v207 offset:23552
	global_load_lds_dwordx4 v[218:219], off
	s_add_i32 m0, s78, 0x2000
	s_add_u32 s78, s54, 0x80000
	v_lshl_add_u64 v[220:221], s[54:55], 0, v[142:143]
	s_addc_u32 s79, s55, 0
	s_add_i32 s80, s74, s60
	global_load_lds_dwordx4 v[220:221], off
	v_lshl_add_u64 v[222:223], s[78:79], 0, v[138:139]
	s_mov_b32 m0, s80
	v_lshl_add_u64 v[224:225], s[56:57], 0, v[140:141]
	global_load_lds_dwordx4 v[222:223], off
	s_add_i32 m0, s80, 0x2000
	v_lshl_add_u64 v[222:223], s[78:79], 0, v[142:143]
	global_load_lds_dwordx4 v[222:223], off
	s_mov_b32 m0, s61
	v_lshl_add_u64 v[222:223], s[56:57], 0, v[136:137]
	global_load_lds_dwordx4 v[222:223], off
	s_mov_b32 m0, s62
	s_nop 0
	global_load_lds_dwordx4 v[224:225], off
	s_waitcnt vmcnt(8)
	s_waitcnt lgkmcnt(0)
	s_setprio 1
	s_barrier
; #define PG8_STAGE(bufoff, gbase, voff) do { _Pragma("unroll") for (int _i = 0; _i < 2; ++_i) \
;         __builtin_amdgcn_global_load_lds((const unsigned*)((const char*)(gbase) + (voff)[_i]), (PG8_LAS unsigned*)(lds + (bufoff) + ldsw + _i * 8192), 16, 0, 0); } while (0)
; #define PG8_LDA(dst, b, h) do { _Pragma("unroll") for (int m = 0; m < 4; ++m) _Pragma("unroll") for (int k = 0; k < 2; ++k) dst[m][k] = *(const PG8_LAS bf16x8*)(lds + PG8_SA(b, h) + aoff + m * 2048 + k * 1024); } while (0)
; #define PG8_LDB(dst, b, h) do { _Pragma("unroll") for (int n = 0; n < 2; ++n) _Pragma("unroll") for (int k = 0; k < 2; ++k) dst[n][k] = *(const PG8_LAS bf16x8*)(lds + PG8_SB(b, h) + boff + n * 2048 + k * 1024); } while (0)
; #define PG8_MMA(ai, bj, At, Bt) do { __builtin_amdgcn_s_setprio(1); _Pragma("unroll") for (int m = 0; m < 4; ++m) _Pragma("unroll") for (int n = 0; n < 2; ++n) _Pragma("unroll") for (int k = 0; k < 2; ++k) \
;         acc[ai][bj][m][n] = __builtin_amdgcn_mfma_f32_16x16x32_bf16(Bt[n][k], At[m][k], acc[ai][bj][m][n], 0, 0, 0); __builtin_amdgcn_s_setprio(0); } while (0)
; #define PG8_WAIT_V(n) asm volatile("s_waitcnt vmcnt(" #n ")" ::: "memory")
; #define PG8_WAIT_L(n) asm volatile("s_waitcnt lgkmcnt(" #n ")" ::: "memory")
; #define PG8_BAR __builtin_amdgcn_s_barrier()
; #define PG8_SCHED __builtin_amdgcn_sched_barrier(0)
; template <class Epi, class Sched, bool ALIGN_EPI = false, bool SP2 = false>
; __device__ __forceinline__ void gemm_phase(PG8_LAS unsigned char* lds, const Gemm g, const Sched& S, const Epi& E) {
;     ...
;             PG8_WAIT_V(8); PG8_WAIT_L(0); PG8_BAR; PG8_MMA(1, 0, At, B0); PG8_MMA(1, 1, At, B1); PG8_BAR; PG8_SCHED;
;             PG8_LDB(B0, 1, 0); PG8_LDB(B1, 1, 1); PG8_SCHED; PG8_LDA(At, 1, 0); PG8_STAGE(PG8_SA(0, 1), a2 + hstep, voffA);
;             PG8_WAIT_V(8); PG8_WAIT_L(0); PG8_BAR; PG8_MMA(0, 0, At, B0); PG8_MMA(0, 1, At, B1); PG8_BAR; PG8_SCHED;
	v_mfma_f32_16x16x32_bf16 v[92:95], v[128:131], v[178:181], v[92:95]
	v_mfma_f32_16x16x32_bf16 v[88:91], v[154:157], v[178:181], v[88:91]
	v_mfma_f32_16x16x32_bf16 v[84:87], v[128:131], v[186:189], v[84:87]
	v_mfma_f32_16x16x32_bf16 v[80:83], v[154:157], v[186:189], v[80:83]
	v_mfma_f32_16x16x32_bf16 v[76:79], v[128:131], v[194:197], v[76:79]
	v_mfma_f32_16x16x32_bf16 v[72:75], v[154:157], v[194:197], v[72:75]
	v_mfma_f32_16x16x32_bf16 v[68:71], v[128:131], v[210:213], v[68:71]
	v_mfma_f32_16x16x32_bf16 v[64:67], v[154:157], v[210:213], v[64:67]
	v_mfma_f32_16x16x32_bf16 v[92:95], v[132:135], v[182:185], v[92:95]
	v_mfma_f32_16x16x32_bf16 v[88:91], v[158:161], v[182:185], v[88:91]
	v_mfma_f32_16x16x32_bf16 v[84:87], v[132:135], v[190:193], v[84:87]
	v_mfma_f32_16x16x32_bf16 v[80:83], v[158:161], v[190:193], v[80:83]
	v_mfma_f32_16x16x32_bf16 v[76:79], v[132:135], v[198:201], v[76:79]
	v_mfma_f32_16x16x32_bf16 v[72:75], v[158:161], v[198:201], v[72:75]
	v_mfma_f32_16x16x32_bf16 v[68:71], v[132:135], v[214:217], v[68:71]
	v_mfma_f32_16x16x32_bf16 v[64:67], v[158:161], v[214:217], v[64:67]
	s_setprio 0
	s_setprio 1
	v_mfma_f32_16x16x32_bf16 v[28:31], v[162:165], v[178:181], v[28:31]
	v_mfma_f32_16x16x32_bf16 v[24:27], v[170:173], v[178:181], v[24:27]
	v_mfma_f32_16x16x32_bf16 v[20:23], v[162:165], v[186:189], v[20:23]
	v_mfma_f32_16x16x32_bf16 v[16:19], v[170:173], v[186:189], v[16:19]
	v_mfma_f32_16x16x32_bf16 v[12:15], v[162:165], v[194:197], v[12:15]
	v_mfma_f32_16x16x32_bf16 v[8:11], v[170:173], v[194:197], v[8:11]
	v_mfma_f32_16x16x32_bf16 v[4:7], v[162:165], v[210:213], v[4:7]
	v_mfma_f32_16x16x32_bf16 v[0:3], v[170:173], v[210:213], v[0:3]
	v_mfma_f32_16x16x32_bf16 v[28:31], v[166:169], v[182:185], v[28:31]
	v_mfma_f32_16x16x32_bf16 v[24:27], v[174:177], v[182:185], v[24:27]
	v_mfma_f32_16x16x32_bf16 v[20:23], v[166:169], v[190:193], v[20:23]
	v_mfma_f32_16x16x32_bf16 v[16:19], v[174:177], v[190:193], v[16:19]
	v_mfma_f32_16x16x32_bf16 v[12:15], v[166:169], v[198:201], v[12:15]
	v_mfma_f32_16x16x32_bf16 v[8:11], v[174:177], v[198:201], v[8:11]
	s_setprio 2
	s_barrier
	v_mfma_f32_16x16x32_bf16 v[4:7], v[166:169], v[214:217], v[4:7]
	v_mfma_f32_16x16x32_bf16 v[0:3], v[174:177], v[214:217], v[0:3]
	s_setprio 0
	s_add_i32 s78, 0, 0x18000
	s_add_i32 s79, 0, 0x1c000
	v_add_u32_e32 v158, s78, v203
	v_add_u32_e32 v174, s79, v203
	ds_read_b128 v[128:131], v158
	ds_read_b128 v[132:135], v158 offset:1024
	ds_read_b128 v[154:157], v158 offset:2048
	ds_read_b128 v[158:161], v158 offset:3072
	ds_read_b128 v[162:165], v174
	ds_read_b128 v[166:169], v174 offset:1024
	ds_read_b128 v[170:173], v174 offset:2048
	ds_read_b128 v[174:177], v174 offset:3072
	s_add_u32 s56, s56, 0x80000
	s_addc_u32 s57, s57, 0
	s_mov_b32 m0, s63
	v_lshl_add_u64 v[226:227], s[56:57], 0, v[136:137]
	ds_read_b128 v[178:181], v207 offset:32768
	ds_read_b128 v[182:185], v207 offset:33792
	ds_read_b128 v[186:189], v207 offset:34816
	ds_read_b128 v[190:193], v207 offset:35840
	ds_read_b128 v[194:197], v207 offset:36864
	ds_read_b128 v[198:201], v207 offset:37888
	ds_read_b128 v[210:213], v207 offset:38912
	ds_read_b128 v[214:217], v207 offset:39936
	global_load_lds_dwordx4 v[226:227], off
	s_mov_b32 m0, s64
	v_lshl_add_u64 v[226:227], s[56:57], 0, v[140:141]
	global_load_lds_dwordx4 v[226:227], off
	s_waitcnt vmcnt(8)
	s_waitcnt lgkmcnt(0)
	s_setprio 1
	s_barrier
	v_mfma_f32_16x16x32_bf16 v[124:127], v[128:131], v[178:181], v[124:127]
	v_mfma_f32_16x16x32_bf16 v[120:123], v[154:157], v[178:181], v[120:123]
	v_mfma_f32_16x16x32_bf16 v[116:119], v[128:131], v[186:189], v[116:119]
	v_mfma_f32_16x16x32_bf16 v[112:115], v[154:157], v[186:189], v[112:115]
	v_mfma_f32_16x16x32_bf16 v[108:111], v[128:131], v[194:197], v[108:111]
	v_mfma_f32_16x16x32_bf16 v[104:107], v[154:157], v[194:197], v[104:107]
	v_mfma_f32_16x16x32_bf16 v[100:103], v[128:131], v[210:213], v[100:103]
	v_mfma_f32_16x16x32_bf16 v[96:99], v[154:157], v[210:213], v[96:99]
	v_mfma_f32_16x16x32_bf16 v[124:127], v[132:135], v[182:185], v[124:127]
	v_mfma_f32_16x16x32_bf16 v[120:123], v[158:161], v[182:185], v[120:123]
	v_mfma_f32_16x16x32_bf16 v[116:119], v[132:135], v[190:193], v[116:119]
	v_mfma_f32_16x16x32_bf16 v[112:115], v[158:161], v[190:193], v[112:115]
	v_mfma_f32_16x16x32_bf16 v[108:111], v[132:135], v[198:201], v[108:111]
	v_mfma_f32_16x16x32_bf16 v[104:107], v[158:161], v[198:201], v[104:107]
	v_mfma_f32_16x16x32_bf16 v[100:103], v[132:135], v[214:217], v[100:103]
	v_mfma_f32_16x16x32_bf16 v[96:99], v[158:161], v[214:217], v[96:99]
	s_setprio 0
	s_setprio 1
	v_mfma_f32_16x16x32_bf16 v[60:63], v[162:165], v[178:181], v[60:63]
	v_mfma_f32_16x16x32_bf16 v[56:59], v[170:173], v[178:181], v[56:59]
	v_mfma_f32_16x16x32_bf16 v[52:55], v[162:165], v[186:189], v[52:55]
	v_mfma_f32_16x16x32_bf16 v[48:51], v[170:173], v[186:189], v[48:51]
	v_mfma_f32_16x16x32_bf16 v[44:47], v[162:165], v[194:197], v[44:47]
	v_mfma_f32_16x16x32_bf16 v[40:43], v[170:173], v[194:197], v[40:43]
	v_mfma_f32_16x16x32_bf16 v[36:39], v[162:165], v[210:213], v[36:39]
	v_mfma_f32_16x16x32_bf16 v[32:35], v[170:173], v[210:213], v[32:35]
	v_mfma_f32_16x16x32_bf16 v[60:63], v[166:169], v[182:185], v[60:63]
	v_mfma_f32_16x16x32_bf16 v[56:59], v[174:177], v[182:185], v[56:59]
	v_mfma_f32_16x16x32_bf16 v[52:55], v[166:169], v[190:193], v[52:55]
	v_mfma_f32_16x16x32_bf16 v[48:51], v[174:177], v[190:193], v[48:51]
	v_mfma_f32_16x16x32_bf16 v[44:47], v[166:169], v[198:201], v[44:47]
	v_mfma_f32_16x16x32_bf16 v[40:43], v[174:177], v[198:201], v[40:43]
	s_setprio 2
	s_barrier
; #define PG8_STAGE(bufoff, gbase, voff) do { _Pragma("unroll") for (int _i = 0; _i < 2; ++_i) \
;         __builtin_amdgcn_global_load_lds((const unsigned*)((const char*)(gbase) + (voff)[_i]), (PG8_LAS unsigned*)(lds + (bufoff) + ldsw + _i * 8192), 16, 0, 0); } while (0)
; #define PG8_LDA(dst, b, h) do { _Pragma("unroll") for (int m = 0; m < 4; ++m) _Pragma("unroll") for (int k = 0; k < 2; ++k) dst[m][k] = *(const PG8_LAS bf16x8*)(lds + PG8_SA(b, h) + aoff + m * 2048 + k * 1024); } while (0)
; #define PG8_MMA(ai, bj, At, Bt) do { __builtin_amdgcn_s_setprio(1); _Pragma("unroll") for (int m = 0; m < 4; ++m) _Pragma("unroll") for (int n = 0; n < 2; ++n) _Pragma("unroll") for (int k = 0; k < 2; ++k) \
;         acc[ai][bj][m][n] = __builtin_amdgcn_mfma_f32_16x16x32_bf16(Bt[n][k], At[m][k], acc[ai][bj][m][n], 0, 0, 0); __builtin_amdgcn_s_setprio(0); } while (0)
; #define PG8_WAIT_V(n) asm volatile("s_waitcnt vmcnt(" #n ")" ::: "memory")
; #define PG8_WAIT_L(n) asm volatile("s_waitcnt lgkmcnt(" #n ")" ::: "memory")
; #define PG8_BAR __builtin_amdgcn_s_barrier()
; #define PG8_SCHED __builtin_amdgcn_sched_barrier(0)
; template <class Epi, class Sched, bool ALIGN_EPI = false, bool SP2 = false>
; __device__ __forceinline__ void gemm_phase(PG8_LAS unsigned char* lds, const Gemm g, const Sched& S, const Epi& E) {
;     ...
;             PG8_WAIT_V(8); PG8_WAIT_L(0); PG8_BAR; PG8_MMA(0, 0, At, B0); PG8_MMA(0, 1, At, B1); PG8_BAR; PG8_SCHED;
;             PG8_LDA(At, 1, 1); PG8_STAGE(PG8_SB(1, 0), b3, voffB); PG8_STAGE(PG8_SB(1, 1), b3 + hstep, voffB); PG8_STAGE(PG8_SA(1, 0), a3, voffA);
;             PG8_WAIT_V(8); PG8_WAIT_L(0); PG8_BAR; PG8_MMA(1, 0, At, B0); PG8_MMA(1, 1, At, B1); PG8_BAR; PG8_SCHED;
;     ...
;         if constexpr (ALIGN_EPI) { if (wr == 0) PG8_BAR; }
	v_mfma_f32_16x16x32_bf16 v[36:39], v[166:169], v[214:217], v[36:39]
	v_mfma_f32_16x16x32_bf16 v[32:35], v[174:177], v[214:217], v[32:35]
	s_setprio 0
	s_add_i32 s56, s78, s60
	v_lshl_add_u64 v[218:219], v[218:219], 0, s[12:13]
	s_mov_b32 m0, s56
	ds_read_b128 v[178:181], v207 offset:49152
	ds_read_b128 v[182:185], v207 offset:50176
	ds_read_b128 v[186:189], v207 offset:51200
	ds_read_b128 v[190:193], v207 offset:52224
	ds_read_b128 v[194:197], v207 offset:53248
	ds_read_b128 v[198:201], v207 offset:54272
	ds_read_b128 v[210:213], v207 offset:55296
	ds_read_b128 v[214:217], v207 offset:56320
	global_load_lds_dwordx4 v[218:219], off
	s_add_i32 m0, s56, 0x2000
	s_add_u32 s54, s54, 0x80080
	v_lshl_add_u64 v[218:219], v[220:221], 0, s[12:13]
	s_addc_u32 s55, s55, 0
	s_add_i32 s56, s79, s60
	global_load_lds_dwordx4 v[218:219], off
	s_mov_b32 m0, s56
	v_lshl_add_u64 v[218:219], s[54:55], 0, v[138:139]
	global_load_lds_dwordx4 v[218:219], off
	s_add_i32 m0, s56, 0x2000
	v_lshl_add_u64 v[218:219], s[54:55], 0, v[142:143]
	global_load_lds_dwordx4 v[218:219], off
	s_mov_b32 m0, s70
	v_lshl_add_u64 v[218:219], v[222:223], 0, s[12:13]
	global_load_lds_dwordx4 v[218:219], off
	s_mov_b32 m0, s71
	v_lshl_add_u64 v[218:219], v[224:225], 0, s[12:13]
	global_load_lds_dwordx4 v[218:219], off
	s_waitcnt vmcnt(8)
	s_waitcnt lgkmcnt(0)
	s_setprio 1
	s_barrier
	v_mfma_f32_16x16x32_bf16 v[92:95], v[128:131], v[178:181], v[92:95]
	v_mfma_f32_16x16x32_bf16 v[88:91], v[154:157], v[178:181], v[88:91]
	v_mfma_f32_16x16x32_bf16 v[84:87], v[128:131], v[186:189], v[84:87]
	v_mfma_f32_16x16x32_bf16 v[80:83], v[154:157], v[186:189], v[80:83]
	v_mfma_f32_16x16x32_bf16 v[76:79], v[128:131], v[194:197], v[76:79]
	v_mfma_f32_16x16x32_bf16 v[72:75], v[154:157], v[194:197], v[72:75]
	v_mfma_f32_16x16x32_bf16 v[68:71], v[128:131], v[210:213], v[68:71]
	v_mfma_f32_16x16x32_bf16 v[64:67], v[154:157], v[210:213], v[64:67]
	v_mfma_f32_16x16x32_bf16 v[92:95], v[132:135], v[182:185], v[92:95]
	v_mfma_f32_16x16x32_bf16 v[88:91], v[158:161], v[182:185], v[88:91]
	v_mfma_f32_16x16x32_bf16 v[84:87], v[132:135], v[190:193], v[84:87]
	v_mfma_f32_16x16x32_bf16 v[80:83], v[158:161], v[190:193], v[80:83]
	v_mfma_f32_16x16x32_bf16 v[76:79], v[132:135], v[198:201], v[76:79]
	v_mfma_f32_16x16x32_bf16 v[72:75], v[158:161], v[198:201], v[72:75]
	v_mfma_f32_16x16x32_bf16 v[68:71], v[132:135], v[214:217], v[68:71]
	v_mfma_f32_16x16x32_bf16 v[64:67], v[158:161], v[214:217], v[64:67]
	s_setprio 0
	s_setprio 1
	v_mfma_f32_16x16x32_bf16 v[28:31], v[162:165], v[178:181], v[28:31]
	v_mfma_f32_16x16x32_bf16 v[24:27], v[170:173], v[178:181], v[24:27]
	v_mfma_f32_16x16x32_bf16 v[20:23], v[162:165], v[186:189], v[20:23]
	v_mfma_f32_16x16x32_bf16 v[16:19], v[170:173], v[186:189], v[16:19]
	v_mfma_f32_16x16x32_bf16 v[12:15], v[162:165], v[194:197], v[12:15]
	v_mfma_f32_16x16x32_bf16 v[8:11], v[170:173], v[194:197], v[8:11]
	v_mfma_f32_16x16x32_bf16 v[4:7], v[162:165], v[210:213], v[4:7]
	v_mfma_f32_16x16x32_bf16 v[0:3], v[170:173], v[210:213], v[0:3]
	v_mfma_f32_16x16x32_bf16 v[28:31], v[166:169], v[182:185], v[28:31]
	v_mfma_f32_16x16x32_bf16 v[24:27], v[174:177], v[182:185], v[24:27]
	v_mfma_f32_16x16x32_bf16 v[20:23], v[166:169], v[190:193], v[20:23]
	v_mfma_f32_16x16x32_bf16 v[16:19], v[174:177], v[190:193], v[16:19]
	v_mfma_f32_16x16x32_bf16 v[12:15], v[166:169], v[198:201], v[12:15]
	v_mfma_f32_16x16x32_bf16 v[8:11], v[174:177], v[198:201], v[8:11]
	s_setprio 2
	s_barrier
	v_mfma_f32_16x16x32_bf16 v[4:7], v[166:169], v[214:217], v[4:7]
	v_mfma_f32_16x16x32_bf16 v[0:3], v[174:177], v[214:217], v[0:3]
	s_setprio 0
	s_add_i32 s77, s77, 2
	s_add_u32 s52, s52, 0x100
	s_addc_u32 s53, s53, 0
	s_add_u32 s75, s75, 0x100
	s_addc_u32 s76, s76, 0
	s_cmp_gt_u32 s77, 29
	s_cbranch_scc0 .LBB0_1051
	s_and_b64 vcc, exec, s[14:15]
	s_cbranch_vccz .LBB0_1054
	s_barrier

; #define PG8_STAGE(bufoff, gbase, voff) do { _Pragma("unroll") for (int _i = 0; _i < 2; ++_i) \
;         __builtin_amdgcn_global_load_lds((const unsigned*)((const char*)(gbase) + (voff)[_i]), (PG8_LAS unsigned*)(lds + (bufoff) + ldsw + _i * 8192), 16, 0, 0); } while (0)
; #define PG8_LDA(dst, b, h) do { _Pragma("unroll") for (int m = 0; m < 4; ++m) _Pragma("unroll") for (int k = 0; k < 2; ++k) dst[m][k] = *(const PG8_LAS bf16x8*)(lds + PG8_SA(b, h) + aoff + m * 2048 + k * 1024); } while (0)
; #define PG8_LDB(dst, b, h) do { _Pragma("unroll") for (int n = 0; n < 2; ++n) _Pragma("unroll") for (int k = 0; k < 2; ++k) dst[n][k] = *(const PG8_LAS bf16x8*)(lds + PG8_SB(b, h) + boff + n * 2048 + k * 1024); } while (0)
; #define PG8_MMA(ai, bj, At, Bt) do { __builtin_amdgcn_s_setprio(1); _Pragma("unroll") for (int m = 0; m < 4; ++m) _Pragma("unroll") for (int n = 0; n < 2; ++n) _Pragma("unroll") for (int k = 0; k < 2; ++k) \
;         acc[ai][bj][m][n] = __builtin_amdgcn_mfma_f32_16x16x32_bf16(Bt[n][k], At[m][k], acc[ai][bj][m][n], 0, 0, 0); __builtin_amdgcn_s_setprio(0); } while (0)
; #define PG8_WAIT_V(n) asm volatile("s_waitcnt vmcnt(" #n ")" ::: "memory")
; #define PG8_WAIT_L(n) asm volatile("s_waitcnt lgkmcnt(" #n ")" ::: "memory")
; #define PG8_BAR __builtin_amdgcn_s_barrier()
; template <class Epi, class Sched, bool ALIGN_EPI = false, bool SP2 = false>
; __device__ __forceinline__ void gemm_phase(PG8_LAS unsigned char* lds, const Gemm g, const Sched& S, const Epi& E) {
;     ...
;             const bool last = (t == nt - 2);
;             const char* a1 = cA + (size_t)(t + 1) * kstep;
;             const char* a2 = last ? nA : cA + (size_t)(t + 2) * kstep; const char* b2 = last ? nB : cB + (size_t)(t + 2) * kstep;
;             const char* a3 = a2 + kstep; const char* b3 = b2 + kstep;
;             if constexpr (SP2) {
;             PG8_LDB(B0, 0, 0); PG8_LDB(B1, 0, 1); PG8_SCHED; PG8_LDA(At, 0, 0); PG8_STAGE(PG8_SA(1, 1), a1 + hstep, voffA);
;             PG8_WAIT_V(8); PG8_WAIT_L(0); PG8_BAR; PG8_MMA(0, 0, At, B0); PG8_MMA(0, 1, At, B1); PG8_BAR; PG8_SCHED;
;             PG8_LDA(At, 0, 1); PG8_STAGE(PG8_SB(0, 0), b2, voffB); PG8_STAGE(PG8_SB(0, 1), b2 + hstep, voffB); PG8_STAGE(PG8_SA(0, 0), a2, voffA);
;             PG8_WAIT_V(8); PG8_WAIT_L(0); PG8_BAR; PG8_MMA(1, 0, At, B0); PG8_MMA(1, 1, At, B1); PG8_BAR; PG8_SCHED;
.LBB0_1142:
	ds_read_b128 v[80:83], v171
	ds_read_b128 v[84:87], v171 offset:1024
	ds_read_b128 v[88:91], v171 offset:2048
	ds_read_b128 v[92:95], v171 offset:3072
	ds_read_b128 v[164:167], v172
	ds_read_b128 v[176:179], v172 offset:1024
	ds_read_b128 v[180:183], v172 offset:2048
	ds_read_b128 v[184:187], v172 offset:3072
	s_add_u32 s44, s42, 0xfff80080
	s_addc_u32 s45, s43, -1
	s_cmp_eq_u32 s64, 28
	s_cselect_b32 s47, s15, s45
	s_cselect_b32 s46, s60, s44
	s_cselect_b32 s45, s13, s63
	s_cselect_b32 s44, s61, s62
	v_lshl_add_u64 v[220:221], s[42:43], 0, v[156:157]
	s_add_i32 m0, s41, 0xc000
	ds_read_b128 v[188:191], v173
	ds_read_b128 v[192:195], v173 offset:1024
	ds_read_b128 v[196:199], v173 offset:2048
	ds_read_b128 v[200:203], v173 offset:3072
	ds_read_b128 v[204:207], v173 offset:4096
	ds_read_b128 v[208:211], v173 offset:5120
	ds_read_b128 v[212:215], v173 offset:6144
	ds_read_b128 v[216:219], v173 offset:7168
	global_load_lds_dwordx4 v[220:221], off
	s_add_i32 m0, s41, 0xe000
	v_lshl_add_u64 v[220:221], s[42:43], 0, v[158:159]
	global_load_lds_dwordx4 v[220:221], off
	s_waitcnt vmcnt(8)
	s_waitcnt lgkmcnt(0)
	s_setprio 1
	s_barrier
	v_mfma_f32_16x16x32_bf16 v[140:143], v[80:83], v[188:191], v[140:143]
	v_mfma_f32_16x16x32_bf16 v[136:139], v[88:91], v[188:191], v[136:139]
	v_mfma_f32_16x16x32_bf16 v[124:127], v[80:83], v[196:199], v[124:127]
	v_mfma_f32_16x16x32_bf16 v[120:123], v[88:91], v[196:199], v[120:123]
	v_mfma_f32_16x16x32_bf16 v[108:111], v[80:83], v[204:207], v[108:111]
	v_mfma_f32_16x16x32_bf16 v[104:107], v[88:91], v[204:207], v[104:107]
	v_mfma_f32_16x16x32_bf16 v[76:79], v[80:83], v[212:215], v[76:79]
	v_mfma_f32_16x16x32_bf16 v[72:75], v[88:91], v[212:215], v[72:75]
	v_mfma_f32_16x16x32_bf16 v[140:143], v[84:87], v[192:195], v[140:143]
	v_mfma_f32_16x16x32_bf16 v[136:139], v[92:95], v[192:195], v[136:139]
	v_mfma_f32_16x16x32_bf16 v[124:127], v[84:87], v[200:203], v[124:127]
	v_mfma_f32_16x16x32_bf16 v[120:123], v[92:95], v[200:203], v[120:123]
	v_mfma_f32_16x16x32_bf16 v[108:111], v[84:87], v[208:211], v[108:111]
	v_mfma_f32_16x16x32_bf16 v[104:107], v[92:95], v[208:211], v[104:107]
	v_mfma_f32_16x16x32_bf16 v[76:79], v[84:87], v[216:219], v[76:79]
	v_mfma_f32_16x16x32_bf16 v[72:75], v[92:95], v[216:219], v[72:75]
	s_setprio 0
	s_setprio 1
	v_mfma_f32_16x16x32_bf16 v[132:135], v[164:167], v[188:191], v[132:135]
	v_mfma_f32_16x16x32_bf16 v[128:131], v[180:183], v[188:191], v[128:131]
	v_mfma_f32_16x16x32_bf16 v[116:119], v[164:167], v[196:199], v[116:119]
	v_mfma_f32_16x16x32_bf16 v[112:115], v[180:183], v[196:199], v[112:115]
	v_mfma_f32_16x16x32_bf16 v[100:103], v[164:167], v[204:207], v[100:103]
	v_mfma_f32_16x16x32_bf16 v[96:99], v[180:183], v[204:207], v[96:99]
	v_mfma_f32_16x16x32_bf16 v[68:71], v[164:167], v[212:215], v[68:71]
	v_mfma_f32_16x16x32_bf16 v[64:67], v[180:183], v[212:215], v[64:67]
	v_mfma_f32_16x16x32_bf16 v[132:135], v[176:179], v[192:195], v[132:135]
	v_mfma_f32_16x16x32_bf16 v[128:131], v[184:187], v[192:195], v[128:131]
	v_mfma_f32_16x16x32_bf16 v[116:119], v[176:179], v[200:203], v[116:119]
	v_mfma_f32_16x16x32_bf16 v[112:115], v[184:187], v[200:203], v[112:115]
	v_mfma_f32_16x16x32_bf16 v[100:103], v[176:179], v[208:211], v[100:103]
	v_mfma_f32_16x16x32_bf16 v[96:99], v[184:187], v[208:211], v[96:99]
	s_setprio 2
	s_barrier
	v_mfma_f32_16x16x32_bf16 v[68:71], v[176:179], v[216:219], v[68:71]
	v_mfma_f32_16x16x32_bf16 v[64:67], v[184:187], v[216:219], v[64:67]
	s_setprio 0
	s_add_i32 s65, s56, s33
	v_lshl_add_u64 v[220:221], s[44:45], 0, v[148:149]
	s_mov_b32 m0, s65
	ds_read_b128 v[188:191], v173 offset:16384
	ds_read_b128 v[192:195], v173 offset:17408
	ds_read_b128 v[196:199], v173 offset:18432
	ds_read_b128 v[200:203], v173 offset:19456
	ds_read_b128 v[204:207], v173 offset:20480
	ds_read_b128 v[208:211], v173 offset:21504
	ds_read_b128 v[212:215], v173 offset:22528
	ds_read_b128 v[216:219], v173 offset:23552
	global_load_lds_dwordx4 v[220:221], off
	s_add_i32 m0, s65, 0x2000
	s_add_u32 s66, s44, 0x80000
	v_lshl_add_u64 v[222:223], s[44:45], 0, v[152:153]
	s_addc_u32 s67, s45, 0
	s_add_i32 s65, s57, s33
	global_load_lds_dwordx4 v[222:223], off
	v_lshl_add_u64 v[224:225], s[66:67], 0, v[148:149]
	s_mov_b32 m0, s65
	v_lshl_add_u64 v[226:227], s[46:47], 0, v[150:151]
	global_load_lds_dwordx4 v[224:225], off
	s_add_i32 m0, s65, 0x2000
	v_lshl_add_u64 v[224:225], s[66:67], 0, v[152:153]
	global_load_lds_dwordx4 v[224:225], off
	s_mov_b32 m0, s41
	v_lshl_add_u64 v[224:225], s[46:47], 0, v[144:145]
	global_load_lds_dwordx4 v[224:225], off
	s_mov_b32 m0, s48
	s_nop 0
	global_load_lds_dwordx4 v[226:227], off
	s_waitcnt vmcnt(8)
	s_waitcnt lgkmcnt(0)
	s_setprio 1
	s_barrier
; #define PG8_STAGE(bufoff, gbase, voff) do { _Pragma("unroll") for (int _i = 0; _i < 2; ++_i) \
;         __builtin_amdgcn_global_load_lds((const unsigned*)((const char*)(gbase) + (voff)[_i]), (PG8_LAS unsigned*)(lds + (bufoff) + ldsw + _i * 8192), 16, 0, 0); } while (0)
; #define PG8_LDA(dst, b, h) do { _Pragma("unroll") for (int m = 0; m < 4; ++m) _Pragma("unroll") for (int k = 0; k < 2; ++k) dst[m][k] = *(const PG8_LAS bf16x8*)(lds + PG8_SA(b, h) + aoff + m * 2048 + k * 1024); } while (0)
; #define PG8_LDB(dst, b, h) do { _Pragma("unroll") for (int n = 0; n < 2; ++n) _Pragma("unroll") for (int k = 0; k < 2; ++k) dst[n][k] = *(const PG8_LAS bf16x8*)(lds + PG8_SB(b, h) + boff + n * 2048 + k * 1024); } while (0)
; #define PG8_MMA(ai, bj, At, Bt) do { __builtin_amdgcn_s_setprio(1); _Pragma("unroll") for (int m = 0; m < 4; ++m) _Pragma("unroll") for (int n = 0; n < 2; ++n) _Pragma("unroll") for (int k = 0; k < 2; ++k) \
;         acc[ai][bj][m][n] = __builtin_amdgcn_mfma_f32_16x16x32_bf16(Bt[n][k], At[m][k], acc[ai][bj][m][n], 0, 0, 0); __builtin_amdgcn_s_setprio(0); } while (0)
; #define PG8_WAIT_V(n) asm volatile("s_waitcnt vmcnt(" #n ")" ::: "memory")
; #define PG8_WAIT_L(n) asm volatile("s_waitcnt lgkmcnt(" #n ")" ::: "memory")
; #define PG8_BAR __builtin_amdgcn_s_barrier()
; #define PG8_SCHED __builtin_amdgcn_sched_barrier(0)
; template <class Epi, class Sched, bool ALIGN_EPI = false, bool SP2 = false>
; __device__ __forceinline__ void gemm_phase(PG8_LAS unsigned char* lds, const Gemm g, const Sched& S, const Epi& E) {
;     ...
;             PG8_WAIT_V(8); PG8_WAIT_L(0); PG8_BAR; PG8_MMA(1, 0, At, B0); PG8_MMA(1, 1, At, B1); PG8_BAR; PG8_SCHED;
;             PG8_LDB(B0, 1, 0); PG8_LDB(B1, 1, 1); PG8_SCHED; PG8_LDA(At, 1, 0); PG8_STAGE(PG8_SA(0, 1), a2 + hstep, voffA);
;             PG8_WAIT_V(8); PG8_WAIT_L(0); PG8_BAR; PG8_MMA(0, 0, At, B0); PG8_MMA(0, 1, At, B1); PG8_BAR; PG8_SCHED;
	v_mfma_f32_16x16x32_bf16 v[60:63], v[80:83], v[188:191], v[60:63]
	v_mfma_f32_16x16x32_bf16 v[56:59], v[88:91], v[188:191], v[56:59]
	v_mfma_f32_16x16x32_bf16 v[44:47], v[80:83], v[196:199], v[44:47]
	v_mfma_f32_16x16x32_bf16 v[40:43], v[88:91], v[196:199], v[40:43]
	v_mfma_f32_16x16x32_bf16 v[28:31], v[80:83], v[204:207], v[28:31]
	v_mfma_f32_16x16x32_bf16 v[24:27], v[88:91], v[204:207], v[24:27]
	v_mfma_f32_16x16x32_bf16 v[12:15], v[80:83], v[212:215], v[12:15]
	v_mfma_f32_16x16x32_bf16 v[8:11], v[88:91], v[212:215], v[8:11]
	v_mfma_f32_16x16x32_bf16 v[60:63], v[84:87], v[192:195], v[60:63]
	v_mfma_f32_16x16x32_bf16 v[56:59], v[92:95], v[192:195], v[56:59]
	v_mfma_f32_16x16x32_bf16 v[44:47], v[84:87], v[200:203], v[44:47]
	v_mfma_f32_16x16x32_bf16 v[40:43], v[92:95], v[200:203], v[40:43]
	v_mfma_f32_16x16x32_bf16 v[28:31], v[84:87], v[208:211], v[28:31]
	v_mfma_f32_16x16x32_bf16 v[24:27], v[92:95], v[208:211], v[24:27]
	v_mfma_f32_16x16x32_bf16 v[12:15], v[84:87], v[216:219], v[12:15]
	v_mfma_f32_16x16x32_bf16 v[8:11], v[92:95], v[216:219], v[8:11]
	s_setprio 0
	s_setprio 1
	v_mfma_f32_16x16x32_bf16 v[52:55], v[164:167], v[188:191], v[52:55]
	v_mfma_f32_16x16x32_bf16 v[48:51], v[180:183], v[188:191], v[48:51]
	v_mfma_f32_16x16x32_bf16 v[36:39], v[164:167], v[196:199], v[36:39]
	v_mfma_f32_16x16x32_bf16 v[32:35], v[180:183], v[196:199], v[32:35]
	v_mfma_f32_16x16x32_bf16 v[20:23], v[164:167], v[204:207], v[20:23]
	v_mfma_f32_16x16x32_bf16 v[16:19], v[180:183], v[204:207], v[16:19]
	v_mfma_f32_16x16x32_bf16 v[4:7], v[164:167], v[212:215], v[4:7]
	v_mfma_f32_16x16x32_bf16 v[0:3], v[180:183], v[212:215], v[0:3]
	v_mfma_f32_16x16x32_bf16 v[52:55], v[176:179], v[192:195], v[52:55]
	v_mfma_f32_16x16x32_bf16 v[48:51], v[184:187], v[192:195], v[48:51]
	v_mfma_f32_16x16x32_bf16 v[36:39], v[176:179], v[200:203], v[36:39]
	v_mfma_f32_16x16x32_bf16 v[32:35], v[184:187], v[200:203], v[32:35]
	v_mfma_f32_16x16x32_bf16 v[20:23], v[176:179], v[208:211], v[20:23]
	v_mfma_f32_16x16x32_bf16 v[16:19], v[184:187], v[208:211], v[16:19]
	s_setprio 2
	s_barrier
	v_mfma_f32_16x16x32_bf16 v[4:7], v[176:179], v[216:219], v[4:7]
	v_mfma_f32_16x16x32_bf16 v[0:3], v[184:187], v[216:219], v[0:3]
	s_setprio 0
	s_add_i32 s65, 0, 0x18000
	s_add_i32 s66, 0, 0x1c000
	v_add_u32_e32 v92, s65, v169
	v_add_u32_e32 v184, s66, v169
	ds_read_b128 v[80:83], v92
	ds_read_b128 v[84:87], v92 offset:1024
	ds_read_b128 v[88:91], v92 offset:2048
	ds_read_b128 v[92:95], v92 offset:3072
	ds_read_b128 v[164:167], v184
	ds_read_b128 v[176:179], v184 offset:1024
	ds_read_b128 v[180:183], v184 offset:2048
	ds_read_b128 v[184:187], v184 offset:3072
	s_add_u32 s46, s46, 0x80000
	s_addc_u32 s47, s47, 0
	s_mov_b32 m0, s49
	v_lshl_add_u64 v[228:229], s[46:47], 0, v[144:145]
	ds_read_b128 v[188:191], v173 offset:32768
	ds_read_b128 v[192:195], v173 offset:33792
	ds_read_b128 v[196:199], v173 offset:34816
	ds_read_b128 v[200:203], v173 offset:35840
	ds_read_b128 v[204:207], v173 offset:36864
	ds_read_b128 v[208:211], v173 offset:37888
	ds_read_b128 v[212:215], v173 offset:38912
	ds_read_b128 v[216:219], v173 offset:39936
	global_load_lds_dwordx4 v[228:229], off
	s_mov_b32 m0, s50
	v_lshl_add_u64 v[228:229], s[46:47], 0, v[150:151]
	global_load_lds_dwordx4 v[228:229], off
	s_waitcnt vmcnt(8)
	s_waitcnt lgkmcnt(0)
	s_setprio 1
	s_barrier
	v_mfma_f32_16x16x32_bf16 v[140:143], v[80:83], v[188:191], v[140:143]
	v_mfma_f32_16x16x32_bf16 v[136:139], v[88:91], v[188:191], v[136:139]
	v_mfma_f32_16x16x32_bf16 v[124:127], v[80:83], v[196:199], v[124:127]
	v_mfma_f32_16x16x32_bf16 v[120:123], v[88:91], v[196:199], v[120:123]
	v_mfma_f32_16x16x32_bf16 v[108:111], v[80:83], v[204:207], v[108:111]
	v_mfma_f32_16x16x32_bf16 v[104:107], v[88:91], v[204:207], v[104:107]
	v_mfma_f32_16x16x32_bf16 v[76:79], v[80:83], v[212:215], v[76:79]
	v_mfma_f32_16x16x32_bf16 v[72:75], v[88:91], v[212:215], v[72:75]
	v_mfma_f32_16x16x32_bf16 v[140:143], v[84:87], v[192:195], v[140:143]
	v_mfma_f32_16x16x32_bf16 v[136:139], v[92:95], v[192:195], v[136:139]
	v_mfma_f32_16x16x32_bf16 v[124:127], v[84:87], v[200:203], v[124:127]
	v_mfma_f32_16x16x32_bf16 v[120:123], v[92:95], v[200:203], v[120:123]
	v_mfma_f32_16x16x32_bf16 v[108:111], v[84:87], v[208:211], v[108:111]
	v_mfma_f32_16x16x32_bf16 v[104:107], v[92:95], v[208:211], v[104:107]
	v_mfma_f32_16x16x32_bf16 v[76:79], v[84:87], v[216:219], v[76:79]
	v_mfma_f32_16x16x32_bf16 v[72:75], v[92:95], v[216:219], v[72:75]
	s_setprio 0
	s_setprio 1
	v_mfma_f32_16x16x32_bf16 v[132:135], v[164:167], v[188:191], v[132:135]
	v_mfma_f32_16x16x32_bf16 v[128:131], v[180:183], v[188:191], v[128:131]
	v_mfma_f32_16x16x32_bf16 v[116:119], v[164:167], v[196:199], v[116:119]
	v_mfma_f32_16x16x32_bf16 v[112:115], v[180:183], v[196:199], v[112:115]
	v_mfma_f32_16x16x32_bf16 v[100:103], v[164:167], v[204:207], v[100:103]
	v_mfma_f32_16x16x32_bf16 v[96:99], v[180:183], v[204:207], v[96:99]
	v_mfma_f32_16x16x32_bf16 v[68:71], v[164:167], v[212:215], v[68:71]
	v_mfma_f32_16x16x32_bf16 v[64:67], v[180:183], v[212:215], v[64:67]
	v_mfma_f32_16x16x32_bf16 v[132:135], v[176:179], v[192:195], v[132:135]
	v_mfma_f32_16x16x32_bf16 v[128:131], v[184:187], v[192:195], v[128:131]
	v_mfma_f32_16x16x32_bf16 v[116:119], v[176:179], v[200:203], v[116:119]
	v_mfma_f32_16x16x32_bf16 v[112:115], v[184:187], v[200:203], v[112:115]
	v_mfma_f32_16x16x32_bf16 v[100:103], v[176:179], v[208:211], v[100:103]
	v_mfma_f32_16x16x32_bf16 v[96:99], v[184:187], v[208:211], v[96:99]
	s_setprio 2
	s_barrier
; #define PG8_STAGE(bufoff, gbase, voff) do { _Pragma("unroll") for (int _i = 0; _i < 2; ++_i) \
;         __builtin_amdgcn_global_load_lds((const unsigned*)((const char*)(gbase) + (voff)[_i]), (PG8_LAS unsigned*)(lds + (bufoff) + ldsw + _i * 8192), 16, 0, 0); } while (0)
; #define PG8_LDA(dst, b, h) do { _Pragma("unroll") for (int m = 0; m < 4; ++m) _Pragma("unroll") for (int k = 0; k < 2; ++k) dst[m][k] = *(const PG8_LAS bf16x8*)(lds + PG8_SA(b, h) + aoff + m * 2048 + k * 1024); } while (0)
; #define PG8_MMA(ai, bj, At, Bt) do { __builtin_amdgcn_s_setprio(1); _Pragma("unroll") for (int m = 0; m < 4; ++m) _Pragma("unroll") for (int n = 0; n < 2; ++n) _Pragma("unroll") for (int k = 0; k < 2; ++k) \
;         acc[ai][bj][m][n] = __builtin_amdgcn_mfma_f32_16x16x32_bf16(Bt[n][k], At[m][k], acc[ai][bj][m][n], 0, 0, 0); __builtin_amdgcn_s_setprio(0); } while (0)
; #define PG8_WAIT_V(n) asm volatile("s_waitcnt vmcnt(" #n ")" ::: "memory")
; #define PG8_WAIT_L(n) asm volatile("s_waitcnt lgkmcnt(" #n ")" ::: "memory")
; #define PG8_BAR __builtin_amdgcn_s_barrier()
; #define PG8_SCHED __builtin_amdgcn_sched_barrier(0)
; template <class Epi, class Sched, bool ALIGN_EPI = false, bool SP2 = false>
; __device__ __forceinline__ void gemm_phase(PG8_LAS unsigned char* lds, const Gemm g, const Sched& S, const Epi& E) {
;     ...
;             PG8_WAIT_V(8); PG8_WAIT_L(0); PG8_BAR; PG8_MMA(0, 0, At, B0); PG8_MMA(0, 1, At, B1); PG8_BAR; PG8_SCHED;
;             PG8_LDA(At, 1, 1); PG8_STAGE(PG8_SB(1, 0), b3, voffB); PG8_STAGE(PG8_SB(1, 1), b3 + hstep, voffB); PG8_STAGE(PG8_SA(1, 0), a3, voffA);
;             PG8_WAIT_V(8); PG8_WAIT_L(0); PG8_BAR; PG8_MMA(1, 0, At, B0); PG8_MMA(1, 1, At, B1); PG8_BAR; PG8_SCHED;
;     ...
;         if constexpr (ALIGN_EPI) { if (wr == 0) PG8_BAR; }
	v_mfma_f32_16x16x32_bf16 v[68:71], v[176:179], v[216:219], v[68:71]
	v_mfma_f32_16x16x32_bf16 v[64:67], v[184:187], v[216:219], v[64:67]
	s_setprio 0
	s_add_i32 s46, s65, s33
	v_lshl_add_u64 v[220:221], v[220:221], 0, s[8:9]
	s_mov_b32 m0, s46
	ds_read_b128 v[188:191], v173 offset:49152
	ds_read_b128 v[192:195], v173 offset:50176
	ds_read_b128 v[196:199], v173 offset:51200
	ds_read_b128 v[200:203], v173 offset:52224
	ds_read_b128 v[204:207], v173 offset:53248
	ds_read_b128 v[208:211], v173 offset:54272
	ds_read_b128 v[212:215], v173 offset:55296
	ds_read_b128 v[216:219], v173 offset:56320
	global_load_lds_dwordx4 v[220:221], off
	s_add_i32 m0, s46, 0x2000
	s_add_u32 s44, s44, 0x80080
	v_lshl_add_u64 v[220:221], v[222:223], 0, s[8:9]
	s_addc_u32 s45, s45, 0
	s_add_i32 s46, s66, s33
	global_load_lds_dwordx4 v[220:221], off
	s_mov_b32 m0, s46
	v_lshl_add_u64 v[220:221], s[44:45], 0, v[148:149]
	global_load_lds_dwordx4 v[220:221], off
	s_add_i32 m0, s46, 0x2000
	v_lshl_add_u64 v[220:221], s[44:45], 0, v[152:153]
	global_load_lds_dwordx4 v[220:221], off
	s_mov_b32 m0, s52
	v_lshl_add_u64 v[220:221], v[224:225], 0, s[8:9]
	global_load_lds_dwordx4 v[220:221], off
	s_mov_b32 m0, s53
	v_lshl_add_u64 v[220:221], v[226:227], 0, s[8:9]
	global_load_lds_dwordx4 v[220:221], off
	s_waitcnt vmcnt(8)
	s_waitcnt lgkmcnt(0)
	s_setprio 1
	s_barrier
	v_mfma_f32_16x16x32_bf16 v[60:63], v[80:83], v[188:191], v[60:63]
	v_mfma_f32_16x16x32_bf16 v[56:59], v[88:91], v[188:191], v[56:59]
	v_mfma_f32_16x16x32_bf16 v[44:47], v[80:83], v[196:199], v[44:47]
	v_mfma_f32_16x16x32_bf16 v[40:43], v[88:91], v[196:199], v[40:43]
	v_mfma_f32_16x16x32_bf16 v[28:31], v[80:83], v[204:207], v[28:31]
	v_mfma_f32_16x16x32_bf16 v[24:27], v[88:91], v[204:207], v[24:27]
	v_mfma_f32_16x16x32_bf16 v[12:15], v[80:83], v[212:215], v[12:15]
	v_mfma_f32_16x16x32_bf16 v[8:11], v[88:91], v[212:215], v[8:11]
	v_mfma_f32_16x16x32_bf16 v[60:63], v[84:87], v[192:195], v[60:63]
	v_mfma_f32_16x16x32_bf16 v[56:59], v[92:95], v[192:195], v[56:59]
	v_mfma_f32_16x16x32_bf16 v[44:47], v[84:87], v[200:203], v[44:47]
	v_mfma_f32_16x16x32_bf16 v[40:43], v[92:95], v[200:203], v[40:43]
	v_mfma_f32_16x16x32_bf16 v[28:31], v[84:87], v[208:211], v[28:31]
	v_mfma_f32_16x16x32_bf16 v[24:27], v[92:95], v[208:211], v[24:27]
	v_mfma_f32_16x16x32_bf16 v[12:15], v[84:87], v[216:219], v[12:15]
	v_mfma_f32_16x16x32_bf16 v[8:11], v[92:95], v[216:219], v[8:11]
	s_setprio 0
	s_setprio 1
	v_mfma_f32_16x16x32_bf16 v[52:55], v[164:167], v[188:191], v[52:55]
	v_mfma_f32_16x16x32_bf16 v[48:51], v[180:183], v[188:191], v[48:51]
	v_mfma_f32_16x16x32_bf16 v[36:39], v[164:167], v[196:199], v[36:39]
	v_mfma_f32_16x16x32_bf16 v[32:35], v[180:183], v[196:199], v[32:35]
	v_mfma_f32_16x16x32_bf16 v[20:23], v[164:167], v[204:207], v[20:23]
	v_mfma_f32_16x16x32_bf16 v[16:19], v[180:183], v[204:207], v[16:19]
	v_mfma_f32_16x16x32_bf16 v[4:7], v[164:167], v[212:215], v[4:7]
	v_mfma_f32_16x16x32_bf16 v[0:3], v[180:183], v[212:215], v[0:3]
	v_mfma_f32_16x16x32_bf16 v[52:55], v[176:179], v[192:195], v[52:55]
	v_mfma_f32_16x16x32_bf16 v[48:51], v[184:187], v[192:195], v[48:51]
	v_mfma_f32_16x16x32_bf16 v[36:39], v[176:179], v[200:203], v[36:39]
	v_mfma_f32_16x16x32_bf16 v[32:35], v[184:187], v[200:203], v[32:35]
	v_mfma_f32_16x16x32_bf16 v[20:23], v[176:179], v[208:211], v[20:23]
	v_mfma_f32_16x16x32_bf16 v[16:19], v[184:187], v[208:211], v[16:19]
	s_setprio 2
	s_barrier
	v_mfma_f32_16x16x32_bf16 v[4:7], v[176:179], v[216:219], v[4:7]
	v_mfma_f32_16x16x32_bf16 v[0:3], v[184:187], v[216:219], v[0:3]
	s_setprio 0
	s_add_i32 s64, s64, 2
	s_add_u32 s42, s42, 0x100
	s_addc_u32 s43, s43, 0
	s_add_u32 s62, s62, 0x100
	s_addc_u32 s63, s63, 0
	s_cmp_gt_u32 s64, 29
	s_cbranch_scc0 .LBB0_1142
	s_and_b64 vcc, exec, s[10:11]
	s_cbranch_vccz .LBB0_1145
	s_barrier

; #define PG8_STAGE(bufoff, gbase, voff) do { _Pragma("unroll") for (int _i = 0; _i < 2; ++_i) \
;         __builtin_amdgcn_global_load_lds((const unsigned*)((const char*)(gbase) + (voff)[_i]), (PG8_LAS unsigned*)(lds + (bufoff) + ldsw + _i * 8192), 16, 0, 0); } while (0)
; #define PG8_LDA(dst, b, h) do { _Pragma("unroll") for (int m = 0; m < 4; ++m) _Pragma("unroll") for (int k = 0; k < 2; ++k) dst[m][k] = *(const PG8_LAS bf16x8*)(lds + PG8_SA(b, h) + aoff + m * 2048 + k * 1024); } while (0)
; #define PG8_LDB(dst, b, h) do { _Pragma("unroll") for (int n = 0; n < 2; ++n) _Pragma("unroll") for (int k = 0; k < 2; ++k) dst[n][k] = *(const PG8_LAS bf16x8*)(lds + PG8_SB(b, h) + boff + n * 2048 + k * 1024); } while (0)
; #define PG8_MMA(ai, bj, At, Bt) do { __builtin_amdgcn_s_setprio(1); _Pragma("unroll") for (int m = 0; m < 4; ++m) _Pragma("unroll") for (int n = 0; n < 2; ++n) _Pragma("unroll") for (int k = 0; k < 2; ++k) \
;         acc[ai][bj][m][n] = __builtin_amdgcn_mfma_f32_16x16x32_bf16(Bt[n][k], At[m][k], acc[ai][bj][m][n], 0, 0, 0); __builtin_amdgcn_s_setprio(0); } while (0)
; #define PG8_WAIT_V(n) asm volatile("s_waitcnt vmcnt(" #n ")" ::: "memory")
; #define PG8_WAIT_L(n) asm volatile("s_waitcnt lgkmcnt(" #n ")" ::: "memory")
; #define PG8_BAR __builtin_amdgcn_s_barrier()
; template <class Epi, class Sched, bool ALIGN_EPI = false, bool SP2 = false>
; __device__ __forceinline__ void gemm_phase(PG8_LAS unsigned char* lds, const Gemm g, const Sched& S, const Epi& E) {
;     ...
;             const bool last = (t == nt - 2);
;             const char* a1 = cA + (size_t)(t + 1) * kstep;
;             const char* a2 = last ? nA : cA + (size_t)(t + 2) * kstep; const char* b2 = last ? nB : cB + (size_t)(t + 2) * kstep;
;             const char* a3 = a2 + kstep; const char* b3 = b2 + kstep;
;             if constexpr (SP2) {
;             PG8_LDB(B0, 0, 0); PG8_LDB(B1, 0, 1); PG8_SCHED; PG8_LDA(At, 0, 0); PG8_STAGE(PG8_SA(1, 1), a1 + hstep, voffA);
;             PG8_WAIT_V(8); PG8_WAIT_L(0); PG8_BAR; PG8_MMA(0, 0, At, B0); PG8_MMA(0, 1, At, B1); PG8_BAR; PG8_SCHED;
;             PG8_LDA(At, 0, 1); PG8_STAGE(PG8_SB(0, 0), b2, voffB); PG8_STAGE(PG8_SB(0, 1), b2 + hstep, voffB); PG8_STAGE(PG8_SA(0, 0), a2, voffA);
;             PG8_WAIT_V(8); PG8_WAIT_L(0); PG8_BAR; PG8_MMA(1, 0, At, B0); PG8_MMA(1, 1, At, B1); PG8_BAR; PG8_SCHED;
.LBB0_1219:
	ds_read_b128 v[128:131], v167
	ds_read_b128 v[132:135], v167 offset:1024
	ds_read_b128 v[154:157], v167 offset:2048
	ds_read_b128 v[158:161], v167 offset:3072
	ds_read_b128 v[170:173], v168
	ds_read_b128 v[174:177], v168 offset:1024
	ds_read_b128 v[178:181], v168 offset:2048
	ds_read_b128 v[182:185], v168 offset:3072
	s_add_u32 s42, s40, 0xffe00080
	s_addc_u32 s43, s41, -1
	s_cmpk_eq_i32 s63, 0x7c
	s_cselect_b32 s45, s15, s43
	s_cselect_b32 s44, s59, s42
	s_cselect_b32 s43, s13, s62
	s_cselect_b32 s42, s60, s61
	v_lshl_add_u64 v[162:163], s[40:41], 0, v[144:145]
	s_add_i32 m0, s39, 0xc000
	ds_read_b128 v[186:189], v169
	ds_read_b128 v[190:193], v169 offset:1024
	ds_read_b128 v[194:197], v169 offset:2048
	ds_read_b128 v[198:201], v169 offset:3072
	ds_read_b128 v[202:205], v169 offset:4096
	ds_read_b128 v[206:209], v169 offset:5120
	ds_read_b128 v[210:213], v169 offset:6144
	ds_read_b128 v[214:217], v169 offset:7168
	global_load_lds_dwordx4 v[162:163], off
	s_add_i32 m0, s39, 0xe000
	v_lshl_add_u64 v[162:163], s[40:41], 0, v[148:149]
	global_load_lds_dwordx4 v[162:163], off
	s_waitcnt vmcnt(8)
	s_waitcnt lgkmcnt(0)
	s_setprio 1
	s_barrier
	v_mfma_f32_16x16x32_bf16 v[124:127], v[128:131], v[186:189], v[124:127]
	v_mfma_f32_16x16x32_bf16 v[120:123], v[154:157], v[186:189], v[120:123]
	v_mfma_f32_16x16x32_bf16 v[116:119], v[128:131], v[194:197], v[116:119]
	v_mfma_f32_16x16x32_bf16 v[112:115], v[154:157], v[194:197], v[112:115]
	v_mfma_f32_16x16x32_bf16 v[108:111], v[128:131], v[202:205], v[108:111]
	v_mfma_f32_16x16x32_bf16 v[104:107], v[154:157], v[202:205], v[104:107]
	v_mfma_f32_16x16x32_bf16 v[100:103], v[128:131], v[210:213], v[100:103]
	v_mfma_f32_16x16x32_bf16 v[96:99], v[154:157], v[210:213], v[96:99]
	v_mfma_f32_16x16x32_bf16 v[124:127], v[132:135], v[190:193], v[124:127]
	v_mfma_f32_16x16x32_bf16 v[120:123], v[158:161], v[190:193], v[120:123]
	v_mfma_f32_16x16x32_bf16 v[116:119], v[132:135], v[198:201], v[116:119]
	v_mfma_f32_16x16x32_bf16 v[112:115], v[158:161], v[198:201], v[112:115]
	v_mfma_f32_16x16x32_bf16 v[108:111], v[132:135], v[206:209], v[108:111]
	v_mfma_f32_16x16x32_bf16 v[104:107], v[158:161], v[206:209], v[104:107]
	v_mfma_f32_16x16x32_bf16 v[100:103], v[132:135], v[214:217], v[100:103]
	v_mfma_f32_16x16x32_bf16 v[96:99], v[158:161], v[214:217], v[96:99]
	s_setprio 0
	s_setprio 1
	v_mfma_f32_16x16x32_bf16 v[68:71], v[170:173], v[186:189], v[68:71]
	v_mfma_f32_16x16x32_bf16 v[60:63], v[178:181], v[186:189], v[60:63]
	v_mfma_f32_16x16x32_bf16 v[52:55], v[170:173], v[194:197], v[52:55]
	v_mfma_f32_16x16x32_bf16 v[48:51], v[178:181], v[194:197], v[48:51]
	v_mfma_f32_16x16x32_bf16 v[44:47], v[170:173], v[202:205], v[44:47]
	v_mfma_f32_16x16x32_bf16 v[40:43], v[178:181], v[202:205], v[40:43]
	v_mfma_f32_16x16x32_bf16 v[36:39], v[170:173], v[210:213], v[36:39]
	v_mfma_f32_16x16x32_bf16 v[32:35], v[178:181], v[210:213], v[32:35]
	v_mfma_f32_16x16x32_bf16 v[68:71], v[174:177], v[190:193], v[68:71]
	v_mfma_f32_16x16x32_bf16 v[60:63], v[182:185], v[190:193], v[60:63]
	v_mfma_f32_16x16x32_bf16 v[52:55], v[174:177], v[198:201], v[52:55]
	v_mfma_f32_16x16x32_bf16 v[48:51], v[182:185], v[198:201], v[48:51]
	v_mfma_f32_16x16x32_bf16 v[44:47], v[174:177], v[206:209], v[44:47]
	v_mfma_f32_16x16x32_bf16 v[40:43], v[182:185], v[206:209], v[40:43]
	s_setprio 2
	s_barrier
	v_mfma_f32_16x16x32_bf16 v[36:39], v[174:177], v[214:217], v[36:39]
	v_mfma_f32_16x16x32_bf16 v[32:35], v[182:185], v[214:217], v[32:35]
	s_setprio 0
	s_add_i32 s64, s56, s33
	v_lshl_add_u64 v[162:163], s[42:43], 0, v[138:139]
	s_mov_b32 m0, s64
	ds_read_b128 v[186:189], v169 offset:16384
	ds_read_b128 v[190:193], v169 offset:17408
	ds_read_b128 v[194:197], v169 offset:18432
	ds_read_b128 v[198:201], v169 offset:19456
	ds_read_b128 v[202:205], v169 offset:20480
	ds_read_b128 v[206:209], v169 offset:21504
	ds_read_b128 v[210:213], v169 offset:22528
	ds_read_b128 v[214:217], v169 offset:23552
	global_load_lds_dwordx4 v[162:163], off
	s_add_i32 m0, s64, 0x2000
	s_add_u32 s64, s42, 0x200000
	v_lshl_add_u64 v[218:219], s[42:43], 0, v[142:143]
	s_addc_u32 s65, s43, 0
	s_add_i32 s66, s57, s33
	global_load_lds_dwordx4 v[218:219], off
	v_lshl_add_u64 v[220:221], s[64:65], 0, v[138:139]
	s_mov_b32 m0, s66
	v_lshl_add_u64 v[222:223], s[44:45], 0, v[140:141]
	global_load_lds_dwordx4 v[220:221], off
	s_add_i32 m0, s66, 0x2000
	v_lshl_add_u64 v[220:221], s[64:65], 0, v[142:143]
	global_load_lds_dwordx4 v[220:221], off
	s_mov_b32 m0, s39
	v_lshl_add_u64 v[220:221], s[44:45], 0, v[136:137]
	global_load_lds_dwordx4 v[220:221], off
	s_mov_b32 m0, s46
	s_nop 0
	global_load_lds_dwordx4 v[222:223], off
	s_waitcnt vmcnt(8)
	s_waitcnt lgkmcnt(0)
	s_setprio 1
	s_barrier
; #define PG8_STAGE(bufoff, gbase, voff) do { _Pragma("unroll") for (int _i = 0; _i < 2; ++_i) \
;         __builtin_amdgcn_global_load_lds((const unsigned*)((const char*)(gbase) + (voff)[_i]), (PG8_LAS unsigned*)(lds + (bufoff) + ldsw + _i * 8192), 16, 0, 0); } while (0)
; #define PG8_LDA(dst, b, h) do { _Pragma("unroll") for (int m = 0; m < 4; ++m) _Pragma("unroll") for (int k = 0; k < 2; ++k) dst[m][k] = *(const PG8_LAS bf16x8*)(lds + PG8_SA(b, h) + aoff + m * 2048 + k * 1024); } while (0)
; #define PG8_LDB(dst, b, h) do { _Pragma("unroll") for (int n = 0; n < 2; ++n) _Pragma("unroll") for (int k = 0; k < 2; ++k) dst[n][k] = *(const PG8_LAS bf16x8*)(lds + PG8_SB(b, h) + boff + n * 2048 + k * 1024); } while (0)
; #define PG8_MMA(ai, bj, At, Bt) do { __builtin_amdgcn_s_setprio(1); _Pragma("unroll") for (int m = 0; m < 4; ++m) _Pragma("unroll") for (int n = 0; n < 2; ++n) _Pragma("unroll") for (int k = 0; k < 2; ++k) \
;         acc[ai][bj][m][n] = __builtin_amdgcn_mfma_f32_16x16x32_bf16(Bt[n][k], At[m][k], acc[ai][bj][m][n], 0, 0, 0); __builtin_amdgcn_s_setprio(0); } while (0)
; #define PG8_WAIT_V(n) asm volatile("s_waitcnt vmcnt(" #n ")" ::: "memory")
; #define PG8_WAIT_L(n) asm volatile("s_waitcnt lgkmcnt(" #n ")" ::: "memory")
; #define PG8_BAR __builtin_amdgcn_s_barrier()
; #define PG8_SCHED __builtin_amdgcn_sched_barrier(0)
; template <class Epi, class Sched, bool ALIGN_EPI = false, bool SP2 = false>
; __device__ __forceinline__ void gemm_phase(PG8_LAS unsigned char* lds, const Gemm g, const Sched& S, const Epi& E) {
;     ...
;             PG8_WAIT_V(8); PG8_WAIT_L(0); PG8_BAR; PG8_MMA(1, 0, At, B0); PG8_MMA(1, 1, At, B1); PG8_BAR; PG8_SCHED;
;             PG8_LDB(B0, 1, 0); PG8_LDB(B1, 1, 1); PG8_SCHED; PG8_LDA(At, 1, 0); PG8_STAGE(PG8_SA(0, 1), a2 + hstep, voffA);
;             PG8_WAIT_V(8); PG8_WAIT_L(0); PG8_BAR; PG8_MMA(0, 0, At, B0); PG8_MMA(0, 1, At, B1); PG8_BAR; PG8_SCHED;
	v_mfma_f32_16x16x32_bf16 v[92:95], v[128:131], v[186:189], v[92:95]
	v_mfma_f32_16x16x32_bf16 v[88:91], v[154:157], v[186:189], v[88:91]
	v_mfma_f32_16x16x32_bf16 v[84:87], v[128:131], v[194:197], v[84:87]
	v_mfma_f32_16x16x32_bf16 v[80:83], v[154:157], v[194:197], v[80:83]
	v_mfma_f32_16x16x32_bf16 v[76:79], v[128:131], v[202:205], v[76:79]
	v_mfma_f32_16x16x32_bf16 v[72:75], v[154:157], v[202:205], v[72:75]
	v_mfma_f32_16x16x32_bf16 v[64:67], v[128:131], v[210:213], v[64:67]
	v_mfma_f32_16x16x32_bf16 v[56:59], v[154:157], v[210:213], v[56:59]
	v_mfma_f32_16x16x32_bf16 v[92:95], v[132:135], v[190:193], v[92:95]
	v_mfma_f32_16x16x32_bf16 v[88:91], v[158:161], v[190:193], v[88:91]
	v_mfma_f32_16x16x32_bf16 v[84:87], v[132:135], v[198:201], v[84:87]
	v_mfma_f32_16x16x32_bf16 v[80:83], v[158:161], v[198:201], v[80:83]
	v_mfma_f32_16x16x32_bf16 v[76:79], v[132:135], v[206:209], v[76:79]
	v_mfma_f32_16x16x32_bf16 v[72:75], v[158:161], v[206:209], v[72:75]
	v_mfma_f32_16x16x32_bf16 v[64:67], v[132:135], v[214:217], v[64:67]
	v_mfma_f32_16x16x32_bf16 v[56:59], v[158:161], v[214:217], v[56:59]
	s_setprio 0
	s_setprio 1
	v_mfma_f32_16x16x32_bf16 v[28:31], v[170:173], v[186:189], v[28:31]
	v_mfma_f32_16x16x32_bf16 v[24:27], v[178:181], v[186:189], v[24:27]
	v_mfma_f32_16x16x32_bf16 v[20:23], v[170:173], v[194:197], v[20:23]
	v_mfma_f32_16x16x32_bf16 v[16:19], v[178:181], v[194:197], v[16:19]
	v_mfma_f32_16x16x32_bf16 v[12:15], v[170:173], v[202:205], v[12:15]
	v_mfma_f32_16x16x32_bf16 v[8:11], v[178:181], v[202:205], v[8:11]
	v_mfma_f32_16x16x32_bf16 v[4:7], v[170:173], v[210:213], v[4:7]
	v_mfma_f32_16x16x32_bf16 v[0:3], v[178:181], v[210:213], v[0:3]
	v_mfma_f32_16x16x32_bf16 v[28:31], v[174:177], v[190:193], v[28:31]
	v_mfma_f32_16x16x32_bf16 v[24:27], v[182:185], v[190:193], v[24:27]
	v_mfma_f32_16x16x32_bf16 v[20:23], v[174:177], v[198:201], v[20:23]
	v_mfma_f32_16x16x32_bf16 v[16:19], v[182:185], v[198:201], v[16:19]
	v_mfma_f32_16x16x32_bf16 v[12:15], v[174:177], v[206:209], v[12:15]
	v_mfma_f32_16x16x32_bf16 v[8:11], v[182:185], v[206:209], v[8:11]
	s_setprio 2
	s_barrier
	v_mfma_f32_16x16x32_bf16 v[4:7], v[174:177], v[214:217], v[4:7]
	v_mfma_f32_16x16x32_bf16 v[0:3], v[182:185], v[214:217], v[0:3]
	s_setprio 0
	s_add_i32 s64, 0, 0x18000
	s_add_i32 s65, 0, 0x1c000
	v_add_u32_e32 v158, s64, v165
	v_add_u32_e32 v182, s65, v165
	ds_read_b128 v[128:131], v158
	ds_read_b128 v[132:135], v158 offset:1024
	ds_read_b128 v[154:157], v158 offset:2048
	ds_read_b128 v[158:161], v158 offset:3072
	ds_read_b128 v[170:173], v182
	ds_read_b128 v[174:177], v182 offset:1024
	ds_read_b128 v[178:181], v182 offset:2048
	ds_read_b128 v[182:185], v182 offset:3072
	s_add_u32 s44, s44, 0x200000
	s_addc_u32 s45, s45, 0
	s_mov_b32 m0, s47
	v_lshl_add_u64 v[224:225], s[44:45], 0, v[136:137]
	ds_read_b128 v[186:189], v169 offset:32768
	ds_read_b128 v[190:193], v169 offset:33792
	ds_read_b128 v[194:197], v169 offset:34816
	ds_read_b128 v[198:201], v169 offset:35840
	ds_read_b128 v[202:205], v169 offset:36864
	ds_read_b128 v[206:209], v169 offset:37888
	ds_read_b128 v[210:213], v169 offset:38912
	ds_read_b128 v[214:217], v169 offset:39936
	global_load_lds_dwordx4 v[224:225], off
	s_mov_b32 m0, s48
	v_lshl_add_u64 v[224:225], s[44:45], 0, v[140:141]
	global_load_lds_dwordx4 v[224:225], off
	s_waitcnt vmcnt(8)
	s_waitcnt lgkmcnt(0)
	s_setprio 1
	s_barrier
	v_mfma_f32_16x16x32_bf16 v[124:127], v[128:131], v[186:189], v[124:127]
	v_mfma_f32_16x16x32_bf16 v[120:123], v[154:157], v[186:189], v[120:123]
	v_mfma_f32_16x16x32_bf16 v[116:119], v[128:131], v[194:197], v[116:119]
	v_mfma_f32_16x16x32_bf16 v[112:115], v[154:157], v[194:197], v[112:115]
	v_mfma_f32_16x16x32_bf16 v[108:111], v[128:131], v[202:205], v[108:111]
	v_mfma_f32_16x16x32_bf16 v[104:107], v[154:157], v[202:205], v[104:107]
	v_mfma_f32_16x16x32_bf16 v[100:103], v[128:131], v[210:213], v[100:103]
	v_mfma_f32_16x16x32_bf16 v[96:99], v[154:157], v[210:213], v[96:99]
	v_mfma_f32_16x16x32_bf16 v[124:127], v[132:135], v[190:193], v[124:127]
	v_mfma_f32_16x16x32_bf16 v[120:123], v[158:161], v[190:193], v[120:123]
	v_mfma_f32_16x16x32_bf16 v[116:119], v[132:135], v[198:201], v[116:119]
	v_mfma_f32_16x16x32_bf16 v[112:115], v[158:161], v[198:201], v[112:115]
	v_mfma_f32_16x16x32_bf16 v[108:111], v[132:135], v[206:209], v[108:111]
	v_mfma_f32_16x16x32_bf16 v[104:107], v[158:161], v[206:209], v[104:107]
	v_mfma_f32_16x16x32_bf16 v[100:103], v[132:135], v[214:217], v[100:103]
	v_mfma_f32_16x16x32_bf16 v[96:99], v[158:161], v[214:217], v[96:99]
	s_setprio 0
	s_setprio 1
	v_mfma_f32_16x16x32_bf16 v[68:71], v[170:173], v[186:189], v[68:71]
	v_mfma_f32_16x16x32_bf16 v[60:63], v[178:181], v[186:189], v[60:63]
	v_mfma_f32_16x16x32_bf16 v[52:55], v[170:173], v[194:197], v[52:55]
	v_mfma_f32_16x16x32_bf16 v[48:51], v[178:181], v[194:197], v[48:51]
	v_mfma_f32_16x16x32_bf16 v[44:47], v[170:173], v[202:205], v[44:47]
	v_mfma_f32_16x16x32_bf16 v[40:43], v[178:181], v[202:205], v[40:43]
	v_mfma_f32_16x16x32_bf16 v[36:39], v[170:173], v[210:213], v[36:39]
	v_mfma_f32_16x16x32_bf16 v[32:35], v[178:181], v[210:213], v[32:35]
	v_mfma_f32_16x16x32_bf16 v[68:71], v[174:177], v[190:193], v[68:71]
	v_mfma_f32_16x16x32_bf16 v[60:63], v[182:185], v[190:193], v[60:63]
	v_mfma_f32_16x16x32_bf16 v[52:55], v[174:177], v[198:201], v[52:55]
	v_mfma_f32_16x16x32_bf16 v[48:51], v[182:185], v[198:201], v[48:51]
	v_mfma_f32_16x16x32_bf16 v[44:47], v[174:177], v[206:209], v[44:47]
	v_mfma_f32_16x16x32_bf16 v[40:43], v[182:185], v[206:209], v[40:43]
	s_setprio 2
	s_barrier
; #define PG8_STAGE(bufoff, gbase, voff) do { _Pragma("unroll") for (int _i = 0; _i < 2; ++_i) \
;         __builtin_amdgcn_global_load_lds((const unsigned*)((const char*)(gbase) + (voff)[_i]), (PG8_LAS unsigned*)(lds + (bufoff) + ldsw + _i * 8192), 16, 0, 0); } while (0)
; #define PG8_LDA(dst, b, h) do { _Pragma("unroll") for (int m = 0; m < 4; ++m) _Pragma("unroll") for (int k = 0; k < 2; ++k) dst[m][k] = *(const PG8_LAS bf16x8*)(lds + PG8_SA(b, h) + aoff + m * 2048 + k * 1024); } while (0)
; #define PG8_MMA(ai, bj, At, Bt) do { __builtin_amdgcn_s_setprio(1); _Pragma("unroll") for (int m = 0; m < 4; ++m) _Pragma("unroll") for (int n = 0; n < 2; ++n) _Pragma("unroll") for (int k = 0; k < 2; ++k) \
;         acc[ai][bj][m][n] = __builtin_amdgcn_mfma_f32_16x16x32_bf16(Bt[n][k], At[m][k], acc[ai][bj][m][n], 0, 0, 0); __builtin_amdgcn_s_setprio(0); } while (0)
; #define PG8_WAIT_V(n) asm volatile("s_waitcnt vmcnt(" #n ")" ::: "memory")
; #define PG8_WAIT_L(n) asm volatile("s_waitcnt lgkmcnt(" #n ")" ::: "memory")
; #define PG8_BAR __builtin_amdgcn_s_barrier()
; #define PG8_SCHED __builtin_amdgcn_sched_barrier(0)
; template <class Epi, class Sched, bool ALIGN_EPI = false, bool SP2 = false>
; __device__ __forceinline__ void gemm_phase(PG8_LAS unsigned char* lds, const Gemm g, const Sched& S, const Epi& E) {
;     ...
;             PG8_WAIT_V(8); PG8_WAIT_L(0); PG8_BAR; PG8_MMA(0, 0, At, B0); PG8_MMA(0, 1, At, B1); PG8_BAR; PG8_SCHED;
;             PG8_LDA(At, 1, 1); PG8_STAGE(PG8_SB(1, 0), b3, voffB); PG8_STAGE(PG8_SB(1, 1), b3 + hstep, voffB); PG8_STAGE(PG8_SA(1, 0), a3, voffA);
;             PG8_WAIT_V(8); PG8_WAIT_L(0); PG8_BAR; PG8_MMA(1, 0, At, B0); PG8_MMA(1, 1, At, B1); PG8_BAR; PG8_SCHED;
;     ...
;         if constexpr (ALIGN_EPI) { if (wr == 0) PG8_BAR; }
	v_mfma_f32_16x16x32_bf16 v[36:39], v[174:177], v[214:217], v[36:39]
	v_mfma_f32_16x16x32_bf16 v[32:35], v[182:185], v[214:217], v[32:35]
	s_setprio 0
	s_add_i32 s44, s64, s33
	v_lshl_add_u64 v[162:163], v[162:163], 0, s[8:9]
	s_mov_b32 m0, s44
	ds_read_b128 v[186:189], v169 offset:49152
	ds_read_b128 v[190:193], v169 offset:50176
	ds_read_b128 v[194:197], v169 offset:51200
	ds_read_b128 v[198:201], v169 offset:52224
	ds_read_b128 v[202:205], v169 offset:53248
	ds_read_b128 v[206:209], v169 offset:54272
	ds_read_b128 v[210:213], v169 offset:55296
	ds_read_b128 v[214:217], v169 offset:56320
	global_load_lds_dwordx4 v[162:163], off
	s_add_i32 m0, s44, 0x2000
	s_add_u32 s42, s42, 0x200080
	v_lshl_add_u64 v[162:163], v[218:219], 0, s[8:9]
	s_addc_u32 s43, s43, 0
	s_add_i32 s44, s65, s33
	global_load_lds_dwordx4 v[162:163], off
	s_mov_b32 m0, s44
	v_lshl_add_u64 v[162:163], s[42:43], 0, v[138:139]
	global_load_lds_dwordx4 v[162:163], off
	s_add_i32 m0, s44, 0x2000
	v_lshl_add_u64 v[162:163], s[42:43], 0, v[142:143]
	global_load_lds_dwordx4 v[162:163], off
	s_mov_b32 m0, s52
	v_lshl_add_u64 v[162:163], v[220:221], 0, s[8:9]
	global_load_lds_dwordx4 v[162:163], off
	s_mov_b32 m0, s53
	v_lshl_add_u64 v[162:163], v[222:223], 0, s[8:9]
	global_load_lds_dwordx4 v[162:163], off
	s_waitcnt vmcnt(8)
	s_waitcnt lgkmcnt(0)
	s_setprio 1
	s_barrier
	v_mfma_f32_16x16x32_bf16 v[92:95], v[128:131], v[186:189], v[92:95]
	v_mfma_f32_16x16x32_bf16 v[88:91], v[154:157], v[186:189], v[88:91]
	v_mfma_f32_16x16x32_bf16 v[84:87], v[128:131], v[194:197], v[84:87]
	v_mfma_f32_16x16x32_bf16 v[80:83], v[154:157], v[194:197], v[80:83]
	v_mfma_f32_16x16x32_bf16 v[76:79], v[128:131], v[202:205], v[76:79]
	v_mfma_f32_16x16x32_bf16 v[72:75], v[154:157], v[202:205], v[72:75]
	v_mfma_f32_16x16x32_bf16 v[64:67], v[128:131], v[210:213], v[64:67]
	v_mfma_f32_16x16x32_bf16 v[56:59], v[154:157], v[210:213], v[56:59]
	v_mfma_f32_16x16x32_bf16 v[92:95], v[132:135], v[190:193], v[92:95]
	v_mfma_f32_16x16x32_bf16 v[88:91], v[158:161], v[190:193], v[88:91]
	v_mfma_f32_16x16x32_bf16 v[84:87], v[132:135], v[198:201], v[84:87]
	v_mfma_f32_16x16x32_bf16 v[80:83], v[158:161], v[198:201], v[80:83]
	v_mfma_f32_16x16x32_bf16 v[76:79], v[132:135], v[206:209], v[76:79]
	v_mfma_f32_16x16x32_bf16 v[72:75], v[158:161], v[206:209], v[72:75]
	v_mfma_f32_16x16x32_bf16 v[64:67], v[132:135], v[214:217], v[64:67]
	v_mfma_f32_16x16x32_bf16 v[56:59], v[158:161], v[214:217], v[56:59]
	s_setprio 0
	s_setprio 1
	v_mfma_f32_16x16x32_bf16 v[28:31], v[170:173], v[186:189], v[28:31]
	v_mfma_f32_16x16x32_bf16 v[24:27], v[178:181], v[186:189], v[24:27]
	v_mfma_f32_16x16x32_bf16 v[20:23], v[170:173], v[194:197], v[20:23]
	v_mfma_f32_16x16x32_bf16 v[16:19], v[178:181], v[194:197], v[16:19]
	v_mfma_f32_16x16x32_bf16 v[12:15], v[170:173], v[202:205], v[12:15]
	v_mfma_f32_16x16x32_bf16 v[8:11], v[178:181], v[202:205], v[8:11]
	v_mfma_f32_16x16x32_bf16 v[4:7], v[170:173], v[210:213], v[4:7]
	v_mfma_f32_16x16x32_bf16 v[0:3], v[178:181], v[210:213], v[0:3]
	v_mfma_f32_16x16x32_bf16 v[28:31], v[174:177], v[190:193], v[28:31]
	v_mfma_f32_16x16x32_bf16 v[24:27], v[182:185], v[190:193], v[24:27]
	v_mfma_f32_16x16x32_bf16 v[20:23], v[174:177], v[198:201], v[20:23]
	v_mfma_f32_16x16x32_bf16 v[16:19], v[182:185], v[198:201], v[16:19]
	v_mfma_f32_16x16x32_bf16 v[12:15], v[174:177], v[206:209], v[12:15]
	v_mfma_f32_16x16x32_bf16 v[8:11], v[182:185], v[206:209], v[8:11]
	s_setprio 2
	s_barrier
	v_mfma_f32_16x16x32_bf16 v[4:7], v[174:177], v[214:217], v[4:7]
	v_mfma_f32_16x16x32_bf16 v[0:3], v[182:185], v[214:217], v[0:3]
	s_setprio 0
	s_add_i32 s63, s63, 2
	s_add_u32 s40, s40, 0x100
	s_addc_u32 s41, s41, 0
	s_add_u32 s61, s61, 0x100
	s_addc_u32 s62, s62, 0
	s_cmpk_gt_u32 s63, 0x7d
	s_cbranch_scc0 .LBB0_1219
	s_and_b64 vcc, exec, s[10:11]
	s_cbranch_vccz .LBB0_1222
	s_barrier
